# pass-major 64-deep macro-steps (all operand rows requested as whole 128-byte lines) also in the FFN-down and out-proj loops
# speedup vs baseline: 1.0550x; 1.0150x over previous
.LBB0_259:
	s_andn2_b64 vcc, exec, s[10:11]
	s_cbranch_vccnz .LBB0_418
	v_readlane_b32 s8, v247, 19
	v_readlane_b32 s9, v247, 20
	s_mov_b64 s[56:57], s[84:85]
	s_andn2_b64 vcc, exec, s[8:9]
	s_cbranch_vccnz .LBB0_327
	s_load_dwordx2 s[40:41], s[56:57], 0x108
	v_readlane_b32 s2, v246, 27
	v_readlane_b32 s8, v246, 21
	s_add_i32 s2, s2, 2
	v_readlane_b32 s9, v246, 22
	s_and_b64 s[8:9], s[8:9], exec
	s_mov_b32 s6, 0x10b98100
	s_cselect_b32 s6, s6, 0x11c18100
	s_lshl_b64 s[8:9], s[0:1], 21
	s_waitcnt lgkmcnt(0)
	s_add_u32 s42, s40, 0x14958100
	s_mul_hi_i32 s10, s2, 0xc0000
	s_mul_i32 s2, s2, 0xc0000
	s_addc_u32 s43, s41, 0
	s_add_u32 s2, s40, s2
	s_addc_u32 s10, s41, s10
	s_add_u32 s44, s2, 0x7200000
	s_addc_u32 s45, s10, 0
	s_add_u32 s2, s40, s6
	s_addc_u32 s6, s41, 0
	s_add_u32 s46, s2, s8
	s_addc_u32 s47, s6, s9
	s_add_u32 s8, s40, 0x7bc5000
	s_addc_u32 s9, s41, 0
	v_readlane_b32 s12, v247, 44
	s_mov_b32 s13, s83
	v_and_b32_e32 v177, 63, v194
	v_lshrrev_b32_e32 v178, 6, v194
	v_lshrrev_b32_e32 v160, 2, v194
	v_lshlrev_b32_e32 v160, 11, v160
	v_and_b32_e32 v179, 3, v177
	v_bfe_u32 v180, v177, 4, 2
	v_xor_b32_e32 v179, v179, v180
	v_lshl_add_u32 v160, v179, 4, v160
	v_add_u32_e32 v161, 0x20000, v160
	v_and_b32_e32 v174, 31, v177
	v_lshrrev_b32_e32 v182, 5, v177
	v_bfe_u32 v183, v174, 2, 2
	v_xor_b32_e32 v184, v182, v183
	v_xor_b32_e32 v185, 2, v184
	v_lshrrev_b32_e32 v186, 1, v178
	v_and_b32_e32 v187, 1, v178
	v_lshl_add_u32 v188, v186, 6, v174
	v_lshl_add_u32 v189, v187, 6, v174
	v_lshlrev_b32_e32 v188, 6, v188
	v_lshlrev_b32_e32 v189, 6, v189
	v_lshl_add_u32 v154, v184, 4, v188
	v_lshl_add_u32 v155, v185, 4, v188
	v_lshl_add_u32 v156, v184, 4, v189
	v_lshl_add_u32 v157, v185, 4, v189
	v_add_u32_e32 v158, 0x2000, v156
	v_add_u32_e32 v159, 0x2000, v157
	v_lshrrev_b32_e32 v179, 3, v177
	v_lshl_add_u32 v179, v178, 3, v179
	v_lshlrev_b32_e32 v179, 11, v179
	v_and_b32_e32 v180, 1, v178
	v_lshrrev_b32_e32 v183, 4, v177
	v_lshl_add_u32 v180, v180, 2, v183
	v_and_b32_e32 v183, 7, v177
	v_xor_b32_e32 v180, v180, v183
	v_lshl_add_u32 v160, v180, 4, v179
	v_add_u32_e32 v161, 0x20000, v160
	v_add_u32_e32 v242, 0x10000, v160
	v_add_u32_e32 v243, 0x30000, v160
	v_bfe_u32 v183, v174, 1, 3
	v_or_b32_e32 v180, 0, v182
	v_xor_b32_e32 v180, v180, v183
	v_lshlrev_b32_e32 v180, 4, v180
	v_lshl_add_u32 v179, v186, 5, v174
	v_lshl_add_u32 v154, v179, 7, v180
	v_lshl_add_u32 v179, v187, 5, v174
	v_lshl_add_u32 v158, v179, 7, v180
	v_or_b32_e32 v180, 2, v182
	v_xor_b32_e32 v180, v180, v183
	v_lshlrev_b32_e32 v180, 4, v180
	v_lshl_add_u32 v179, v186, 5, v174
	v_lshl_add_u32 v155, v179, 7, v180
	v_lshl_add_u32 v179, v187, 5, v174
	v_lshl_add_u32 v159, v179, 7, v180
	v_or_b32_e32 v180, 4, v182
	v_xor_b32_e32 v180, v180, v183
	v_lshlrev_b32_e32 v180, 4, v180
	v_lshl_add_u32 v179, v186, 5, v174
	v_lshl_add_u32 v156, v179, 7, v180
	v_lshl_add_u32 v179, v187, 5, v174
	v_lshl_add_u32 v236, v179, 7, v180
	v_or_b32_e32 v180, 6, v182
	v_xor_b32_e32 v180, v180, v183
	v_lshlrev_b32_e32 v180, 4, v180
	v_lshl_add_u32 v179, v186, 5, v174
	v_lshl_add_u32 v157, v179, 7, v180
	v_lshl_add_u32 v179, v187, 5, v174
	v_lshl_add_u32 v237, v179, 7, v180
	v_lshlrev_b32_e32 v190, 6, v186
	v_lshl_add_u32 v190, v182, 2, v190
	v_lshl_add_u32 v191, v187, 6, v174
	v_lshlrev_b32_e32 v192, 12, v190
	v_lshl_add_u32 v162, v191, 2, v192
	v_add_u32_e32 v163, 0x1000, v162
	v_add_u32_e32 v164, 0x2000, v162
	v_add_u32_e32 v165, 0x3000, v162
	v_lshlrev_b32_e32 v166, 2, v191
	v_mul_u32_u24_e32 v167, 0xc000, v187
	v_lshl_add_u32 v167, v190, 2, v167
	v_xor_b32_e32 v168, 16, v177
	v_lshlrev_b32_e32 v168, 2, v168
	v_xor_b32_e32 v169, 8, v177
	v_lshlrev_b32_e32 v169, 2, v169
	v_xor_b32_e32 v171, 4, v177
	v_lshlrev_b32_e32 v171, 2, v171
	v_xor_b32_e32 v172, 2, v177
	v_lshlrev_b32_e32 v172, 2, v172
	v_xor_b32_e32 v173, 1, v177
	v_lshlrev_b32_e32 v173, 2, v173
	v_readfirstlane_b32 s65, v194
	s_nop 0
	s_lshl_b32 s65, s65, 4
	s_add_u32 s65, s65, 16
	s_mov_b32 s16, s83
.Lhw_outproj_tloop:
	s_cmpk_gt_u32 s16, 47
	s_cbranch_scc1 .Lhw_outproj_exit
	v_readlane_b32 s6, v246, 16
	s_lshr_b32 s2, s16, 2
	s_and_b32 s15, s16, 3
	s_add_i32 s6, s6, s2
	s_lshl_b32 s6, s6, 7
	s_lshl_b32 s15, s15, 8
	s_mul_i32 vcc_lo, s6, 0x800
	s_add_u32 s66, s42, vcc_lo
	s_addc_u32 s67, s43, 0
	s_mul_i32 vcc_lo, s15, 0x800
	s_add_u32 s62, s46, vcc_lo
	s_addc_u32 s63, s47, 0
	s_add_u32 s18, s62, 0x40000
	s_addc_u32 s19, s63, 0
	s_barrier
	s_add_u32 m0, s65, 0x6000
	s_nop 0
	global_load_lds_dwordx4 v160, s[62:63]
	s_add_u32 m0, s65, 0x7000
	s_nop 0
	global_load_lds_dwordx4 v161, s[62:63]
	s_add_u32 m0, s65, 0x8000
	s_nop 0
	global_load_lds_dwordx4 v160, s[66:67]
	s_add_u32 m0, s65, 0x9000
	s_nop 0
	global_load_lds_dwordx4 v161, s[66:67]
	s_add_u32 m0, s65, 0xa000
	s_nop 0
	global_load_lds_dwordx4 v242, s[66:67]
	s_add_u32 m0, s65, 0xb000
	s_nop 0
	global_load_lds_dwordx4 v243, s[66:67]
	s_add_u32 m0, s65, 0x0
	s_nop 0
	global_load_lds_dwordx4 v242, s[62:63]
	s_add_u32 m0, s65, 0x1000
	s_nop 0
	global_load_lds_dwordx4 v243, s[62:63]
	s_add_u32 m0, s65, 0x2000
	s_nop 0
	global_load_lds_dwordx4 v160, s[18:19]
	s_add_u32 m0, s65, 0x3000
	s_nop 0
	global_load_lds_dwordx4 v161, s[18:19]
	v_mov_b32_e32 v2, 0
	v_mov_b32_e32 v3, 0
	v_mov_b32_e32 v4, 0
	v_mov_b32_e32 v5, 0
	v_mov_b32_e32 v6, 0
	v_mov_b32_e32 v7, 0
	v_mov_b32_e32 v8, 0
	v_mov_b32_e32 v9, 0
	v_mov_b32_e32 v10, 0
	v_mov_b32_e32 v11, 0
	v_mov_b32_e32 v12, 0
	v_mov_b32_e32 v13, 0
	v_mov_b32_e32 v14, 0
	v_mov_b32_e32 v15, 0
	v_mov_b32_e32 v16, 0
	v_mov_b32_e32 v17, 0
	v_mov_b32_e32 v18, 0
	v_mov_b32_e32 v19, 0
	v_mov_b32_e32 v20, 0
	v_mov_b32_e32 v21, 0
	v_mov_b32_e32 v22, 0
	v_mov_b32_e32 v23, 0
	v_mov_b32_e32 v24, 0
	v_mov_b32_e32 v25, 0
	v_mov_b32_e32 v26, 0
	v_mov_b32_e32 v27, 0
	v_mov_b32_e32 v28, 0
	v_mov_b32_e32 v29, 0
	v_mov_b32_e32 v30, 0
	v_mov_b32_e32 v31, 0
	v_mov_b32_e32 v32, 0
	v_mov_b32_e32 v33, 0
	v_mov_b32_e32 v34, 0
	v_mov_b32_e32 v35, 0
	v_mov_b32_e32 v36, 0
	v_mov_b32_e32 v37, 0
	v_mov_b32_e32 v38, 0
	v_mov_b32_e32 v39, 0
	v_mov_b32_e32 v40, 0
	v_mov_b32_e32 v41, 0
	v_mov_b32_e32 v42, 0
	v_mov_b32_e32 v43, 0
	v_mov_b32_e32 v44, 0
	v_mov_b32_e32 v45, 0
	v_mov_b32_e32 v46, 0
	v_mov_b32_e32 v47, 0
	v_mov_b32_e32 v48, 0
	v_mov_b32_e32 v49, 0
	v_mov_b32_e32 v50, 0
	v_mov_b32_e32 v51, 0
	v_mov_b32_e32 v52, 0
	v_mov_b32_e32 v53, 0
	v_mov_b32_e32 v54, 0
	v_mov_b32_e32 v55, 0
	v_mov_b32_e32 v56, 0
	v_mov_b32_e32 v57, 0
	v_mov_b32_e32 v58, 0
	v_mov_b32_e32 v59, 0
	v_mov_b32_e32 v60, 0
	v_mov_b32_e32 v61, 0
	v_mov_b32_e32 v62, 0
	v_mov_b32_e32 v63, 0
	v_mov_b32_e32 v64, 0
	v_mov_b32_e32 v65, 0
	v_mov_b32_e32 v66, 0
	v_mov_b32_e32 v67, 0
	v_mov_b32_e32 v68, 0
	v_mov_b32_e32 v69, 0
	v_mov_b32_e32 v70, 0
	v_mov_b32_e32 v71, 0
	v_mov_b32_e32 v72, 0
	v_mov_b32_e32 v73, 0
	v_mov_b32_e32 v74, 0
	v_mov_b32_e32 v75, 0
	v_mov_b32_e32 v76, 0
	v_mov_b32_e32 v77, 0
	v_mov_b32_e32 v78, 0
	v_mov_b32_e32 v79, 0
	v_mov_b32_e32 v80, 0
	v_mov_b32_e32 v81, 0
	v_mov_b32_e32 v82, 0
	v_mov_b32_e32 v83, 0
	v_mov_b32_e32 v84, 0
	v_mov_b32_e32 v85, 0
	v_mov_b32_e32 v86, 0
	v_mov_b32_e32 v87, 0
	v_mov_b32_e32 v88, 0
	v_mov_b32_e32 v89, 0
	v_mov_b32_e32 v90, 0
	v_mov_b32_e32 v91, 0
	v_mov_b32_e32 v92, 0
	v_mov_b32_e32 v93, 0
	v_mov_b32_e32 v94, 0
	v_mov_b32_e32 v95, 0
	v_mov_b32_e32 v96, 0
	v_mov_b32_e32 v97, 0
	v_mov_b32_e32 v98, 0
	v_mov_b32_e32 v99, 0
	v_mov_b32_e32 v100, 0
	v_mov_b32_e32 v101, 0
	v_mov_b32_e32 v102, 0
	v_mov_b32_e32 v103, 0
	v_mov_b32_e32 v104, 0
	v_mov_b32_e32 v105, 0
	v_mov_b32_e32 v106, 0
	v_mov_b32_e32 v107, 0
	v_mov_b32_e32 v108, 0
	v_mov_b32_e32 v109, 0
	v_mov_b32_e32 v110, 0
	v_mov_b32_e32 v111, 0
	v_mov_b32_e32 v112, 0
	v_mov_b32_e32 v113, 0
	v_mov_b32_e32 v114, 0
	v_mov_b32_e32 v115, 0
	v_mov_b32_e32 v116, 0
	v_mov_b32_e32 v117, 0
	v_mov_b32_e32 v118, 0
	v_mov_b32_e32 v119, 0
	v_mov_b32_e32 v120, 0
	v_mov_b32_e32 v121, 0
	v_mov_b32_e32 v122, 0
	v_mov_b32_e32 v123, 0
	v_mov_b32_e32 v124, 0
	v_mov_b32_e32 v125, 0
	v_mov_b32_e32 v126, 0
	v_mov_b32_e32 v127, 0
	v_mov_b32_e32 v128, 0
	v_mov_b32_e32 v129, 0
	s_waitcnt vmcnt(0)
	s_barrier
	ds_read_b128 v[130:133], v154 offset:32784
	ds_read_b128 v[146:149], v154 offset:40976
	ds_read_b128 v[220:223], v158 offset:24592
	ds_read_b128 v[134:137], v155 offset:32784
	ds_read_b128 v[150:153], v155 offset:40976
	ds_read_b128 v[224:227], v159 offset:24592
	ds_read_b128 v[138:141], v156 offset:32784
	ds_read_b128 v[212:215], v156 offset:40976
	ds_read_b128 v[228:231], v236 offset:24592
	ds_read_b128 v[142:145], v157 offset:32784
	ds_read_b128 v[216:219], v157 offset:40976
	ds_read_b128 v[232:235], v237 offset:24592
	s_waitcnt lgkmcnt(0)
	s_barrier
	s_mov_b32 s59, 15
.Lhw_outproj_loop:
	v_mfma_f32_32x32x16_bf16 v[2:17], v[130:133], v[220:223], v[2:17]
	s_add_u32 m0, s65, 0x4000
	s_nop 0
	global_load_lds_dwordx4 v242, s[18:19]
	v_mfma_f32_32x32x16_bf16 v[34:49], v[146:149], v[220:223], v[34:49]
	s_add_u32 m0, s65, 0x5000
	ds_read_b128 v[220:223], v158 offset:16
	global_load_lds_dwordx4 v243, s[18:19]
	v_mfma_f32_32x32x16_bf16 v[2:17], v[134:137], v[224:227], v[2:17]
	s_add_u32 s62, s62, 128
	s_addc_u32 s63, s63, 0
	s_add_u32 s66, s66, 128
	s_addc_u32 s67, s67, 0
	v_mfma_f32_32x32x16_bf16 v[34:49], v[150:153], v[224:227], v[34:49]
	s_add_u32 m0, s65, 0x6000
	ds_read_b128 v[224:227], v159 offset:16
	global_load_lds_dwordx4 v160, s[62:63]
	v_mfma_f32_32x32x16_bf16 v[2:17], v[138:141], v[228:231], v[2:17]
	s_add_u32 m0, s65, 0x7000
	s_nop 0
	global_load_lds_dwordx4 v161, s[62:63]
	v_mfma_f32_32x32x16_bf16 v[34:49], v[212:215], v[228:231], v[34:49]
	s_add_u32 m0, s65, 0x8000
	ds_read_b128 v[228:231], v236 offset:16
	global_load_lds_dwordx4 v160, s[66:67]
	v_mfma_f32_32x32x16_bf16 v[2:17], v[142:145], v[232:235], v[2:17]
	s_add_u32 m0, s65, 0x9000
	s_nop 0
	global_load_lds_dwordx4 v161, s[66:67]
	v_mfma_f32_32x32x16_bf16 v[34:49], v[216:219], v[232:235], v[34:49]
	s_add_u32 m0, s65, 0xa000
	ds_read_b128 v[232:235], v237 offset:16
	global_load_lds_dwordx4 v242, s[66:67]
	s_waitcnt lgkmcnt(3)
	v_mfma_f32_32x32x16_bf16 v[18:33], v[130:133], v[220:223], v[18:33]
	s_add_u32 m0, s65, 0xb000
	s_nop 0
	global_load_lds_dwordx4 v243, s[66:67]
	v_mfma_f32_32x32x16_bf16 v[50:65], v[146:149], v[220:223], v[50:65]
	ds_read_b128 v[220:223], v158 offset:8208
	s_waitcnt lgkmcnt(3)
	v_mfma_f32_32x32x16_bf16 v[18:33], v[134:137], v[224:227], v[18:33]
	v_mfma_f32_32x32x16_bf16 v[50:65], v[150:153], v[224:227], v[50:65]
	ds_read_b128 v[224:227], v159 offset:8208
	s_waitcnt lgkmcnt(3)
	v_mfma_f32_32x32x16_bf16 v[18:33], v[138:141], v[228:231], v[18:33]
	v_mfma_f32_32x32x16_bf16 v[50:65], v[212:215], v[228:231], v[50:65]
	ds_read_b128 v[228:231], v236 offset:8208
	s_waitcnt lgkmcnt(3)
	v_mfma_f32_32x32x16_bf16 v[18:33], v[142:145], v[232:235], v[18:33]
	v_mfma_f32_32x32x16_bf16 v[50:65], v[216:219], v[232:235], v[50:65]
	ds_read_b128 v[232:235], v237 offset:8208
	s_waitcnt vmcnt(0) lgkmcnt(0)
	s_barrier
	v_mfma_f32_32x32x16_bf16 v[66:81], v[130:133], v[220:223], v[66:81]
	s_add_u32 s18, s18, 128
	s_addc_u32 s19, s19, 0
	v_mfma_f32_32x32x16_bf16 v[98:113], v[146:149], v[220:223], v[98:113]
	s_add_u32 m0, s65, 0x0
	ds_read_b128 v[220:223], v158 offset:16400
	global_load_lds_dwordx4 v242, s[62:63]
	v_mfma_f32_32x32x16_bf16 v[66:81], v[134:137], v[224:227], v[66:81]
	s_add_u32 m0, s65, 0x1000
	s_nop 0
	global_load_lds_dwordx4 v243, s[62:63]
	v_mfma_f32_32x32x16_bf16 v[98:113], v[150:153], v[224:227], v[98:113]
	s_add_u32 m0, s65, 0x2000
	ds_read_b128 v[224:227], v159 offset:16400
	global_load_lds_dwordx4 v160, s[18:19]
	v_mfma_f32_32x32x16_bf16 v[66:81], v[138:141], v[228:231], v[66:81]
	s_add_u32 m0, s65, 0x3000
	s_nop 0
	global_load_lds_dwordx4 v161, s[18:19]
	v_mfma_f32_32x32x16_bf16 v[98:113], v[212:215], v[228:231], v[98:113]
	ds_read_b128 v[228:231], v236 offset:16400
	v_mfma_f32_32x32x16_bf16 v[66:81], v[142:145], v[232:235], v[66:81]
	v_mfma_f32_32x32x16_bf16 v[98:113], v[216:219], v[232:235], v[98:113]
	ds_read_b128 v[232:235], v237 offset:16400
	s_waitcnt lgkmcnt(3)
	v_mfma_f32_32x32x16_bf16 v[82:97], v[130:133], v[220:223], v[82:97]
	ds_read_b128 v[130:133], v154 offset:32784
	v_mfma_f32_32x32x16_bf16 v[114:129], v[146:149], v[220:223], v[114:129]
	ds_read_b128 v[220:223], v158 offset:24592
	ds_read_b128 v[146:149], v154 offset:40976
	s_waitcnt lgkmcnt(5)
	v_mfma_f32_32x32x16_bf16 v[82:97], v[134:137], v[224:227], v[82:97]
	ds_read_b128 v[134:137], v155 offset:32784
	v_mfma_f32_32x32x16_bf16 v[114:129], v[150:153], v[224:227], v[114:129]
	ds_read_b128 v[224:227], v159 offset:24592
	ds_read_b128 v[150:153], v155 offset:40976
	s_waitcnt lgkmcnt(7)
	v_mfma_f32_32x32x16_bf16 v[82:97], v[138:141], v[228:231], v[82:97]
	ds_read_b128 v[138:141], v156 offset:32784
	v_mfma_f32_32x32x16_bf16 v[114:129], v[212:215], v[228:231], v[114:129]
	ds_read_b128 v[228:231], v236 offset:24592
	ds_read_b128 v[212:215], v156 offset:40976
	s_waitcnt lgkmcnt(9)
	v_mfma_f32_32x32x16_bf16 v[82:97], v[142:145], v[232:235], v[82:97]
	ds_read_b128 v[142:145], v157 offset:32784
	v_mfma_f32_32x32x16_bf16 v[114:129], v[216:219], v[232:235], v[114:129]
	ds_read_b128 v[232:235], v237 offset:24592
	ds_read_b128 v[216:219], v157 offset:40976
	s_waitcnt vmcnt(0) lgkmcnt(0)
	s_barrier
	s_sub_u32 s59, s59, 1
	s_cmp_lg_u32 s59, 0
	s_cbranch_scc1 .Lhw_outproj_loop
	v_mfma_f32_32x32x16_bf16 v[2:17], v[130:133], v[220:223], v[2:17]
	s_add_u32 m0, s65, 0x4000
	s_nop 0
	global_load_lds_dwordx4 v242, s[18:19]
	v_mfma_f32_32x32x16_bf16 v[34:49], v[146:149], v[220:223], v[34:49]
	s_add_u32 m0, s65, 0x5000
	ds_read_b128 v[220:223], v158 offset:16
	global_load_lds_dwordx4 v243, s[18:19]
	v_mfma_f32_32x32x16_bf16 v[2:17], v[134:137], v[224:227], v[2:17]
	v_mfma_f32_32x32x16_bf16 v[34:49], v[150:153], v[224:227], v[34:49]
	ds_read_b128 v[224:227], v159 offset:16
	v_mfma_f32_32x32x16_bf16 v[2:17], v[138:141], v[228:231], v[2:17]
	v_mfma_f32_32x32x16_bf16 v[34:49], v[212:215], v[228:231], v[34:49]
	ds_read_b128 v[228:231], v236 offset:16
	v_mfma_f32_32x32x16_bf16 v[2:17], v[142:145], v[232:235], v[2:17]
	v_mfma_f32_32x32x16_bf16 v[34:49], v[216:219], v[232:235], v[34:49]
	ds_read_b128 v[232:235], v237 offset:16
	s_waitcnt lgkmcnt(3)
	v_mfma_f32_32x32x16_bf16 v[18:33], v[130:133], v[220:223], v[18:33]
	v_mfma_f32_32x32x16_bf16 v[50:65], v[146:149], v[220:223], v[50:65]
	ds_read_b128 v[220:223], v158 offset:8208
	s_waitcnt lgkmcnt(3)
	v_mfma_f32_32x32x16_bf16 v[18:33], v[134:137], v[224:227], v[18:33]
	v_mfma_f32_32x32x16_bf16 v[50:65], v[150:153], v[224:227], v[50:65]
	ds_read_b128 v[224:227], v159 offset:8208
	s_waitcnt lgkmcnt(3)
	v_mfma_f32_32x32x16_bf16 v[18:33], v[138:141], v[228:231], v[18:33]
	v_mfma_f32_32x32x16_bf16 v[50:65], v[212:215], v[228:231], v[50:65]
	ds_read_b128 v[228:231], v236 offset:8208
	s_waitcnt lgkmcnt(3)
	v_mfma_f32_32x32x16_bf16 v[18:33], v[142:145], v[232:235], v[18:33]
	v_mfma_f32_32x32x16_bf16 v[50:65], v[216:219], v[232:235], v[50:65]
	ds_read_b128 v[232:235], v237 offset:8208
	s_waitcnt vmcnt(0) lgkmcnt(0)
	s_barrier
	v_mfma_f32_32x32x16_bf16 v[66:81], v[130:133], v[220:223], v[66:81]
	v_mfma_f32_32x32x16_bf16 v[98:113], v[146:149], v[220:223], v[98:113]
	ds_read_b128 v[220:223], v158 offset:16400
	v_mfma_f32_32x32x16_bf16 v[66:81], v[134:137], v[224:227], v[66:81]
	v_mfma_f32_32x32x16_bf16 v[98:113], v[150:153], v[224:227], v[98:113]
	ds_read_b128 v[224:227], v159 offset:16400
	v_mfma_f32_32x32x16_bf16 v[66:81], v[138:141], v[228:231], v[66:81]
	v_mfma_f32_32x32x16_bf16 v[98:113], v[212:215], v[228:231], v[98:113]
	ds_read_b128 v[228:231], v236 offset:16400
	v_mfma_f32_32x32x16_bf16 v[66:81], v[142:145], v[232:235], v[66:81]
	v_mfma_f32_32x32x16_bf16 v[98:113], v[216:219], v[232:235], v[98:113]
	ds_read_b128 v[232:235], v237 offset:16400
	s_waitcnt lgkmcnt(3)
	v_mfma_f32_32x32x16_bf16 v[82:97], v[130:133], v[220:223], v[82:97]
	v_mfma_f32_32x32x16_bf16 v[114:129], v[146:149], v[220:223], v[114:129]
	s_waitcnt lgkmcnt(2)
	v_mfma_f32_32x32x16_bf16 v[82:97], v[134:137], v[224:227], v[82:97]
	v_mfma_f32_32x32x16_bf16 v[114:129], v[150:153], v[224:227], v[114:129]
	s_waitcnt lgkmcnt(1)
	v_mfma_f32_32x32x16_bf16 v[82:97], v[138:141], v[228:231], v[82:97]
	v_mfma_f32_32x32x16_bf16 v[114:129], v[212:215], v[228:231], v[114:129]
	s_waitcnt lgkmcnt(0)
	v_mfma_f32_32x32x16_bf16 v[82:97], v[142:145], v[232:235], v[82:97]
	v_mfma_f32_32x32x16_bf16 v[114:129], v[216:219], v[232:235], v[114:129]
	s_nop 7
	s_nop 7
	s_sub_i32 s2, s6, 0x1000
	s_ashr_i32 s2, s2, 11
	s_add_i32 s2, s2, 1
	s_max_i32 s2, s2, 0
	v_readlane_b32 s17, v246, 28
	s_nop 0
	s_add_i32 s2, s2, s17
	s_mul_i32 s2, s2, 0x9000
	s_lshl_b32 s17, s15, 2
	s_add_u32 s2, s2, s17
	s_add_u32 s60, s8, s2
	s_addc_u32 s61, s9, 0
	s_lshr_b32 s2, s15, 7
	s_mul_i32 s2, s2, 0x18000
	s_lshl_b32 s20, s6, 2
	s_add_u32 s2, s2, s20
	s_add_u32 s10, s44, s2
	s_addc_u32 s11, s45, 0
	s_lshl_b32 s2, s6, 12
	s_add_u32 s2, s2, s17
	s_add_u32 s48, s40, s2
	s_addc_u32 s49, s41, 0
	global_load_dword v175, v166, s[60:61]
	global_load_dword v176, v166, s[60:61] offset:128
	global_load_dword v130, v162, s[48:49]
	global_load_dword v212, v162, s[48:49] offset:128
	global_load_dword v131, v163, s[48:49]
	global_load_dword v213, v163, s[48:49] offset:128
	global_load_dword v132, v164, s[48:49]
	global_load_dword v214, v164, s[48:49] offset:128
	global_load_dword v133, v165, s[48:49]
	global_load_dword v215, v165, s[48:49] offset:128
	s_add_u32 s48, s48, 0x8000
	s_addc_u32 s49, s49, 0
	global_load_dword v134, v162, s[48:49]
	global_load_dword v216, v162, s[48:49] offset:128
	global_load_dword v135, v163, s[48:49]
	global_load_dword v217, v163, s[48:49] offset:128
	global_load_dword v136, v164, s[48:49]
	global_load_dword v218, v164, s[48:49] offset:128
	global_load_dword v137, v165, s[48:49]
	global_load_dword v219, v165, s[48:49] offset:128
	s_add_u32 s48, s48, 0x8000
	s_addc_u32 s49, s49, 0
	global_load_dword v138, v162, s[48:49]
	global_load_dword v220, v162, s[48:49] offset:128
	global_load_dword v139, v163, s[48:49]
	global_load_dword v221, v163, s[48:49] offset:128
	global_load_dword v140, v164, s[48:49]
	global_load_dword v222, v164, s[48:49] offset:128
	global_load_dword v141, v165, s[48:49]
	global_load_dword v223, v165, s[48:49] offset:128
	s_add_u32 s48, s48, 0x8000
	s_addc_u32 s49, s49, 0
	global_load_dword v142, v162, s[48:49]
	global_load_dword v224, v162, s[48:49] offset:128
	global_load_dword v143, v163, s[48:49]
	global_load_dword v225, v163, s[48:49] offset:128
	global_load_dword v144, v164, s[48:49]
	global_load_dword v226, v164, s[48:49] offset:128
	global_load_dword v145, v165, s[48:49]
	global_load_dword v227, v165, s[48:49] offset:128
	s_sub_u32 s48, s48, 0x18000
	s_subb_u32 s49, s49, 0
	s_waitcnt vmcnt(32)
	s_waitcnt vmcnt(30)
	v_fmac_f32_e32 v130, v2, v175
	v_fmac_f32_e32 v212, v18, v176
	global_store_dword v162, v130, s[48:49]
	global_store_dword v162, v212, s[48:49] offset:128
	s_waitcnt vmcnt(30)
	v_fmac_f32_e32 v131, v3, v175
	v_fmac_f32_e32 v213, v19, v176
	global_store_dword v163, v131, s[48:49]
	global_store_dword v163, v213, s[48:49] offset:128
	s_waitcnt vmcnt(30)
	v_fmac_f32_e32 v132, v4, v175
	v_fmac_f32_e32 v214, v20, v176
	global_store_dword v164, v132, s[48:49]
	global_store_dword v164, v214, s[48:49] offset:128
	s_waitcnt vmcnt(30)
	v_fmac_f32_e32 v133, v5, v175
	v_fmac_f32_e32 v215, v21, v176
	global_store_dword v165, v133, s[48:49]
	global_store_dword v165, v215, s[48:49] offset:128
	s_add_u32 s48, s48, 0x8000
	s_addc_u32 s49, s49, 0
	s_waitcnt vmcnt(30)
	v_fmac_f32_e32 v134, v6, v175
	v_fmac_f32_e32 v216, v22, v176
	global_store_dword v162, v134, s[48:49]
	global_store_dword v162, v216, s[48:49] offset:128
	s_waitcnt vmcnt(30)
	v_fmac_f32_e32 v135, v7, v175
	v_fmac_f32_e32 v217, v23, v176
	global_store_dword v163, v135, s[48:49]
	global_store_dword v163, v217, s[48:49] offset:128
	s_waitcnt vmcnt(30)
	v_fmac_f32_e32 v136, v8, v175
	v_fmac_f32_e32 v218, v24, v176
	global_store_dword v164, v136, s[48:49]
	global_store_dword v164, v218, s[48:49] offset:128
	s_waitcnt vmcnt(30)
	v_fmac_f32_e32 v137, v9, v175
	v_fmac_f32_e32 v219, v25, v176
	global_store_dword v165, v137, s[48:49]
	global_store_dword v165, v219, s[48:49] offset:128
	s_add_u32 s48, s48, 0x8000
	s_addc_u32 s49, s49, 0
	s_waitcnt vmcnt(30)
	v_fmac_f32_e32 v138, v10, v175
	v_fmac_f32_e32 v220, v26, v176
	global_store_dword v162, v138, s[48:49]
	global_store_dword v162, v220, s[48:49] offset:128
	s_waitcnt vmcnt(30)
	v_fmac_f32_e32 v139, v11, v175
	v_fmac_f32_e32 v221, v27, v176
	global_store_dword v163, v139, s[48:49]
	global_store_dword v163, v221, s[48:49] offset:128
	s_waitcnt vmcnt(30)
	v_fmac_f32_e32 v140, v12, v175
	v_fmac_f32_e32 v222, v28, v176
	global_store_dword v164, v140, s[48:49]
	global_store_dword v164, v222, s[48:49] offset:128
	s_waitcnt vmcnt(30)
	v_fmac_f32_e32 v141, v13, v175
	v_fmac_f32_e32 v223, v29, v176
	global_store_dword v165, v141, s[48:49]
	global_store_dword v165, v223, s[48:49] offset:128
	s_add_u32 s48, s48, 0x8000
	s_addc_u32 s49, s49, 0
	s_waitcnt vmcnt(30)
	v_fmac_f32_e32 v142, v14, v175
	v_fmac_f32_e32 v224, v30, v176
	global_store_dword v162, v142, s[48:49]
	global_store_dword v162, v224, s[48:49] offset:128
	s_waitcnt vmcnt(30)
	v_fmac_f32_e32 v143, v15, v175
	v_fmac_f32_e32 v225, v31, v176
	global_store_dword v163, v143, s[48:49]
	global_store_dword v163, v225, s[48:49] offset:128
	s_waitcnt vmcnt(30)
	v_fmac_f32_e32 v144, v16, v175
	v_fmac_f32_e32 v226, v32, v176
	global_store_dword v164, v144, s[48:49]
	global_store_dword v164, v226, s[48:49] offset:128
	s_waitcnt vmcnt(30)
	v_fmac_f32_e32 v145, v17, v175
	v_fmac_f32_e32 v227, v33, v176
	global_store_dword v165, v145, s[48:49]
	global_store_dword v165, v227, s[48:49] offset:128
	s_sub_u32 s48, s48, 0x18000
	s_subb_u32 s49, s49, 0
	v_mul_f32_e32 v130, v130, v130
	v_fmac_f32_e32 v130, v212, v212
	v_mul_f32_e32 v131, v131, v131
	v_fmac_f32_e32 v131, v213, v213
	v_mul_f32_e32 v132, v132, v132
	v_fmac_f32_e32 v132, v214, v214
	v_mul_f32_e32 v133, v133, v133
	v_fmac_f32_e32 v133, v215, v215
	v_mul_f32_e32 v134, v134, v134
	v_fmac_f32_e32 v134, v216, v216
	v_mul_f32_e32 v135, v135, v135
	v_fmac_f32_e32 v135, v217, v217
	v_mul_f32_e32 v136, v136, v136
	v_fmac_f32_e32 v136, v218, v218
	v_mul_f32_e32 v137, v137, v137
	v_fmac_f32_e32 v137, v219, v219
	v_mul_f32_e32 v138, v138, v138
	v_fmac_f32_e32 v138, v220, v220
	v_mul_f32_e32 v139, v139, v139
	v_fmac_f32_e32 v139, v221, v221
	v_mul_f32_e32 v140, v140, v140
	v_fmac_f32_e32 v140, v222, v222
	v_mul_f32_e32 v141, v141, v141
	v_fmac_f32_e32 v141, v223, v223
	v_mul_f32_e32 v142, v142, v142
	v_fmac_f32_e32 v142, v224, v224
	v_mul_f32_e32 v143, v143, v143
	v_fmac_f32_e32 v143, v225, v225
	v_mul_f32_e32 v144, v144, v144
	v_fmac_f32_e32 v144, v226, v226
	v_mul_f32_e32 v145, v145, v145
	v_fmac_f32_e32 v145, v227, v227
	s_waitcnt lgkmcnt(0)
	ds_bpermute_b32 v212, v168, v130
	ds_bpermute_b32 v213, v168, v131
	ds_bpermute_b32 v214, v168, v132
	ds_bpermute_b32 v215, v168, v133
	ds_bpermute_b32 v216, v168, v134
	ds_bpermute_b32 v217, v168, v135
	ds_bpermute_b32 v218, v168, v136
	ds_bpermute_b32 v219, v168, v137
	s_waitcnt lgkmcnt(7)
	v_add_f32_e32 v130, v130, v212
	s_waitcnt lgkmcnt(6)
	v_add_f32_e32 v131, v131, v213
	s_waitcnt lgkmcnt(5)
	v_add_f32_e32 v132, v132, v214
	s_waitcnt lgkmcnt(4)
	v_add_f32_e32 v133, v133, v215
	s_waitcnt lgkmcnt(3)
	v_add_f32_e32 v134, v134, v216
	s_waitcnt lgkmcnt(2)
	v_add_f32_e32 v135, v135, v217
	s_waitcnt lgkmcnt(1)
	v_add_f32_e32 v136, v136, v218
	s_waitcnt lgkmcnt(0)
	v_add_f32_e32 v137, v137, v219
	ds_bpermute_b32 v212, v169, v130
	ds_bpermute_b32 v213, v169, v131
	ds_bpermute_b32 v214, v169, v132
	ds_bpermute_b32 v215, v169, v133
	ds_bpermute_b32 v216, v169, v134
	ds_bpermute_b32 v217, v169, v135
	ds_bpermute_b32 v218, v169, v136
	ds_bpermute_b32 v219, v169, v137
	s_waitcnt lgkmcnt(7)
	v_add_f32_e32 v130, v130, v212
	s_waitcnt lgkmcnt(6)
	v_add_f32_e32 v131, v131, v213
	s_waitcnt lgkmcnt(5)
	v_add_f32_e32 v132, v132, v214
	s_waitcnt lgkmcnt(4)
	v_add_f32_e32 v133, v133, v215
	s_waitcnt lgkmcnt(3)
	v_add_f32_e32 v134, v134, v216
	s_waitcnt lgkmcnt(2)
	v_add_f32_e32 v135, v135, v217
	s_waitcnt lgkmcnt(1)
	v_add_f32_e32 v136, v136, v218
	s_waitcnt lgkmcnt(0)
	v_add_f32_e32 v137, v137, v219
	ds_bpermute_b32 v212, v171, v130
	ds_bpermute_b32 v213, v171, v131
	ds_bpermute_b32 v214, v171, v132
	ds_bpermute_b32 v215, v171, v133
	ds_bpermute_b32 v216, v171, v134
	ds_bpermute_b32 v217, v171, v135
	ds_bpermute_b32 v218, v171, v136
	ds_bpermute_b32 v219, v171, v137
	s_waitcnt lgkmcnt(7)
	v_add_f32_e32 v130, v130, v212
	s_waitcnt lgkmcnt(6)
	v_add_f32_e32 v131, v131, v213
	s_waitcnt lgkmcnt(5)
	v_add_f32_e32 v132, v132, v214
	s_waitcnt lgkmcnt(4)
	v_add_f32_e32 v133, v133, v215
	s_waitcnt lgkmcnt(3)
	v_add_f32_e32 v134, v134, v216
	s_waitcnt lgkmcnt(2)
	v_add_f32_e32 v135, v135, v217
	s_waitcnt lgkmcnt(1)
	v_add_f32_e32 v136, v136, v218
	s_waitcnt lgkmcnt(0)
	v_add_f32_e32 v137, v137, v219
	ds_bpermute_b32 v212, v172, v130
	ds_bpermute_b32 v213, v172, v131
	ds_bpermute_b32 v214, v172, v132
	ds_bpermute_b32 v215, v172, v133
	ds_bpermute_b32 v216, v172, v134
	ds_bpermute_b32 v217, v172, v135
	ds_bpermute_b32 v218, v172, v136
	ds_bpermute_b32 v219, v172, v137
	s_waitcnt lgkmcnt(7)
	v_add_f32_e32 v130, v130, v212
	s_waitcnt lgkmcnt(6)
	v_add_f32_e32 v131, v131, v213
	s_waitcnt lgkmcnt(5)
	v_add_f32_e32 v132, v132, v214
	s_waitcnt lgkmcnt(4)
	v_add_f32_e32 v133, v133, v215
	s_waitcnt lgkmcnt(3)
	v_add_f32_e32 v134, v134, v216
	s_waitcnt lgkmcnt(2)
	v_add_f32_e32 v135, v135, v217
	s_waitcnt lgkmcnt(1)
	v_add_f32_e32 v136, v136, v218
	s_waitcnt lgkmcnt(0)
	v_add_f32_e32 v137, v137, v219
	ds_bpermute_b32 v212, v173, v130
	ds_bpermute_b32 v213, v173, v131
	ds_bpermute_b32 v214, v173, v132
	ds_bpermute_b32 v215, v173, v133
	ds_bpermute_b32 v216, v173, v134
	ds_bpermute_b32 v217, v173, v135
	ds_bpermute_b32 v218, v173, v136
	ds_bpermute_b32 v219, v173, v137
	s_waitcnt lgkmcnt(7)
	v_add_f32_e32 v130, v130, v212
	s_waitcnt lgkmcnt(6)
	v_add_f32_e32 v131, v131, v213
	s_waitcnt lgkmcnt(5)
	v_add_f32_e32 v132, v132, v214
	s_waitcnt lgkmcnt(4)
	v_add_f32_e32 v133, v133, v215
	s_waitcnt lgkmcnt(3)
	v_add_f32_e32 v134, v134, v216
	s_waitcnt lgkmcnt(2)
	v_add_f32_e32 v135, v135, v217
	s_waitcnt lgkmcnt(1)
	v_add_f32_e32 v136, v136, v218
	s_waitcnt lgkmcnt(0)
	v_add_f32_e32 v137, v137, v219
	ds_bpermute_b32 v220, v168, v138
	ds_bpermute_b32 v221, v168, v139
	ds_bpermute_b32 v222, v168, v140
	ds_bpermute_b32 v223, v168, v141
	ds_bpermute_b32 v224, v168, v142
	ds_bpermute_b32 v225, v168, v143
	ds_bpermute_b32 v226, v168, v144
	ds_bpermute_b32 v227, v168, v145
	s_waitcnt lgkmcnt(7)
	v_add_f32_e32 v138, v138, v220
	s_waitcnt lgkmcnt(6)
	v_add_f32_e32 v139, v139, v221
	s_waitcnt lgkmcnt(5)
	v_add_f32_e32 v140, v140, v222
	s_waitcnt lgkmcnt(4)
	v_add_f32_e32 v141, v141, v223
	s_waitcnt lgkmcnt(3)
	v_add_f32_e32 v142, v142, v224
	s_waitcnt lgkmcnt(2)
	v_add_f32_e32 v143, v143, v225
	s_waitcnt lgkmcnt(1)
	v_add_f32_e32 v144, v144, v226
	s_waitcnt lgkmcnt(0)
	v_add_f32_e32 v145, v145, v227
	ds_bpermute_b32 v220, v169, v138
	ds_bpermute_b32 v221, v169, v139
	ds_bpermute_b32 v222, v169, v140
	ds_bpermute_b32 v223, v169, v141
	ds_bpermute_b32 v224, v169, v142
	ds_bpermute_b32 v225, v169, v143
	ds_bpermute_b32 v226, v169, v144
	ds_bpermute_b32 v227, v169, v145
	s_waitcnt lgkmcnt(7)
	v_add_f32_e32 v138, v138, v220
	s_waitcnt lgkmcnt(6)
	v_add_f32_e32 v139, v139, v221
	s_waitcnt lgkmcnt(5)
	v_add_f32_e32 v140, v140, v222
	s_waitcnt lgkmcnt(4)
	v_add_f32_e32 v141, v141, v223
	s_waitcnt lgkmcnt(3)
	v_add_f32_e32 v142, v142, v224
	s_waitcnt lgkmcnt(2)
	v_add_f32_e32 v143, v143, v225
	s_waitcnt lgkmcnt(1)
	v_add_f32_e32 v144, v144, v226
	s_waitcnt lgkmcnt(0)
	v_add_f32_e32 v145, v145, v227
	ds_bpermute_b32 v220, v171, v138
	ds_bpermute_b32 v221, v171, v139
	ds_bpermute_b32 v222, v171, v140
	ds_bpermute_b32 v223, v171, v141
	ds_bpermute_b32 v224, v171, v142
	ds_bpermute_b32 v225, v171, v143
	ds_bpermute_b32 v226, v171, v144
	ds_bpermute_b32 v227, v171, v145
	s_waitcnt lgkmcnt(7)
	v_add_f32_e32 v138, v138, v220
	s_waitcnt lgkmcnt(6)
	v_add_f32_e32 v139, v139, v221
	s_waitcnt lgkmcnt(5)
	v_add_f32_e32 v140, v140, v222
	s_waitcnt lgkmcnt(4)
	v_add_f32_e32 v141, v141, v223
	s_waitcnt lgkmcnt(3)
	v_add_f32_e32 v142, v142, v224
	s_waitcnt lgkmcnt(2)
	v_add_f32_e32 v143, v143, v225
	s_waitcnt lgkmcnt(1)
	v_add_f32_e32 v144, v144, v226
	s_waitcnt lgkmcnt(0)
	v_add_f32_e32 v145, v145, v227
	ds_bpermute_b32 v220, v172, v138
	ds_bpermute_b32 v221, v172, v139
	ds_bpermute_b32 v222, v172, v140
	ds_bpermute_b32 v223, v172, v141
	ds_bpermute_b32 v224, v172, v142
	ds_bpermute_b32 v225, v172, v143
	ds_bpermute_b32 v226, v172, v144
	ds_bpermute_b32 v227, v172, v145
	s_waitcnt lgkmcnt(7)
	v_add_f32_e32 v138, v138, v220
	s_waitcnt lgkmcnt(6)
	v_add_f32_e32 v139, v139, v221
	s_waitcnt lgkmcnt(5)
	v_add_f32_e32 v140, v140, v222
	s_waitcnt lgkmcnt(4)
	v_add_f32_e32 v141, v141, v223
	s_waitcnt lgkmcnt(3)
	v_add_f32_e32 v142, v142, v224
	s_waitcnt lgkmcnt(2)
	v_add_f32_e32 v143, v143, v225
	s_waitcnt lgkmcnt(1)
	v_add_f32_e32 v144, v144, v226
	s_waitcnt lgkmcnt(0)
	v_add_f32_e32 v145, v145, v227
	ds_bpermute_b32 v220, v173, v138
	ds_bpermute_b32 v221, v173, v139
	ds_bpermute_b32 v222, v173, v140
	ds_bpermute_b32 v223, v173, v141
	ds_bpermute_b32 v224, v173, v142
	ds_bpermute_b32 v225, v173, v143
	ds_bpermute_b32 v226, v173, v144
	ds_bpermute_b32 v227, v173, v145
	s_waitcnt lgkmcnt(7)
	v_add_f32_e32 v138, v138, v220
	s_waitcnt lgkmcnt(6)
	v_add_f32_e32 v139, v139, v221
	s_waitcnt lgkmcnt(5)
	v_add_f32_e32 v140, v140, v222
	s_waitcnt lgkmcnt(4)
	v_add_f32_e32 v141, v141, v223
	s_waitcnt lgkmcnt(3)
	v_add_f32_e32 v142, v142, v224
	s_waitcnt lgkmcnt(2)
	v_add_f32_e32 v143, v143, v225
	s_waitcnt lgkmcnt(1)
	v_add_f32_e32 v144, v144, v226
	s_waitcnt lgkmcnt(0)
	v_add_f32_e32 v145, v145, v227
	v_cmp_eq_u32_e32 vcc, 0, v174
	s_and_saveexec_b64 s[58:59], vcc
	global_store_dword v167, v130, s[10:11]
	global_store_dword v167, v131, s[10:11] offset:4
	global_store_dword v167, v132, s[10:11] offset:8
	global_store_dword v167, v133, s[10:11] offset:12
	global_store_dword v167, v134, s[10:11] offset:32
	global_store_dword v167, v135, s[10:11] offset:36
	global_store_dword v167, v136, s[10:11] offset:40
	global_store_dword v167, v137, s[10:11] offset:44
	global_store_dword v167, v138, s[10:11] offset:64
	global_store_dword v167, v139, s[10:11] offset:68
	global_store_dword v167, v140, s[10:11] offset:72
	global_store_dword v167, v141, s[10:11] offset:76
	global_store_dword v167, v142, s[10:11] offset:96
	global_store_dword v167, v143, s[10:11] offset:100
	global_store_dword v167, v144, s[10:11] offset:104
	global_store_dword v167, v145, s[10:11] offset:108
	s_mov_b64 exec, -1
	s_add_u32 s48, s48, 0x20000
	s_addc_u32 s49, s49, 0
	global_load_dword v130, v162, s[48:49]
	global_load_dword v212, v162, s[48:49] offset:128
	global_load_dword v131, v163, s[48:49]
	global_load_dword v213, v163, s[48:49] offset:128
	global_load_dword v132, v164, s[48:49]
	global_load_dword v214, v164, s[48:49] offset:128
	global_load_dword v133, v165, s[48:49]
	global_load_dword v215, v165, s[48:49] offset:128
	s_add_u32 s48, s48, 0x8000
	s_addc_u32 s49, s49, 0
	global_load_dword v134, v162, s[48:49]
	global_load_dword v216, v162, s[48:49] offset:128
	global_load_dword v135, v163, s[48:49]
	global_load_dword v217, v163, s[48:49] offset:128
	global_load_dword v136, v164, s[48:49]
	global_load_dword v218, v164, s[48:49] offset:128
	global_load_dword v137, v165, s[48:49]
	global_load_dword v219, v165, s[48:49] offset:128
	s_add_u32 s48, s48, 0x8000
	s_addc_u32 s49, s49, 0
	global_load_dword v138, v162, s[48:49]
	global_load_dword v220, v162, s[48:49] offset:128
	global_load_dword v139, v163, s[48:49]
	global_load_dword v221, v163, s[48:49] offset:128
	global_load_dword v140, v164, s[48:49]
	global_load_dword v222, v164, s[48:49] offset:128
	global_load_dword v141, v165, s[48:49]
	global_load_dword v223, v165, s[48:49] offset:128
	s_add_u32 s48, s48, 0x8000
	s_addc_u32 s49, s49, 0
	global_load_dword v142, v162, s[48:49]
	global_load_dword v224, v162, s[48:49] offset:128
	global_load_dword v143, v163, s[48:49]
	global_load_dword v225, v163, s[48:49] offset:128
	global_load_dword v144, v164, s[48:49]
	global_load_dword v226, v164, s[48:49] offset:128
	global_load_dword v145, v165, s[48:49]
	global_load_dword v227, v165, s[48:49] offset:128
	s_sub_u32 s48, s48, 0x18000
	s_subb_u32 s49, s49, 0
	s_waitcnt vmcnt(30)
	v_fmac_f32_e32 v130, v34, v175
	v_fmac_f32_e32 v212, v50, v176
	global_store_dword v162, v130, s[48:49]
	global_store_dword v162, v212, s[48:49] offset:128
	s_waitcnt vmcnt(30)
	v_fmac_f32_e32 v131, v35, v175
	v_fmac_f32_e32 v213, v51, v176
	global_store_dword v163, v131, s[48:49]
	global_store_dword v163, v213, s[48:49] offset:128
	s_waitcnt vmcnt(30)
	v_fmac_f32_e32 v132, v36, v175
	v_fmac_f32_e32 v214, v52, v176
	global_store_dword v164, v132, s[48:49]
	global_store_dword v164, v214, s[48:49] offset:128
	s_waitcnt vmcnt(30)
	v_fmac_f32_e32 v133, v37, v175
	v_fmac_f32_e32 v215, v53, v176
	global_store_dword v165, v133, s[48:49]
	global_store_dword v165, v215, s[48:49] offset:128
	s_add_u32 s48, s48, 0x8000
	s_addc_u32 s49, s49, 0
	s_waitcnt vmcnt(30)
	v_fmac_f32_e32 v134, v38, v175
	v_fmac_f32_e32 v216, v54, v176
	global_store_dword v162, v134, s[48:49]
	global_store_dword v162, v216, s[48:49] offset:128
	s_waitcnt vmcnt(30)
	v_fmac_f32_e32 v135, v39, v175
	v_fmac_f32_e32 v217, v55, v176
	global_store_dword v163, v135, s[48:49]
	global_store_dword v163, v217, s[48:49] offset:128
	s_waitcnt vmcnt(30)
	v_fmac_f32_e32 v136, v40, v175
	v_fmac_f32_e32 v218, v56, v176
	global_store_dword v164, v136, s[48:49]
	global_store_dword v164, v218, s[48:49] offset:128
	s_waitcnt vmcnt(30)
	v_fmac_f32_e32 v137, v41, v175
	v_fmac_f32_e32 v219, v57, v176
	global_store_dword v165, v137, s[48:49]
	global_store_dword v165, v219, s[48:49] offset:128
	s_add_u32 s48, s48, 0x8000
	s_addc_u32 s49, s49, 0
	s_waitcnt vmcnt(30)
	v_fmac_f32_e32 v138, v42, v175
	v_fmac_f32_e32 v220, v58, v176
	global_store_dword v162, v138, s[48:49]
	global_store_dword v162, v220, s[48:49] offset:128
	s_waitcnt vmcnt(30)
	v_fmac_f32_e32 v139, v43, v175
	v_fmac_f32_e32 v221, v59, v176
	global_store_dword v163, v139, s[48:49]
	global_store_dword v163, v221, s[48:49] offset:128
	s_waitcnt vmcnt(30)
	v_fmac_f32_e32 v140, v44, v175
	v_fmac_f32_e32 v222, v60, v176
	global_store_dword v164, v140, s[48:49]
	global_store_dword v164, v222, s[48:49] offset:128
	s_waitcnt vmcnt(30)
	v_fmac_f32_e32 v141, v45, v175
	v_fmac_f32_e32 v223, v61, v176
	global_store_dword v165, v141, s[48:49]
	global_store_dword v165, v223, s[48:49] offset:128
	s_add_u32 s48, s48, 0x8000
	s_addc_u32 s49, s49, 0
	s_waitcnt vmcnt(30)
	v_fmac_f32_e32 v142, v46, v175
	v_fmac_f32_e32 v224, v62, v176
	global_store_dword v162, v142, s[48:49]
	global_store_dword v162, v224, s[48:49] offset:128
	s_waitcnt vmcnt(30)
	v_fmac_f32_e32 v143, v47, v175
	v_fmac_f32_e32 v225, v63, v176
	global_store_dword v163, v143, s[48:49]
	global_store_dword v163, v225, s[48:49] offset:128
	s_waitcnt vmcnt(30)
	v_fmac_f32_e32 v144, v48, v175
	v_fmac_f32_e32 v226, v64, v176
	global_store_dword v164, v144, s[48:49]
	global_store_dword v164, v226, s[48:49] offset:128
	s_waitcnt vmcnt(30)
	v_fmac_f32_e32 v145, v49, v175
	v_fmac_f32_e32 v227, v65, v176
	global_store_dword v165, v145, s[48:49]
	global_store_dword v165, v227, s[48:49] offset:128
	s_sub_u32 s48, s48, 0x18000
	s_subb_u32 s49, s49, 0
	v_mul_f32_e32 v130, v130, v130
	v_fmac_f32_e32 v130, v212, v212
	v_mul_f32_e32 v131, v131, v131
	v_fmac_f32_e32 v131, v213, v213
	v_mul_f32_e32 v132, v132, v132
	v_fmac_f32_e32 v132, v214, v214
	v_mul_f32_e32 v133, v133, v133
	v_fmac_f32_e32 v133, v215, v215
	v_mul_f32_e32 v134, v134, v134
	v_fmac_f32_e32 v134, v216, v216
	v_mul_f32_e32 v135, v135, v135
	v_fmac_f32_e32 v135, v217, v217
	v_mul_f32_e32 v136, v136, v136
	v_fmac_f32_e32 v136, v218, v218
	v_mul_f32_e32 v137, v137, v137
	v_fmac_f32_e32 v137, v219, v219
	v_mul_f32_e32 v138, v138, v138
	v_fmac_f32_e32 v138, v220, v220
	v_mul_f32_e32 v139, v139, v139
	v_fmac_f32_e32 v139, v221, v221
	v_mul_f32_e32 v140, v140, v140
	v_fmac_f32_e32 v140, v222, v222
	v_mul_f32_e32 v141, v141, v141
	v_fmac_f32_e32 v141, v223, v223
	v_mul_f32_e32 v142, v142, v142
	v_fmac_f32_e32 v142, v224, v224
	v_mul_f32_e32 v143, v143, v143
	v_fmac_f32_e32 v143, v225, v225
	v_mul_f32_e32 v144, v144, v144
	v_fmac_f32_e32 v144, v226, v226
	v_mul_f32_e32 v145, v145, v145
	v_fmac_f32_e32 v145, v227, v227
	s_waitcnt lgkmcnt(0)
	ds_bpermute_b32 v212, v168, v130
	ds_bpermute_b32 v213, v168, v131
	ds_bpermute_b32 v214, v168, v132
	ds_bpermute_b32 v215, v168, v133
	ds_bpermute_b32 v216, v168, v134
	ds_bpermute_b32 v217, v168, v135
	ds_bpermute_b32 v218, v168, v136
	ds_bpermute_b32 v219, v168, v137
	s_waitcnt lgkmcnt(7)
	v_add_f32_e32 v130, v130, v212
	s_waitcnt lgkmcnt(6)
	v_add_f32_e32 v131, v131, v213
	s_waitcnt lgkmcnt(5)
	v_add_f32_e32 v132, v132, v214
	s_waitcnt lgkmcnt(4)
	v_add_f32_e32 v133, v133, v215
	s_waitcnt lgkmcnt(3)
	v_add_f32_e32 v134, v134, v216
	s_waitcnt lgkmcnt(2)
	v_add_f32_e32 v135, v135, v217
	s_waitcnt lgkmcnt(1)
	v_add_f32_e32 v136, v136, v218
	s_waitcnt lgkmcnt(0)
	v_add_f32_e32 v137, v137, v219
	ds_bpermute_b32 v212, v169, v130
	ds_bpermute_b32 v213, v169, v131
	ds_bpermute_b32 v214, v169, v132
	ds_bpermute_b32 v215, v169, v133
	ds_bpermute_b32 v216, v169, v134
	ds_bpermute_b32 v217, v169, v135
	ds_bpermute_b32 v218, v169, v136
	ds_bpermute_b32 v219, v169, v137
	s_waitcnt lgkmcnt(7)
	v_add_f32_e32 v130, v130, v212
	s_waitcnt lgkmcnt(6)
	v_add_f32_e32 v131, v131, v213
	s_waitcnt lgkmcnt(5)
	v_add_f32_e32 v132, v132, v214
	s_waitcnt lgkmcnt(4)
	v_add_f32_e32 v133, v133, v215
	s_waitcnt lgkmcnt(3)
	v_add_f32_e32 v134, v134, v216
	s_waitcnt lgkmcnt(2)
	v_add_f32_e32 v135, v135, v217
	s_waitcnt lgkmcnt(1)
	v_add_f32_e32 v136, v136, v218
	s_waitcnt lgkmcnt(0)
	v_add_f32_e32 v137, v137, v219
	ds_bpermute_b32 v212, v171, v130
	ds_bpermute_b32 v213, v171, v131
	ds_bpermute_b32 v214, v171, v132
	ds_bpermute_b32 v215, v171, v133
	ds_bpermute_b32 v216, v171, v134
	ds_bpermute_b32 v217, v171, v135
	ds_bpermute_b32 v218, v171, v136
	ds_bpermute_b32 v219, v171, v137
	s_waitcnt lgkmcnt(7)
	v_add_f32_e32 v130, v130, v212
	s_waitcnt lgkmcnt(6)
	v_add_f32_e32 v131, v131, v213
	s_waitcnt lgkmcnt(5)
	v_add_f32_e32 v132, v132, v214
	s_waitcnt lgkmcnt(4)
	v_add_f32_e32 v133, v133, v215
	s_waitcnt lgkmcnt(3)
	v_add_f32_e32 v134, v134, v216
	s_waitcnt lgkmcnt(2)
	v_add_f32_e32 v135, v135, v217
	s_waitcnt lgkmcnt(1)
	v_add_f32_e32 v136, v136, v218
	s_waitcnt lgkmcnt(0)
	v_add_f32_e32 v137, v137, v219
	ds_bpermute_b32 v212, v172, v130
	ds_bpermute_b32 v213, v172, v131
	ds_bpermute_b32 v214, v172, v132
	ds_bpermute_b32 v215, v172, v133
	ds_bpermute_b32 v216, v172, v134
	ds_bpermute_b32 v217, v172, v135
	ds_bpermute_b32 v218, v172, v136
	ds_bpermute_b32 v219, v172, v137
	s_waitcnt lgkmcnt(7)
	v_add_f32_e32 v130, v130, v212
	s_waitcnt lgkmcnt(6)
	v_add_f32_e32 v131, v131, v213
	s_waitcnt lgkmcnt(5)
	v_add_f32_e32 v132, v132, v214
	s_waitcnt lgkmcnt(4)
	v_add_f32_e32 v133, v133, v215
	s_waitcnt lgkmcnt(3)
	v_add_f32_e32 v134, v134, v216
	s_waitcnt lgkmcnt(2)
	v_add_f32_e32 v135, v135, v217
	s_waitcnt lgkmcnt(1)
	v_add_f32_e32 v136, v136, v218
	s_waitcnt lgkmcnt(0)
	v_add_f32_e32 v137, v137, v219
	ds_bpermute_b32 v212, v173, v130
	ds_bpermute_b32 v213, v173, v131
	ds_bpermute_b32 v214, v173, v132
	ds_bpermute_b32 v215, v173, v133
	ds_bpermute_b32 v216, v173, v134
	ds_bpermute_b32 v217, v173, v135
	ds_bpermute_b32 v218, v173, v136
	ds_bpermute_b32 v219, v173, v137
	s_waitcnt lgkmcnt(7)
	v_add_f32_e32 v130, v130, v212
	s_waitcnt lgkmcnt(6)
	v_add_f32_e32 v131, v131, v213
	s_waitcnt lgkmcnt(5)
	v_add_f32_e32 v132, v132, v214
	s_waitcnt lgkmcnt(4)
	v_add_f32_e32 v133, v133, v215
	s_waitcnt lgkmcnt(3)
	v_add_f32_e32 v134, v134, v216
	s_waitcnt lgkmcnt(2)
	v_add_f32_e32 v135, v135, v217
	s_waitcnt lgkmcnt(1)
	v_add_f32_e32 v136, v136, v218
	s_waitcnt lgkmcnt(0)
	v_add_f32_e32 v137, v137, v219
	ds_bpermute_b32 v220, v168, v138
	ds_bpermute_b32 v221, v168, v139
	ds_bpermute_b32 v222, v168, v140
	ds_bpermute_b32 v223, v168, v141
	ds_bpermute_b32 v224, v168, v142
	ds_bpermute_b32 v225, v168, v143
	ds_bpermute_b32 v226, v168, v144
	ds_bpermute_b32 v227, v168, v145
	s_waitcnt lgkmcnt(7)
	v_add_f32_e32 v138, v138, v220
	s_waitcnt lgkmcnt(6)
	v_add_f32_e32 v139, v139, v221
	s_waitcnt lgkmcnt(5)
	v_add_f32_e32 v140, v140, v222
	s_waitcnt lgkmcnt(4)
	v_add_f32_e32 v141, v141, v223
	s_waitcnt lgkmcnt(3)
	v_add_f32_e32 v142, v142, v224
	s_waitcnt lgkmcnt(2)
	v_add_f32_e32 v143, v143, v225
	s_waitcnt lgkmcnt(1)
	v_add_f32_e32 v144, v144, v226
	s_waitcnt lgkmcnt(0)
	v_add_f32_e32 v145, v145, v227
	ds_bpermute_b32 v220, v169, v138
	ds_bpermute_b32 v221, v169, v139
	ds_bpermute_b32 v222, v169, v140
	ds_bpermute_b32 v223, v169, v141
	ds_bpermute_b32 v224, v169, v142
	ds_bpermute_b32 v225, v169, v143
	ds_bpermute_b32 v226, v169, v144
	ds_bpermute_b32 v227, v169, v145
	s_waitcnt lgkmcnt(7)
	v_add_f32_e32 v138, v138, v220
	s_waitcnt lgkmcnt(6)
	v_add_f32_e32 v139, v139, v221
	s_waitcnt lgkmcnt(5)
	v_add_f32_e32 v140, v140, v222
	s_waitcnt lgkmcnt(4)
	v_add_f32_e32 v141, v141, v223
	s_waitcnt lgkmcnt(3)
	v_add_f32_e32 v142, v142, v224
	s_waitcnt lgkmcnt(2)
	v_add_f32_e32 v143, v143, v225
	s_waitcnt lgkmcnt(1)
	v_add_f32_e32 v144, v144, v226
	s_waitcnt lgkmcnt(0)
	v_add_f32_e32 v145, v145, v227
	ds_bpermute_b32 v220, v171, v138
	ds_bpermute_b32 v221, v171, v139
	ds_bpermute_b32 v222, v171, v140
	ds_bpermute_b32 v223, v171, v141
	ds_bpermute_b32 v224, v171, v142
	ds_bpermute_b32 v225, v171, v143
	ds_bpermute_b32 v226, v171, v144
	ds_bpermute_b32 v227, v171, v145
	s_waitcnt lgkmcnt(7)
	v_add_f32_e32 v138, v138, v220
	s_waitcnt lgkmcnt(6)
	v_add_f32_e32 v139, v139, v221
	s_waitcnt lgkmcnt(5)
	v_add_f32_e32 v140, v140, v222
	s_waitcnt lgkmcnt(4)
	v_add_f32_e32 v141, v141, v223
	s_waitcnt lgkmcnt(3)
	v_add_f32_e32 v142, v142, v224
	s_waitcnt lgkmcnt(2)
	v_add_f32_e32 v143, v143, v225
	s_waitcnt lgkmcnt(1)
	v_add_f32_e32 v144, v144, v226
	s_waitcnt lgkmcnt(0)
	v_add_f32_e32 v145, v145, v227
	ds_bpermute_b32 v220, v172, v138
	ds_bpermute_b32 v221, v172, v139
	ds_bpermute_b32 v222, v172, v140
	ds_bpermute_b32 v223, v172, v141
	ds_bpermute_b32 v224, v172, v142
	ds_bpermute_b32 v225, v172, v143
	ds_bpermute_b32 v226, v172, v144
	ds_bpermute_b32 v227, v172, v145
	s_waitcnt lgkmcnt(7)
	v_add_f32_e32 v138, v138, v220
	s_waitcnt lgkmcnt(6)
	v_add_f32_e32 v139, v139, v221
	s_waitcnt lgkmcnt(5)
	v_add_f32_e32 v140, v140, v222
	s_waitcnt lgkmcnt(4)
	v_add_f32_e32 v141, v141, v223
	s_waitcnt lgkmcnt(3)
	v_add_f32_e32 v142, v142, v224
	s_waitcnt lgkmcnt(2)
	v_add_f32_e32 v143, v143, v225
	s_waitcnt lgkmcnt(1)
	v_add_f32_e32 v144, v144, v226
	s_waitcnt lgkmcnt(0)
	v_add_f32_e32 v145, v145, v227
	ds_bpermute_b32 v220, v173, v138
	ds_bpermute_b32 v221, v173, v139
	ds_bpermute_b32 v222, v173, v140
	ds_bpermute_b32 v223, v173, v141
	ds_bpermute_b32 v224, v173, v142
	ds_bpermute_b32 v225, v173, v143
	ds_bpermute_b32 v226, v173, v144
	ds_bpermute_b32 v227, v173, v145
	s_waitcnt lgkmcnt(7)
	v_add_f32_e32 v138, v138, v220
	s_waitcnt lgkmcnt(6)
	v_add_f32_e32 v139, v139, v221
	s_waitcnt lgkmcnt(5)
	v_add_f32_e32 v140, v140, v222
	s_waitcnt lgkmcnt(4)
	v_add_f32_e32 v141, v141, v223
	s_waitcnt lgkmcnt(3)
	v_add_f32_e32 v142, v142, v224
	s_waitcnt lgkmcnt(2)
	v_add_f32_e32 v143, v143, v225
	s_waitcnt lgkmcnt(1)
	v_add_f32_e32 v144, v144, v226
	s_waitcnt lgkmcnt(0)
	v_add_f32_e32 v145, v145, v227
	v_cmp_eq_u32_e32 vcc, 0, v174
	s_and_saveexec_b64 s[58:59], vcc
	global_store_dword v167, v130, s[10:11] offset:128
	global_store_dword v167, v131, s[10:11] offset:132
	global_store_dword v167, v132, s[10:11] offset:136
	global_store_dword v167, v133, s[10:11] offset:140
	global_store_dword v167, v134, s[10:11] offset:160
	global_store_dword v167, v135, s[10:11] offset:164
	global_store_dword v167, v136, s[10:11] offset:168
	global_store_dword v167, v137, s[10:11] offset:172
	global_store_dword v167, v138, s[10:11] offset:192
	global_store_dword v167, v139, s[10:11] offset:196
	global_store_dword v167, v140, s[10:11] offset:200
	global_store_dword v167, v141, s[10:11] offset:204
	global_store_dword v167, v142, s[10:11] offset:224
	global_store_dword v167, v143, s[10:11] offset:228
	global_store_dword v167, v144, s[10:11] offset:232
	global_store_dword v167, v145, s[10:11] offset:236
	s_mov_b64 exec, -1
	s_sub_u32 s48, s48, 0x20000
	s_subb_u32 s49, s49, 0
	s_add_u32 s60, s60, 0x200
	s_addc_u32 s61, s61, 0
	s_add_u32 s10, s10, 0x18000
	s_addc_u32 s11, s11, 0
	s_add_u32 s48, s48, 0x200
	s_addc_u32 s49, s49, 0
	global_load_dword v175, v166, s[60:61]
	global_load_dword v176, v166, s[60:61] offset:128
	global_load_dword v130, v162, s[48:49]
	global_load_dword v212, v162, s[48:49] offset:128
	global_load_dword v131, v163, s[48:49]
	global_load_dword v213, v163, s[48:49] offset:128
	global_load_dword v132, v164, s[48:49]
	global_load_dword v214, v164, s[48:49] offset:128
	global_load_dword v133, v165, s[48:49]
	global_load_dword v215, v165, s[48:49] offset:128
	s_add_u32 s48, s48, 0x8000
	s_addc_u32 s49, s49, 0
	global_load_dword v134, v162, s[48:49]
	global_load_dword v216, v162, s[48:49] offset:128
	global_load_dword v135, v163, s[48:49]
	global_load_dword v217, v163, s[48:49] offset:128
	global_load_dword v136, v164, s[48:49]
	global_load_dword v218, v164, s[48:49] offset:128
	global_load_dword v137, v165, s[48:49]
	global_load_dword v219, v165, s[48:49] offset:128
	s_add_u32 s48, s48, 0x8000
	s_addc_u32 s49, s49, 0
	global_load_dword v138, v162, s[48:49]
	global_load_dword v220, v162, s[48:49] offset:128
	global_load_dword v139, v163, s[48:49]
	global_load_dword v221, v163, s[48:49] offset:128
	global_load_dword v140, v164, s[48:49]
	global_load_dword v222, v164, s[48:49] offset:128
	global_load_dword v141, v165, s[48:49]
	global_load_dword v223, v165, s[48:49] offset:128
	s_add_u32 s48, s48, 0x8000
	s_addc_u32 s49, s49, 0
	global_load_dword v142, v162, s[48:49]
	global_load_dword v224, v162, s[48:49] offset:128
	global_load_dword v143, v163, s[48:49]
	global_load_dword v225, v163, s[48:49] offset:128
	global_load_dword v144, v164, s[48:49]
	global_load_dword v226, v164, s[48:49] offset:128
	global_load_dword v145, v165, s[48:49]
	global_load_dword v227, v165, s[48:49] offset:128
	s_sub_u32 s48, s48, 0x18000
	s_subb_u32 s49, s49, 0
	s_waitcnt vmcnt(32)
	s_waitcnt vmcnt(30)
	v_fmac_f32_e32 v130, v66, v175
	v_fmac_f32_e32 v212, v82, v176
	global_store_dword v162, v130, s[48:49]
	global_store_dword v162, v212, s[48:49] offset:128
	s_waitcnt vmcnt(30)
	v_fmac_f32_e32 v131, v67, v175
	v_fmac_f32_e32 v213, v83, v176
	global_store_dword v163, v131, s[48:49]
	global_store_dword v163, v213, s[48:49] offset:128
	s_waitcnt vmcnt(30)
	v_fmac_f32_e32 v132, v68, v175
	v_fmac_f32_e32 v214, v84, v176
	global_store_dword v164, v132, s[48:49]
	global_store_dword v164, v214, s[48:49] offset:128
	s_waitcnt vmcnt(30)
	v_fmac_f32_e32 v133, v69, v175
	v_fmac_f32_e32 v215, v85, v176
	global_store_dword v165, v133, s[48:49]
	global_store_dword v165, v215, s[48:49] offset:128
	s_add_u32 s48, s48, 0x8000
	s_addc_u32 s49, s49, 0
	s_waitcnt vmcnt(30)
	v_fmac_f32_e32 v134, v70, v175
	v_fmac_f32_e32 v216, v86, v176
	global_store_dword v162, v134, s[48:49]
	global_store_dword v162, v216, s[48:49] offset:128
	s_waitcnt vmcnt(30)
	v_fmac_f32_e32 v135, v71, v175
	v_fmac_f32_e32 v217, v87, v176
	global_store_dword v163, v135, s[48:49]
	global_store_dword v163, v217, s[48:49] offset:128
	s_waitcnt vmcnt(30)
	v_fmac_f32_e32 v136, v72, v175
	v_fmac_f32_e32 v218, v88, v176
	global_store_dword v164, v136, s[48:49]
	global_store_dword v164, v218, s[48:49] offset:128
	s_waitcnt vmcnt(30)
	v_fmac_f32_e32 v137, v73, v175
	v_fmac_f32_e32 v219, v89, v176
	global_store_dword v165, v137, s[48:49]
	global_store_dword v165, v219, s[48:49] offset:128
	s_add_u32 s48, s48, 0x8000
	s_addc_u32 s49, s49, 0
	s_waitcnt vmcnt(30)
	v_fmac_f32_e32 v138, v74, v175
	v_fmac_f32_e32 v220, v90, v176
	global_store_dword v162, v138, s[48:49]
	global_store_dword v162, v220, s[48:49] offset:128
	s_waitcnt vmcnt(30)
	v_fmac_f32_e32 v139, v75, v175
	v_fmac_f32_e32 v221, v91, v176
	global_store_dword v163, v139, s[48:49]
	global_store_dword v163, v221, s[48:49] offset:128
	s_waitcnt vmcnt(30)
	v_fmac_f32_e32 v140, v76, v175
	v_fmac_f32_e32 v222, v92, v176
	global_store_dword v164, v140, s[48:49]
	global_store_dword v164, v222, s[48:49] offset:128
	s_waitcnt vmcnt(30)
	v_fmac_f32_e32 v141, v77, v175
	v_fmac_f32_e32 v223, v93, v176
	global_store_dword v165, v141, s[48:49]
	global_store_dword v165, v223, s[48:49] offset:128
	s_add_u32 s48, s48, 0x8000
	s_addc_u32 s49, s49, 0
	s_waitcnt vmcnt(30)
	v_fmac_f32_e32 v142, v78, v175
	v_fmac_f32_e32 v224, v94, v176
	global_store_dword v162, v142, s[48:49]
	global_store_dword v162, v224, s[48:49] offset:128
	s_waitcnt vmcnt(30)
	v_fmac_f32_e32 v143, v79, v175
	v_fmac_f32_e32 v225, v95, v176
	global_store_dword v163, v143, s[48:49]
	global_store_dword v163, v225, s[48:49] offset:128
	s_waitcnt vmcnt(30)
	v_fmac_f32_e32 v144, v80, v175
	v_fmac_f32_e32 v226, v96, v176
	global_store_dword v164, v144, s[48:49]
	global_store_dword v164, v226, s[48:49] offset:128
	s_waitcnt vmcnt(30)
	v_fmac_f32_e32 v145, v81, v175
	v_fmac_f32_e32 v227, v97, v176
	global_store_dword v165, v145, s[48:49]
	global_store_dword v165, v227, s[48:49] offset:128
	s_sub_u32 s48, s48, 0x18000
	s_subb_u32 s49, s49, 0
	v_mul_f32_e32 v130, v130, v130
	v_fmac_f32_e32 v130, v212, v212
	v_mul_f32_e32 v131, v131, v131
	v_fmac_f32_e32 v131, v213, v213
	v_mul_f32_e32 v132, v132, v132
	v_fmac_f32_e32 v132, v214, v214
	v_mul_f32_e32 v133, v133, v133
	v_fmac_f32_e32 v133, v215, v215
	v_mul_f32_e32 v134, v134, v134
	v_fmac_f32_e32 v134, v216, v216
	v_mul_f32_e32 v135, v135, v135
	v_fmac_f32_e32 v135, v217, v217
	v_mul_f32_e32 v136, v136, v136
	v_fmac_f32_e32 v136, v218, v218
	v_mul_f32_e32 v137, v137, v137
	v_fmac_f32_e32 v137, v219, v219
	v_mul_f32_e32 v138, v138, v138
	v_fmac_f32_e32 v138, v220, v220
	v_mul_f32_e32 v139, v139, v139
	v_fmac_f32_e32 v139, v221, v221
	v_mul_f32_e32 v140, v140, v140
	v_fmac_f32_e32 v140, v222, v222
	v_mul_f32_e32 v141, v141, v141
	v_fmac_f32_e32 v141, v223, v223
	v_mul_f32_e32 v142, v142, v142
	v_fmac_f32_e32 v142, v224, v224
	v_mul_f32_e32 v143, v143, v143
	v_fmac_f32_e32 v143, v225, v225
	v_mul_f32_e32 v144, v144, v144
	v_fmac_f32_e32 v144, v226, v226
	v_mul_f32_e32 v145, v145, v145
	v_fmac_f32_e32 v145, v227, v227
	s_waitcnt lgkmcnt(0)
	ds_bpermute_b32 v212, v168, v130
	ds_bpermute_b32 v213, v168, v131
	ds_bpermute_b32 v214, v168, v132
	ds_bpermute_b32 v215, v168, v133
	ds_bpermute_b32 v216, v168, v134
	ds_bpermute_b32 v217, v168, v135
	ds_bpermute_b32 v218, v168, v136
	ds_bpermute_b32 v219, v168, v137
	s_waitcnt lgkmcnt(7)
	v_add_f32_e32 v130, v130, v212
	s_waitcnt lgkmcnt(6)
	v_add_f32_e32 v131, v131, v213
	s_waitcnt lgkmcnt(5)
	v_add_f32_e32 v132, v132, v214
	s_waitcnt lgkmcnt(4)
	v_add_f32_e32 v133, v133, v215
	s_waitcnt lgkmcnt(3)
	v_add_f32_e32 v134, v134, v216
	s_waitcnt lgkmcnt(2)
	v_add_f32_e32 v135, v135, v217
	s_waitcnt lgkmcnt(1)
	v_add_f32_e32 v136, v136, v218
	s_waitcnt lgkmcnt(0)
	v_add_f32_e32 v137, v137, v219
	ds_bpermute_b32 v212, v169, v130
	ds_bpermute_b32 v213, v169, v131
	ds_bpermute_b32 v214, v169, v132
	ds_bpermute_b32 v215, v169, v133
	ds_bpermute_b32 v216, v169, v134
	ds_bpermute_b32 v217, v169, v135
	ds_bpermute_b32 v218, v169, v136
	ds_bpermute_b32 v219, v169, v137
	s_waitcnt lgkmcnt(7)
	v_add_f32_e32 v130, v130, v212
	s_waitcnt lgkmcnt(6)
	v_add_f32_e32 v131, v131, v213
	s_waitcnt lgkmcnt(5)
	v_add_f32_e32 v132, v132, v214
	s_waitcnt lgkmcnt(4)
	v_add_f32_e32 v133, v133, v215
	s_waitcnt lgkmcnt(3)
	v_add_f32_e32 v134, v134, v216
	s_waitcnt lgkmcnt(2)
	v_add_f32_e32 v135, v135, v217
	s_waitcnt lgkmcnt(1)
	v_add_f32_e32 v136, v136, v218
	s_waitcnt lgkmcnt(0)
	v_add_f32_e32 v137, v137, v219
	ds_bpermute_b32 v212, v171, v130
	ds_bpermute_b32 v213, v171, v131
	ds_bpermute_b32 v214, v171, v132
	ds_bpermute_b32 v215, v171, v133
	ds_bpermute_b32 v216, v171, v134
	ds_bpermute_b32 v217, v171, v135
	ds_bpermute_b32 v218, v171, v136
	ds_bpermute_b32 v219, v171, v137
	s_waitcnt lgkmcnt(7)
	v_add_f32_e32 v130, v130, v212
	s_waitcnt lgkmcnt(6)
	v_add_f32_e32 v131, v131, v213
	s_waitcnt lgkmcnt(5)
	v_add_f32_e32 v132, v132, v214
	s_waitcnt lgkmcnt(4)
	v_add_f32_e32 v133, v133, v215
	s_waitcnt lgkmcnt(3)
	v_add_f32_e32 v134, v134, v216
	s_waitcnt lgkmcnt(2)
	v_add_f32_e32 v135, v135, v217
	s_waitcnt lgkmcnt(1)
	v_add_f32_e32 v136, v136, v218
	s_waitcnt lgkmcnt(0)
	v_add_f32_e32 v137, v137, v219
	ds_bpermute_b32 v212, v172, v130
	ds_bpermute_b32 v213, v172, v131
	ds_bpermute_b32 v214, v172, v132
	ds_bpermute_b32 v215, v172, v133
	ds_bpermute_b32 v216, v172, v134
	ds_bpermute_b32 v217, v172, v135
	ds_bpermute_b32 v218, v172, v136
	ds_bpermute_b32 v219, v172, v137
	s_waitcnt lgkmcnt(7)
	v_add_f32_e32 v130, v130, v212
	s_waitcnt lgkmcnt(6)
	v_add_f32_e32 v131, v131, v213
	s_waitcnt lgkmcnt(5)
	v_add_f32_e32 v132, v132, v214
	s_waitcnt lgkmcnt(4)
	v_add_f32_e32 v133, v133, v215
	s_waitcnt lgkmcnt(3)
	v_add_f32_e32 v134, v134, v216
	s_waitcnt lgkmcnt(2)
	v_add_f32_e32 v135, v135, v217
	s_waitcnt lgkmcnt(1)
	v_add_f32_e32 v136, v136, v218
	s_waitcnt lgkmcnt(0)
	v_add_f32_e32 v137, v137, v219
	ds_bpermute_b32 v212, v173, v130
	ds_bpermute_b32 v213, v173, v131
	ds_bpermute_b32 v214, v173, v132
	ds_bpermute_b32 v215, v173, v133
	ds_bpermute_b32 v216, v173, v134
	ds_bpermute_b32 v217, v173, v135
	ds_bpermute_b32 v218, v173, v136
	ds_bpermute_b32 v219, v173, v137
	s_waitcnt lgkmcnt(7)
	v_add_f32_e32 v130, v130, v212
	s_waitcnt lgkmcnt(6)
	v_add_f32_e32 v131, v131, v213
	s_waitcnt lgkmcnt(5)
	v_add_f32_e32 v132, v132, v214
	s_waitcnt lgkmcnt(4)
	v_add_f32_e32 v133, v133, v215
	s_waitcnt lgkmcnt(3)
	v_add_f32_e32 v134, v134, v216
	s_waitcnt lgkmcnt(2)
	v_add_f32_e32 v135, v135, v217
	s_waitcnt lgkmcnt(1)
	v_add_f32_e32 v136, v136, v218
	s_waitcnt lgkmcnt(0)
	v_add_f32_e32 v137, v137, v219
	ds_bpermute_b32 v220, v168, v138
	ds_bpermute_b32 v221, v168, v139
	ds_bpermute_b32 v222, v168, v140
	ds_bpermute_b32 v223, v168, v141
	ds_bpermute_b32 v224, v168, v142
	ds_bpermute_b32 v225, v168, v143
	ds_bpermute_b32 v226, v168, v144
	ds_bpermute_b32 v227, v168, v145
	s_waitcnt lgkmcnt(7)
	v_add_f32_e32 v138, v138, v220
	s_waitcnt lgkmcnt(6)
	v_add_f32_e32 v139, v139, v221
	s_waitcnt lgkmcnt(5)
	v_add_f32_e32 v140, v140, v222
	s_waitcnt lgkmcnt(4)
	v_add_f32_e32 v141, v141, v223
	s_waitcnt lgkmcnt(3)
	v_add_f32_e32 v142, v142, v224
	s_waitcnt lgkmcnt(2)
	v_add_f32_e32 v143, v143, v225
	s_waitcnt lgkmcnt(1)
	v_add_f32_e32 v144, v144, v226
	s_waitcnt lgkmcnt(0)
	v_add_f32_e32 v145, v145, v227
	ds_bpermute_b32 v220, v169, v138
	ds_bpermute_b32 v221, v169, v139
	ds_bpermute_b32 v222, v169, v140
	ds_bpermute_b32 v223, v169, v141
	ds_bpermute_b32 v224, v169, v142
	ds_bpermute_b32 v225, v169, v143
	ds_bpermute_b32 v226, v169, v144
	ds_bpermute_b32 v227, v169, v145
	s_waitcnt lgkmcnt(7)
	v_add_f32_e32 v138, v138, v220
	s_waitcnt lgkmcnt(6)
	v_add_f32_e32 v139, v139, v221
	s_waitcnt lgkmcnt(5)
	v_add_f32_e32 v140, v140, v222
	s_waitcnt lgkmcnt(4)
	v_add_f32_e32 v141, v141, v223
	s_waitcnt lgkmcnt(3)
	v_add_f32_e32 v142, v142, v224
	s_waitcnt lgkmcnt(2)
	v_add_f32_e32 v143, v143, v225
	s_waitcnt lgkmcnt(1)
	v_add_f32_e32 v144, v144, v226
	s_waitcnt lgkmcnt(0)
	v_add_f32_e32 v145, v145, v227
	ds_bpermute_b32 v220, v171, v138
	ds_bpermute_b32 v221, v171, v139
	ds_bpermute_b32 v222, v171, v140
	ds_bpermute_b32 v223, v171, v141
	ds_bpermute_b32 v224, v171, v142
	ds_bpermute_b32 v225, v171, v143
	ds_bpermute_b32 v226, v171, v144
	ds_bpermute_b32 v227, v171, v145
	s_waitcnt lgkmcnt(7)
	v_add_f32_e32 v138, v138, v220
	s_waitcnt lgkmcnt(6)
	v_add_f32_e32 v139, v139, v221
	s_waitcnt lgkmcnt(5)
	v_add_f32_e32 v140, v140, v222
	s_waitcnt lgkmcnt(4)
	v_add_f32_e32 v141, v141, v223
	s_waitcnt lgkmcnt(3)
	v_add_f32_e32 v142, v142, v224
	s_waitcnt lgkmcnt(2)
	v_add_f32_e32 v143, v143, v225
	s_waitcnt lgkmcnt(1)
	v_add_f32_e32 v144, v144, v226
	s_waitcnt lgkmcnt(0)
	v_add_f32_e32 v145, v145, v227
	ds_bpermute_b32 v220, v172, v138
	ds_bpermute_b32 v221, v172, v139
	ds_bpermute_b32 v222, v172, v140
	ds_bpermute_b32 v223, v172, v141
	ds_bpermute_b32 v224, v172, v142
	ds_bpermute_b32 v225, v172, v143
	ds_bpermute_b32 v226, v172, v144
	ds_bpermute_b32 v227, v172, v145
	s_waitcnt lgkmcnt(7)
	v_add_f32_e32 v138, v138, v220
	s_waitcnt lgkmcnt(6)
	v_add_f32_e32 v139, v139, v221
	s_waitcnt lgkmcnt(5)
	v_add_f32_e32 v140, v140, v222
	s_waitcnt lgkmcnt(4)
	v_add_f32_e32 v141, v141, v223
	s_waitcnt lgkmcnt(3)
	v_add_f32_e32 v142, v142, v224
	s_waitcnt lgkmcnt(2)
	v_add_f32_e32 v143, v143, v225
	s_waitcnt lgkmcnt(1)
	v_add_f32_e32 v144, v144, v226
	s_waitcnt lgkmcnt(0)
	v_add_f32_e32 v145, v145, v227
	ds_bpermute_b32 v220, v173, v138
	ds_bpermute_b32 v221, v173, v139
	ds_bpermute_b32 v222, v173, v140
	ds_bpermute_b32 v223, v173, v141
	ds_bpermute_b32 v224, v173, v142
	ds_bpermute_b32 v225, v173, v143
	ds_bpermute_b32 v226, v173, v144
	ds_bpermute_b32 v227, v173, v145
	s_waitcnt lgkmcnt(7)
	v_add_f32_e32 v138, v138, v220
	s_waitcnt lgkmcnt(6)
	v_add_f32_e32 v139, v139, v221
	s_waitcnt lgkmcnt(5)
	v_add_f32_e32 v140, v140, v222
	s_waitcnt lgkmcnt(4)
	v_add_f32_e32 v141, v141, v223
	s_waitcnt lgkmcnt(3)
	v_add_f32_e32 v142, v142, v224
	s_waitcnt lgkmcnt(2)
	v_add_f32_e32 v143, v143, v225
	s_waitcnt lgkmcnt(1)
	v_add_f32_e32 v144, v144, v226
	s_waitcnt lgkmcnt(0)
	v_add_f32_e32 v145, v145, v227
	v_cmp_eq_u32_e32 vcc, 0, v174
	s_and_saveexec_b64 s[58:59], vcc
	global_store_dword v167, v130, s[10:11]
	global_store_dword v167, v131, s[10:11] offset:4
	global_store_dword v167, v132, s[10:11] offset:8
	global_store_dword v167, v133, s[10:11] offset:12
	global_store_dword v167, v134, s[10:11] offset:32
	global_store_dword v167, v135, s[10:11] offset:36
	global_store_dword v167, v136, s[10:11] offset:40
	global_store_dword v167, v137, s[10:11] offset:44
	global_store_dword v167, v138, s[10:11] offset:64
	global_store_dword v167, v139, s[10:11] offset:68
	global_store_dword v167, v140, s[10:11] offset:72
	global_store_dword v167, v141, s[10:11] offset:76
	global_store_dword v167, v142, s[10:11] offset:96
	global_store_dword v167, v143, s[10:11] offset:100
	global_store_dword v167, v144, s[10:11] offset:104
	global_store_dword v167, v145, s[10:11] offset:108
	s_mov_b64 exec, -1
	s_add_u32 s48, s48, 0x20000
	s_addc_u32 s49, s49, 0
	global_load_dword v130, v162, s[48:49]
	global_load_dword v212, v162, s[48:49] offset:128
	global_load_dword v131, v163, s[48:49]
	global_load_dword v213, v163, s[48:49] offset:128
	global_load_dword v132, v164, s[48:49]
	global_load_dword v214, v164, s[48:49] offset:128
	global_load_dword v133, v165, s[48:49]
	global_load_dword v215, v165, s[48:49] offset:128
	s_add_u32 s48, s48, 0x8000
	s_addc_u32 s49, s49, 0
	global_load_dword v134, v162, s[48:49]
	global_load_dword v216, v162, s[48:49] offset:128
	global_load_dword v135, v163, s[48:49]
	global_load_dword v217, v163, s[48:49] offset:128
	global_load_dword v136, v164, s[48:49]
	global_load_dword v218, v164, s[48:49] offset:128
	global_load_dword v137, v165, s[48:49]
	global_load_dword v219, v165, s[48:49] offset:128
	s_add_u32 s48, s48, 0x8000
	s_addc_u32 s49, s49, 0
	global_load_dword v138, v162, s[48:49]
	global_load_dword v220, v162, s[48:49] offset:128
	global_load_dword v139, v163, s[48:49]
	global_load_dword v221, v163, s[48:49] offset:128
	global_load_dword v140, v164, s[48:49]
	global_load_dword v222, v164, s[48:49] offset:128
	global_load_dword v141, v165, s[48:49]
	global_load_dword v223, v165, s[48:49] offset:128
	s_add_u32 s48, s48, 0x8000
	s_addc_u32 s49, s49, 0
	global_load_dword v142, v162, s[48:49]
	global_load_dword v224, v162, s[48:49] offset:128
	global_load_dword v143, v163, s[48:49]
	global_load_dword v225, v163, s[48:49] offset:128
	global_load_dword v144, v164, s[48:49]
	global_load_dword v226, v164, s[48:49] offset:128
	global_load_dword v145, v165, s[48:49]
	global_load_dword v227, v165, s[48:49] offset:128
	s_sub_u32 s48, s48, 0x18000
	s_subb_u32 s49, s49, 0
	s_waitcnt vmcnt(30)
	v_fmac_f32_e32 v130, v98, v175
	v_fmac_f32_e32 v212, v114, v176
	global_store_dword v162, v130, s[48:49]
	global_store_dword v162, v212, s[48:49] offset:128
	s_waitcnt vmcnt(30)
	v_fmac_f32_e32 v131, v99, v175
	v_fmac_f32_e32 v213, v115, v176
	global_store_dword v163, v131, s[48:49]
	global_store_dword v163, v213, s[48:49] offset:128
	s_waitcnt vmcnt(30)
	v_fmac_f32_e32 v132, v100, v175
	v_fmac_f32_e32 v214, v116, v176
	global_store_dword v164, v132, s[48:49]
	global_store_dword v164, v214, s[48:49] offset:128
	s_waitcnt vmcnt(30)
	v_fmac_f32_e32 v133, v101, v175
	v_fmac_f32_e32 v215, v117, v176
	global_store_dword v165, v133, s[48:49]
	global_store_dword v165, v215, s[48:49] offset:128
	s_add_u32 s48, s48, 0x8000
	s_addc_u32 s49, s49, 0
	s_waitcnt vmcnt(30)
	v_fmac_f32_e32 v134, v102, v175
	v_fmac_f32_e32 v216, v118, v176
	global_store_dword v162, v134, s[48:49]
	global_store_dword v162, v216, s[48:49] offset:128
	s_waitcnt vmcnt(30)
	v_fmac_f32_e32 v135, v103, v175
	v_fmac_f32_e32 v217, v119, v176
	global_store_dword v163, v135, s[48:49]
	global_store_dword v163, v217, s[48:49] offset:128
	s_waitcnt vmcnt(30)
	v_fmac_f32_e32 v136, v104, v175
	v_fmac_f32_e32 v218, v120, v176
	global_store_dword v164, v136, s[48:49]
	global_store_dword v164, v218, s[48:49] offset:128
	s_waitcnt vmcnt(30)
	v_fmac_f32_e32 v137, v105, v175
	v_fmac_f32_e32 v219, v121, v176
	global_store_dword v165, v137, s[48:49]
	global_store_dword v165, v219, s[48:49] offset:128
	s_add_u32 s48, s48, 0x8000
	s_addc_u32 s49, s49, 0
	s_waitcnt vmcnt(30)
	v_fmac_f32_e32 v138, v106, v175
	v_fmac_f32_e32 v220, v122, v176
	global_store_dword v162, v138, s[48:49]
	global_store_dword v162, v220, s[48:49] offset:128
	s_waitcnt vmcnt(30)
	v_fmac_f32_e32 v139, v107, v175
	v_fmac_f32_e32 v221, v123, v176
	global_store_dword v163, v139, s[48:49]
	global_store_dword v163, v221, s[48:49] offset:128
	s_waitcnt vmcnt(30)
	v_fmac_f32_e32 v140, v108, v175
	v_fmac_f32_e32 v222, v124, v176
	global_store_dword v164, v140, s[48:49]
	global_store_dword v164, v222, s[48:49] offset:128
	s_waitcnt vmcnt(30)
	v_fmac_f32_e32 v141, v109, v175
	v_fmac_f32_e32 v223, v125, v176
	global_store_dword v165, v141, s[48:49]
	global_store_dword v165, v223, s[48:49] offset:128
	s_add_u32 s48, s48, 0x8000
	s_addc_u32 s49, s49, 0
	s_waitcnt vmcnt(30)
	v_fmac_f32_e32 v142, v110, v175
	v_fmac_f32_e32 v224, v126, v176
	global_store_dword v162, v142, s[48:49]
	global_store_dword v162, v224, s[48:49] offset:128
	s_waitcnt vmcnt(30)
	v_fmac_f32_e32 v143, v111, v175
	v_fmac_f32_e32 v225, v127, v176
	global_store_dword v163, v143, s[48:49]
	global_store_dword v163, v225, s[48:49] offset:128
	s_waitcnt vmcnt(30)
	v_fmac_f32_e32 v144, v112, v175
	v_fmac_f32_e32 v226, v128, v176
	global_store_dword v164, v144, s[48:49]
	global_store_dword v164, v226, s[48:49] offset:128
	s_waitcnt vmcnt(30)
	v_fmac_f32_e32 v145, v113, v175
	v_fmac_f32_e32 v227, v129, v176
	global_store_dword v165, v145, s[48:49]
	global_store_dword v165, v227, s[48:49] offset:128
	s_sub_u32 s48, s48, 0x18000
	s_subb_u32 s49, s49, 0
	v_mul_f32_e32 v130, v130, v130
	v_fmac_f32_e32 v130, v212, v212
	v_mul_f32_e32 v131, v131, v131
	v_fmac_f32_e32 v131, v213, v213
	v_mul_f32_e32 v132, v132, v132
	v_fmac_f32_e32 v132, v214, v214
	v_mul_f32_e32 v133, v133, v133
	v_fmac_f32_e32 v133, v215, v215
	v_mul_f32_e32 v134, v134, v134
	v_fmac_f32_e32 v134, v216, v216
	v_mul_f32_e32 v135, v135, v135
	v_fmac_f32_e32 v135, v217, v217
	v_mul_f32_e32 v136, v136, v136
	v_fmac_f32_e32 v136, v218, v218
	v_mul_f32_e32 v137, v137, v137
	v_fmac_f32_e32 v137, v219, v219
	v_mul_f32_e32 v138, v138, v138
	v_fmac_f32_e32 v138, v220, v220
	v_mul_f32_e32 v139, v139, v139
	v_fmac_f32_e32 v139, v221, v221
	v_mul_f32_e32 v140, v140, v140
	v_fmac_f32_e32 v140, v222, v222
	v_mul_f32_e32 v141, v141, v141
	v_fmac_f32_e32 v141, v223, v223
	v_mul_f32_e32 v142, v142, v142
	v_fmac_f32_e32 v142, v224, v224
	v_mul_f32_e32 v143, v143, v143
	v_fmac_f32_e32 v143, v225, v225
	v_mul_f32_e32 v144, v144, v144
	v_fmac_f32_e32 v144, v226, v226
	v_mul_f32_e32 v145, v145, v145
	v_fmac_f32_e32 v145, v227, v227
	s_waitcnt lgkmcnt(0)
	ds_bpermute_b32 v212, v168, v130
	ds_bpermute_b32 v213, v168, v131
	ds_bpermute_b32 v214, v168, v132
	ds_bpermute_b32 v215, v168, v133
	ds_bpermute_b32 v216, v168, v134
	ds_bpermute_b32 v217, v168, v135
	ds_bpermute_b32 v218, v168, v136
	ds_bpermute_b32 v219, v168, v137
	s_waitcnt lgkmcnt(7)
	v_add_f32_e32 v130, v130, v212
	s_waitcnt lgkmcnt(6)
	v_add_f32_e32 v131, v131, v213
	s_waitcnt lgkmcnt(5)
	v_add_f32_e32 v132, v132, v214
	s_waitcnt lgkmcnt(4)
	v_add_f32_e32 v133, v133, v215
	s_waitcnt lgkmcnt(3)
	v_add_f32_e32 v134, v134, v216
	s_waitcnt lgkmcnt(2)
	v_add_f32_e32 v135, v135, v217
	s_waitcnt lgkmcnt(1)
	v_add_f32_e32 v136, v136, v218
	s_waitcnt lgkmcnt(0)
	v_add_f32_e32 v137, v137, v219
	ds_bpermute_b32 v212, v169, v130
	ds_bpermute_b32 v213, v169, v131
	ds_bpermute_b32 v214, v169, v132
	ds_bpermute_b32 v215, v169, v133
	ds_bpermute_b32 v216, v169, v134
	ds_bpermute_b32 v217, v169, v135
	ds_bpermute_b32 v218, v169, v136
	ds_bpermute_b32 v219, v169, v137
	s_waitcnt lgkmcnt(7)
	v_add_f32_e32 v130, v130, v212
	s_waitcnt lgkmcnt(6)
	v_add_f32_e32 v131, v131, v213
	s_waitcnt lgkmcnt(5)
	v_add_f32_e32 v132, v132, v214
	s_waitcnt lgkmcnt(4)
	v_add_f32_e32 v133, v133, v215
	s_waitcnt lgkmcnt(3)
	v_add_f32_e32 v134, v134, v216
	s_waitcnt lgkmcnt(2)
	v_add_f32_e32 v135, v135, v217
	s_waitcnt lgkmcnt(1)
	v_add_f32_e32 v136, v136, v218
	s_waitcnt lgkmcnt(0)
	v_add_f32_e32 v137, v137, v219
	ds_bpermute_b32 v212, v171, v130
	ds_bpermute_b32 v213, v171, v131
	ds_bpermute_b32 v214, v171, v132
	ds_bpermute_b32 v215, v171, v133
	ds_bpermute_b32 v216, v171, v134
	ds_bpermute_b32 v217, v171, v135
	ds_bpermute_b32 v218, v171, v136
	ds_bpermute_b32 v219, v171, v137
	s_waitcnt lgkmcnt(7)
	v_add_f32_e32 v130, v130, v212
	s_waitcnt lgkmcnt(6)
	v_add_f32_e32 v131, v131, v213
	s_waitcnt lgkmcnt(5)
	v_add_f32_e32 v132, v132, v214
	s_waitcnt lgkmcnt(4)
	v_add_f32_e32 v133, v133, v215
	s_waitcnt lgkmcnt(3)
	v_add_f32_e32 v134, v134, v216
	s_waitcnt lgkmcnt(2)
	v_add_f32_e32 v135, v135, v217
	s_waitcnt lgkmcnt(1)
	v_add_f32_e32 v136, v136, v218
	s_waitcnt lgkmcnt(0)
	v_add_f32_e32 v137, v137, v219
	ds_bpermute_b32 v212, v172, v130
	ds_bpermute_b32 v213, v172, v131
	ds_bpermute_b32 v214, v172, v132
	ds_bpermute_b32 v215, v172, v133
	ds_bpermute_b32 v216, v172, v134
	ds_bpermute_b32 v217, v172, v135
	ds_bpermute_b32 v218, v172, v136
	ds_bpermute_b32 v219, v172, v137
	s_waitcnt lgkmcnt(7)
	v_add_f32_e32 v130, v130, v212
	s_waitcnt lgkmcnt(6)
	v_add_f32_e32 v131, v131, v213
	s_waitcnt lgkmcnt(5)
	v_add_f32_e32 v132, v132, v214
	s_waitcnt lgkmcnt(4)
	v_add_f32_e32 v133, v133, v215
	s_waitcnt lgkmcnt(3)
	v_add_f32_e32 v134, v134, v216
	s_waitcnt lgkmcnt(2)
	v_add_f32_e32 v135, v135, v217
	s_waitcnt lgkmcnt(1)
	v_add_f32_e32 v136, v136, v218
	s_waitcnt lgkmcnt(0)
	v_add_f32_e32 v137, v137, v219
	ds_bpermute_b32 v212, v173, v130
	ds_bpermute_b32 v213, v173, v131
	ds_bpermute_b32 v214, v173, v132
	ds_bpermute_b32 v215, v173, v133
	ds_bpermute_b32 v216, v173, v134
	ds_bpermute_b32 v217, v173, v135
	ds_bpermute_b32 v218, v173, v136
	ds_bpermute_b32 v219, v173, v137
	s_waitcnt lgkmcnt(7)
	v_add_f32_e32 v130, v130, v212
	s_waitcnt lgkmcnt(6)
	v_add_f32_e32 v131, v131, v213
	s_waitcnt lgkmcnt(5)
	v_add_f32_e32 v132, v132, v214
	s_waitcnt lgkmcnt(4)
	v_add_f32_e32 v133, v133, v215
	s_waitcnt lgkmcnt(3)
	v_add_f32_e32 v134, v134, v216
	s_waitcnt lgkmcnt(2)
	v_add_f32_e32 v135, v135, v217
	s_waitcnt lgkmcnt(1)
	v_add_f32_e32 v136, v136, v218
	s_waitcnt lgkmcnt(0)
	v_add_f32_e32 v137, v137, v219
	ds_bpermute_b32 v220, v168, v138
	ds_bpermute_b32 v221, v168, v139
	ds_bpermute_b32 v222, v168, v140
	ds_bpermute_b32 v223, v168, v141
	ds_bpermute_b32 v224, v168, v142
	ds_bpermute_b32 v225, v168, v143
	ds_bpermute_b32 v226, v168, v144
	ds_bpermute_b32 v227, v168, v145
	s_waitcnt lgkmcnt(7)
	v_add_f32_e32 v138, v138, v220
	s_waitcnt lgkmcnt(6)
	v_add_f32_e32 v139, v139, v221
	s_waitcnt lgkmcnt(5)
	v_add_f32_e32 v140, v140, v222
	s_waitcnt lgkmcnt(4)
	v_add_f32_e32 v141, v141, v223
	s_waitcnt lgkmcnt(3)
	v_add_f32_e32 v142, v142, v224
	s_waitcnt lgkmcnt(2)
	v_add_f32_e32 v143, v143, v225
	s_waitcnt lgkmcnt(1)
	v_add_f32_e32 v144, v144, v226
	s_waitcnt lgkmcnt(0)
	v_add_f32_e32 v145, v145, v227
	ds_bpermute_b32 v220, v169, v138
	ds_bpermute_b32 v221, v169, v139
	ds_bpermute_b32 v222, v169, v140
	ds_bpermute_b32 v223, v169, v141
	ds_bpermute_b32 v224, v169, v142
	ds_bpermute_b32 v225, v169, v143
	ds_bpermute_b32 v226, v169, v144
	ds_bpermute_b32 v227, v169, v145
	s_waitcnt lgkmcnt(7)
	v_add_f32_e32 v138, v138, v220
	s_waitcnt lgkmcnt(6)
	v_add_f32_e32 v139, v139, v221
	s_waitcnt lgkmcnt(5)
	v_add_f32_e32 v140, v140, v222
	s_waitcnt lgkmcnt(4)
	v_add_f32_e32 v141, v141, v223
	s_waitcnt lgkmcnt(3)
	v_add_f32_e32 v142, v142, v224
	s_waitcnt lgkmcnt(2)
	v_add_f32_e32 v143, v143, v225
	s_waitcnt lgkmcnt(1)
	v_add_f32_e32 v144, v144, v226
	s_waitcnt lgkmcnt(0)
	v_add_f32_e32 v145, v145, v227
	ds_bpermute_b32 v220, v171, v138
	ds_bpermute_b32 v221, v171, v139
	ds_bpermute_b32 v222, v171, v140
	ds_bpermute_b32 v223, v171, v141
	ds_bpermute_b32 v224, v171, v142
	ds_bpermute_b32 v225, v171, v143
	ds_bpermute_b32 v226, v171, v144
	ds_bpermute_b32 v227, v171, v145
	s_waitcnt lgkmcnt(7)
	v_add_f32_e32 v138, v138, v220
	s_waitcnt lgkmcnt(6)
	v_add_f32_e32 v139, v139, v221
	s_waitcnt lgkmcnt(5)
	v_add_f32_e32 v140, v140, v222
	s_waitcnt lgkmcnt(4)
	v_add_f32_e32 v141, v141, v223
	s_waitcnt lgkmcnt(3)
	v_add_f32_e32 v142, v142, v224
	s_waitcnt lgkmcnt(2)
	v_add_f32_e32 v143, v143, v225
	s_waitcnt lgkmcnt(1)
	v_add_f32_e32 v144, v144, v226
	s_waitcnt lgkmcnt(0)
	v_add_f32_e32 v145, v145, v227
	ds_bpermute_b32 v220, v172, v138
	ds_bpermute_b32 v221, v172, v139
	ds_bpermute_b32 v222, v172, v140
	ds_bpermute_b32 v223, v172, v141
	ds_bpermute_b32 v224, v172, v142
	ds_bpermute_b32 v225, v172, v143
	ds_bpermute_b32 v226, v172, v144
	ds_bpermute_b32 v227, v172, v145
	s_waitcnt lgkmcnt(7)
	v_add_f32_e32 v138, v138, v220
	s_waitcnt lgkmcnt(6)
	v_add_f32_e32 v139, v139, v221
	s_waitcnt lgkmcnt(5)
	v_add_f32_e32 v140, v140, v222
	s_waitcnt lgkmcnt(4)
	v_add_f32_e32 v141, v141, v223
	s_waitcnt lgkmcnt(3)
	v_add_f32_e32 v142, v142, v224
	s_waitcnt lgkmcnt(2)
	v_add_f32_e32 v143, v143, v225
	s_waitcnt lgkmcnt(1)
	v_add_f32_e32 v144, v144, v226
	s_waitcnt lgkmcnt(0)
	v_add_f32_e32 v145, v145, v227
	ds_bpermute_b32 v220, v173, v138
	ds_bpermute_b32 v221, v173, v139
	ds_bpermute_b32 v222, v173, v140
	ds_bpermute_b32 v223, v173, v141
	ds_bpermute_b32 v224, v173, v142
	ds_bpermute_b32 v225, v173, v143
	ds_bpermute_b32 v226, v173, v144
	ds_bpermute_b32 v227, v173, v145
	s_waitcnt lgkmcnt(7)
	v_add_f32_e32 v138, v138, v220
	s_waitcnt lgkmcnt(6)
	v_add_f32_e32 v139, v139, v221
	s_waitcnt lgkmcnt(5)
	v_add_f32_e32 v140, v140, v222
	s_waitcnt lgkmcnt(4)
	v_add_f32_e32 v141, v141, v223
	s_waitcnt lgkmcnt(3)
	v_add_f32_e32 v142, v142, v224
	s_waitcnt lgkmcnt(2)
	v_add_f32_e32 v143, v143, v225
	s_waitcnt lgkmcnt(1)
	v_add_f32_e32 v144, v144, v226
	s_waitcnt lgkmcnt(0)
	v_add_f32_e32 v145, v145, v227
	v_cmp_eq_u32_e32 vcc, 0, v174
	s_and_saveexec_b64 s[58:59], vcc
	global_store_dword v167, v130, s[10:11] offset:128
	global_store_dword v167, v131, s[10:11] offset:132
	global_store_dword v167, v132, s[10:11] offset:136
	global_store_dword v167, v133, s[10:11] offset:140
	global_store_dword v167, v134, s[10:11] offset:160
	global_store_dword v167, v135, s[10:11] offset:164
	global_store_dword v167, v136, s[10:11] offset:168
	global_store_dword v167, v137, s[10:11] offset:172
	global_store_dword v167, v138, s[10:11] offset:192
	global_store_dword v167, v139, s[10:11] offset:196
	global_store_dword v167, v140, s[10:11] offset:200
	global_store_dword v167, v141, s[10:11] offset:204
	global_store_dword v167, v142, s[10:11] offset:224
	global_store_dword v167, v143, s[10:11] offset:228
	global_store_dword v167, v144, s[10:11] offset:232
	global_store_dword v167, v145, s[10:11] offset:236
	s_mov_b64 exec, -1
	s_sub_u32 s48, s48, 0x20000
	s_subb_u32 s49, s49, 0
	v_readlane_b32 s2, v246, 14
	s_nop 0
	s_add_i32 s16, s16, s2
	s_branch .Lhw_outproj_tloop

.LBB0_2297:
	s_lshl_b32 s58, s88, 1
	v_readlane_b32 s0, v246, 25
	v_readlane_b32 s66, v246, 19
	s_cmp_gt_i32 s0, 1
	s_mov_b64 s[0:1], -1
	s_mov_b32 s59, 0x30000
	s_movk_i32 s62, 0xfff
	s_mov_b32 s63, 0x20000
	s_mov_b32 s64, 0xfffffc0
	s_movk_i32 s65, 0x1ff
	v_readlane_b32 s67, v246, 20
	s_cbranch_scc0 .LBB0_2457
	v_readlane_b32 s0, v246, 26
	v_readlane_b32 s10, v247, 19
	s_cmp_eq_u32 s0, 11
	v_readlane_b32 s11, v247, 20
	s_cselect_b64 s[8:9], -1, 0
	s_mov_b64 s[0:1], s[84:85]
	s_andn2_b64 vcc, exec, s[10:11]
	s_cbranch_vccnz .LBB0_2365
	v_cndmask_b32_e64 v0, 0, 1, s[8:9]
	s_load_dwordx2 s[40:41], s[0:1], 0x108
	v_readfirstlane_b32 s2, v0
	s_or_b32 s2, s58, s2
	s_and_b64 s[10:11], s[8:9], exec
	s_cselect_b32 s10, 3, 1
	v_readlane_b32 s11, v246, 27
	s_cselect_b32 s12, 8, 2
	s_add_i32 s10, s11, s10
	s_waitcnt lgkmcnt(0)
	s_add_u32 s42, s40, 0x3000000
	s_addc_u32 s43, s41, 0
	s_add_u32 s13, s40, 0x7bc0000
	s_addc_u32 s14, s41, 0
	s_mul_hi_i32 s11, s10, 0xc0000
	s_mul_i32 s10, s10, 0xc0000
	s_add_u32 s10, s40, s10
	s_addc_u32 s11, s41, s11
	s_add_u32 s44, s10, 0x7200000
	s_mul_hi_i32 s6, s2, 0x580000
	s_mul_i32 s2, s2, 0x580000
	s_addc_u32 s45, s11, 0
	s_add_u32 s2, s40, s2
	s_addc_u32 s6, s41, s6
	s_add_u32 s46, s2, 0xd478100
	s_addc_u32 s47, s6, 0
	v_readlane_b32 s15, v247, 44
	s_mov_b32 s16, s83
	s_lshl_b32 s2, s12, 12
	s_add_u32 s12, s13, s2
	s_addc_u32 s13, s14, 0
	v_and_b32_e32 v177, 63, v194
	v_lshrrev_b32_e32 v178, 6, v194
	v_lshrrev_b32_e32 v160, 2, v194
	v_mul_u32_u24_e32 v160, 0x1600, v160
	v_and_b32_e32 v179, 3, v177
	v_bfe_u32 v180, v177, 4, 2
	v_xor_b32_e32 v179, v179, v180
	v_lshl_add_u32 v160, v179, 4, v160
	v_add_u32_e32 v161, 0x58000, v160
	v_and_b32_e32 v174, 31, v177
	v_lshrrev_b32_e32 v182, 5, v177
	v_bfe_u32 v183, v174, 2, 2
	v_xor_b32_e32 v184, v182, v183
	v_xor_b32_e32 v185, 2, v184
	v_lshrrev_b32_e32 v186, 1, v178
	v_and_b32_e32 v187, 1, v178
	v_lshl_add_u32 v188, v186, 6, v174
	v_lshl_add_u32 v189, v187, 6, v174
	v_lshlrev_b32_e32 v188, 6, v188
	v_lshlrev_b32_e32 v189, 6, v189
	v_lshl_add_u32 v154, v184, 4, v188
	v_lshl_add_u32 v155, v185, 4, v188
	v_lshl_add_u32 v156, v184, 4, v189
	v_lshl_add_u32 v157, v185, 4, v189
	v_add_u32_e32 v158, 0x2000, v156
	v_add_u32_e32 v159, 0x2000, v157
	v_lshrrev_b32_e32 v179, 3, v177
	v_lshl_add_u32 v179, v178, 3, v179
	v_mul_u32_u24_e32 v179, 0x1600, v179
	v_and_b32_e32 v180, 1, v178
	v_lshrrev_b32_e32 v183, 4, v177
	v_lshl_add_u32 v180, v180, 2, v183
	v_and_b32_e32 v183, 7, v177
	v_xor_b32_e32 v180, v180, v183
	v_lshl_add_u32 v160, v180, 4, v179
	v_add_u32_e32 v161, 0x58000, v160
	v_add_u32_e32 v242, 0x2c000, v160
	v_add_u32_e32 v243, 0x84000, v160
	v_bfe_u32 v183, v174, 1, 3
	v_or_b32_e32 v180, 0, v182
	v_xor_b32_e32 v180, v180, v183
	v_lshlrev_b32_e32 v180, 4, v180
	v_lshl_add_u32 v179, v186, 5, v174
	v_lshl_add_u32 v154, v179, 7, v180
	v_lshl_add_u32 v179, v187, 5, v174
	v_lshl_add_u32 v158, v179, 7, v180
	v_or_b32_e32 v180, 2, v182
	v_xor_b32_e32 v180, v180, v183
	v_lshlrev_b32_e32 v180, 4, v180
	v_lshl_add_u32 v179, v186, 5, v174
	v_lshl_add_u32 v155, v179, 7, v180
	v_lshl_add_u32 v179, v187, 5, v174
	v_lshl_add_u32 v159, v179, 7, v180
	v_or_b32_e32 v180, 4, v182
	v_xor_b32_e32 v180, v180, v183
	v_lshlrev_b32_e32 v180, 4, v180
	v_lshl_add_u32 v179, v186, 5, v174
	v_lshl_add_u32 v156, v179, 7, v180
	v_lshl_add_u32 v179, v187, 5, v174
	v_lshl_add_u32 v236, v179, 7, v180
	v_or_b32_e32 v180, 6, v182
	v_xor_b32_e32 v180, v180, v183
	v_lshlrev_b32_e32 v180, 4, v180
	v_lshl_add_u32 v179, v186, 5, v174
	v_lshl_add_u32 v157, v179, 7, v180
	v_lshl_add_u32 v179, v187, 5, v174
	v_lshl_add_u32 v237, v179, 7, v180
	v_lshlrev_b32_e32 v190, 6, v186
	v_lshl_add_u32 v190, v182, 2, v190
	v_lshl_add_u32 v191, v187, 6, v174
	v_lshlrev_b32_e32 v192, 12, v190
	v_lshl_add_u32 v162, v191, 2, v192
	v_add_u32_e32 v163, 0x1000, v162
	v_add_u32_e32 v164, 0x2000, v162
	v_add_u32_e32 v165, 0x3000, v162
	v_lshlrev_b32_e32 v166, 2, v191
	v_mul_u32_u24_e32 v167, 0xc000, v187
	v_lshl_add_u32 v167, v190, 2, v167
	v_xor_b32_e32 v168, 16, v177
	v_lshlrev_b32_e32 v168, 2, v168
	v_xor_b32_e32 v169, 8, v177
	v_lshlrev_b32_e32 v169, 2, v169
	v_xor_b32_e32 v171, 4, v177
	v_lshlrev_b32_e32 v171, 2, v171
	v_xor_b32_e32 v172, 2, v177
	v_lshlrev_b32_e32 v172, 2, v172
	v_xor_b32_e32 v173, 1, v177
	v_lshlrev_b32_e32 v173, 2, v173
	v_readfirstlane_b32 s65, v194
	s_nop 0
	s_lshl_b32 s65, s65, 4
	s_add_u32 s65, s65, 16
	s_mov_b32 s16, s83
.Lhw_ffndown_tloop:
	s_cmpk_gt_u32 s16, 47
	s_cbranch_scc1 .Lhw_ffndown_exit
	v_readlane_b32 s6, v246, 16
	s_lshr_b32 s2, s16, 2
	s_and_b32 s15, s16, 3
	s_add_i32 s6, s6, s2
	s_lshl_b32 s6, s6, 7
	s_lshl_b32 s15, s15, 8
	s_mul_i32 vcc_lo, s6, 0x1600
	s_add_u32 s66, s42, vcc_lo
	s_addc_u32 s67, s43, 0
	s_mul_i32 vcc_lo, s15, 0x1600
	s_add_u32 s62, s46, vcc_lo
	s_addc_u32 s63, s47, 0
	s_add_u32 s18, s62, 0xb0000
	s_addc_u32 s19, s63, 0
	s_barrier
	s_add_u32 m0, s65, 0x6000
	s_nop 0
	global_load_lds_dwordx4 v160, s[62:63]
	s_add_u32 m0, s65, 0x7000
	s_nop 0
	global_load_lds_dwordx4 v161, s[62:63]
	s_add_u32 m0, s65, 0x8000
	s_nop 0
	global_load_lds_dwordx4 v160, s[66:67]
	s_add_u32 m0, s65, 0x9000
	s_nop 0
	global_load_lds_dwordx4 v161, s[66:67]
	s_add_u32 m0, s65, 0xa000
	s_nop 0
	global_load_lds_dwordx4 v242, s[66:67]
	s_add_u32 m0, s65, 0xb000
	s_nop 0
	global_load_lds_dwordx4 v243, s[66:67]
	s_add_u32 m0, s65, 0x0
	s_nop 0
	global_load_lds_dwordx4 v242, s[62:63]
	s_add_u32 m0, s65, 0x1000
	s_nop 0
	global_load_lds_dwordx4 v243, s[62:63]
	s_add_u32 m0, s65, 0x2000
	s_nop 0
	global_load_lds_dwordx4 v160, s[18:19]
	s_add_u32 m0, s65, 0x3000
	s_nop 0
	global_load_lds_dwordx4 v161, s[18:19]
	v_mov_b32_e32 v2, 0
	v_mov_b32_e32 v3, 0
	v_mov_b32_e32 v4, 0
	v_mov_b32_e32 v5, 0
	v_mov_b32_e32 v6, 0
	v_mov_b32_e32 v7, 0
	v_mov_b32_e32 v8, 0
	v_mov_b32_e32 v9, 0
	v_mov_b32_e32 v10, 0
	v_mov_b32_e32 v11, 0
	v_mov_b32_e32 v12, 0
	v_mov_b32_e32 v13, 0
	v_mov_b32_e32 v14, 0
	v_mov_b32_e32 v15, 0
	v_mov_b32_e32 v16, 0
	v_mov_b32_e32 v17, 0
	v_mov_b32_e32 v18, 0
	v_mov_b32_e32 v19, 0
	v_mov_b32_e32 v20, 0
	v_mov_b32_e32 v21, 0
	v_mov_b32_e32 v22, 0
	v_mov_b32_e32 v23, 0
	v_mov_b32_e32 v24, 0
	v_mov_b32_e32 v25, 0
	v_mov_b32_e32 v26, 0
	v_mov_b32_e32 v27, 0
	v_mov_b32_e32 v28, 0
	v_mov_b32_e32 v29, 0
	v_mov_b32_e32 v30, 0
	v_mov_b32_e32 v31, 0
	v_mov_b32_e32 v32, 0
	v_mov_b32_e32 v33, 0
	v_mov_b32_e32 v34, 0
	v_mov_b32_e32 v35, 0
	v_mov_b32_e32 v36, 0
	v_mov_b32_e32 v37, 0
	v_mov_b32_e32 v38, 0
	v_mov_b32_e32 v39, 0
	v_mov_b32_e32 v40, 0
	v_mov_b32_e32 v41, 0
	v_mov_b32_e32 v42, 0
	v_mov_b32_e32 v43, 0
	v_mov_b32_e32 v44, 0
	v_mov_b32_e32 v45, 0
	v_mov_b32_e32 v46, 0
	v_mov_b32_e32 v47, 0
	v_mov_b32_e32 v48, 0
	v_mov_b32_e32 v49, 0
	v_mov_b32_e32 v50, 0
	v_mov_b32_e32 v51, 0
	v_mov_b32_e32 v52, 0
	v_mov_b32_e32 v53, 0
	v_mov_b32_e32 v54, 0
	v_mov_b32_e32 v55, 0
	v_mov_b32_e32 v56, 0
	v_mov_b32_e32 v57, 0
	v_mov_b32_e32 v58, 0
	v_mov_b32_e32 v59, 0
	v_mov_b32_e32 v60, 0
	v_mov_b32_e32 v61, 0
	v_mov_b32_e32 v62, 0
	v_mov_b32_e32 v63, 0
	v_mov_b32_e32 v64, 0
	v_mov_b32_e32 v65, 0
	v_mov_b32_e32 v66, 0
	v_mov_b32_e32 v67, 0
	v_mov_b32_e32 v68, 0
	v_mov_b32_e32 v69, 0
	v_mov_b32_e32 v70, 0
	v_mov_b32_e32 v71, 0
	v_mov_b32_e32 v72, 0
	v_mov_b32_e32 v73, 0
	v_mov_b32_e32 v74, 0
	v_mov_b32_e32 v75, 0
	v_mov_b32_e32 v76, 0
	v_mov_b32_e32 v77, 0
	v_mov_b32_e32 v78, 0
	v_mov_b32_e32 v79, 0
	v_mov_b32_e32 v80, 0
	v_mov_b32_e32 v81, 0
	v_mov_b32_e32 v82, 0
	v_mov_b32_e32 v83, 0
	v_mov_b32_e32 v84, 0
	v_mov_b32_e32 v85, 0
	v_mov_b32_e32 v86, 0
	v_mov_b32_e32 v87, 0
	v_mov_b32_e32 v88, 0
	v_mov_b32_e32 v89, 0
	v_mov_b32_e32 v90, 0
	v_mov_b32_e32 v91, 0
	v_mov_b32_e32 v92, 0
	v_mov_b32_e32 v93, 0
	v_mov_b32_e32 v94, 0
	v_mov_b32_e32 v95, 0
	v_mov_b32_e32 v96, 0
	v_mov_b32_e32 v97, 0
	v_mov_b32_e32 v98, 0
	v_mov_b32_e32 v99, 0
	v_mov_b32_e32 v100, 0
	v_mov_b32_e32 v101, 0
	v_mov_b32_e32 v102, 0
	v_mov_b32_e32 v103, 0
	v_mov_b32_e32 v104, 0
	v_mov_b32_e32 v105, 0
	v_mov_b32_e32 v106, 0
	v_mov_b32_e32 v107, 0
	v_mov_b32_e32 v108, 0
	v_mov_b32_e32 v109, 0
	v_mov_b32_e32 v110, 0
	v_mov_b32_e32 v111, 0
	v_mov_b32_e32 v112, 0
	v_mov_b32_e32 v113, 0
	v_mov_b32_e32 v114, 0
	v_mov_b32_e32 v115, 0
	v_mov_b32_e32 v116, 0
	v_mov_b32_e32 v117, 0
	v_mov_b32_e32 v118, 0
	v_mov_b32_e32 v119, 0
	v_mov_b32_e32 v120, 0
	v_mov_b32_e32 v121, 0
	v_mov_b32_e32 v122, 0
	v_mov_b32_e32 v123, 0
	v_mov_b32_e32 v124, 0
	v_mov_b32_e32 v125, 0
	v_mov_b32_e32 v126, 0
	v_mov_b32_e32 v127, 0
	v_mov_b32_e32 v128, 0
	v_mov_b32_e32 v129, 0
	s_waitcnt vmcnt(0)
	s_barrier
	ds_read_b128 v[130:133], v154 offset:32784
	ds_read_b128 v[146:149], v154 offset:40976
	ds_read_b128 v[220:223], v158 offset:24592
	ds_read_b128 v[134:137], v155 offset:32784
	ds_read_b128 v[150:153], v155 offset:40976
	ds_read_b128 v[224:227], v159 offset:24592
	ds_read_b128 v[138:141], v156 offset:32784
	ds_read_b128 v[212:215], v156 offset:40976
	ds_read_b128 v[228:231], v236 offset:24592
	ds_read_b128 v[142:145], v157 offset:32784
	ds_read_b128 v[216:219], v157 offset:40976
	ds_read_b128 v[232:235], v237 offset:24592
	s_waitcnt lgkmcnt(0)
	s_barrier
	s_mov_b32 s59, 43
.Lhw_ffndown_loop:
	v_mfma_f32_32x32x16_bf16 v[2:17], v[130:133], v[220:223], v[2:17]
	s_add_u32 m0, s65, 0x4000
	s_nop 0
	global_load_lds_dwordx4 v242, s[18:19]
	v_mfma_f32_32x32x16_bf16 v[34:49], v[146:149], v[220:223], v[34:49]
	s_add_u32 m0, s65, 0x5000
	ds_read_b128 v[220:223], v158 offset:16
	global_load_lds_dwordx4 v243, s[18:19]
	v_mfma_f32_32x32x16_bf16 v[2:17], v[134:137], v[224:227], v[2:17]
	s_add_u32 s62, s62, 128
	s_addc_u32 s63, s63, 0
	s_add_u32 s66, s66, 128
	s_addc_u32 s67, s67, 0
	v_mfma_f32_32x32x16_bf16 v[34:49], v[150:153], v[224:227], v[34:49]
	s_add_u32 m0, s65, 0x6000
	ds_read_b128 v[224:227], v159 offset:16
	global_load_lds_dwordx4 v160, s[62:63]
	v_mfma_f32_32x32x16_bf16 v[2:17], v[138:141], v[228:231], v[2:17]
	s_add_u32 m0, s65, 0x7000
	s_nop 0
	global_load_lds_dwordx4 v161, s[62:63]
	v_mfma_f32_32x32x16_bf16 v[34:49], v[212:215], v[228:231], v[34:49]
	s_add_u32 m0, s65, 0x8000
	ds_read_b128 v[228:231], v236 offset:16
	global_load_lds_dwordx4 v160, s[66:67]
	v_mfma_f32_32x32x16_bf16 v[2:17], v[142:145], v[232:235], v[2:17]
	s_add_u32 m0, s65, 0x9000
	s_nop 0
	global_load_lds_dwordx4 v161, s[66:67]
	v_mfma_f32_32x32x16_bf16 v[34:49], v[216:219], v[232:235], v[34:49]
	s_add_u32 m0, s65, 0xa000
	ds_read_b128 v[232:235], v237 offset:16
	global_load_lds_dwordx4 v242, s[66:67]
	s_waitcnt lgkmcnt(3)
	v_mfma_f32_32x32x16_bf16 v[18:33], v[130:133], v[220:223], v[18:33]
	s_add_u32 m0, s65, 0xb000
	s_nop 0
	global_load_lds_dwordx4 v243, s[66:67]
	v_mfma_f32_32x32x16_bf16 v[50:65], v[146:149], v[220:223], v[50:65]
	ds_read_b128 v[220:223], v158 offset:8208
	s_waitcnt lgkmcnt(3)
	v_mfma_f32_32x32x16_bf16 v[18:33], v[134:137], v[224:227], v[18:33]
	v_mfma_f32_32x32x16_bf16 v[50:65], v[150:153], v[224:227], v[50:65]
	ds_read_b128 v[224:227], v159 offset:8208
	s_waitcnt lgkmcnt(3)
	v_mfma_f32_32x32x16_bf16 v[18:33], v[138:141], v[228:231], v[18:33]
	v_mfma_f32_32x32x16_bf16 v[50:65], v[212:215], v[228:231], v[50:65]
	ds_read_b128 v[228:231], v236 offset:8208
	s_waitcnt lgkmcnt(3)
	v_mfma_f32_32x32x16_bf16 v[18:33], v[142:145], v[232:235], v[18:33]
	v_mfma_f32_32x32x16_bf16 v[50:65], v[216:219], v[232:235], v[50:65]
	ds_read_b128 v[232:235], v237 offset:8208
	s_waitcnt vmcnt(0) lgkmcnt(0)
	s_barrier
	v_mfma_f32_32x32x16_bf16 v[66:81], v[130:133], v[220:223], v[66:81]
	s_add_u32 s18, s18, 128
	s_addc_u32 s19, s19, 0
	v_mfma_f32_32x32x16_bf16 v[98:113], v[146:149], v[220:223], v[98:113]
	s_add_u32 m0, s65, 0x0
	ds_read_b128 v[220:223], v158 offset:16400
	global_load_lds_dwordx4 v242, s[62:63]
	v_mfma_f32_32x32x16_bf16 v[66:81], v[134:137], v[224:227], v[66:81]
	s_add_u32 m0, s65, 0x1000
	s_nop 0
	global_load_lds_dwordx4 v243, s[62:63]
	v_mfma_f32_32x32x16_bf16 v[98:113], v[150:153], v[224:227], v[98:113]
	s_add_u32 m0, s65, 0x2000
	ds_read_b128 v[224:227], v159 offset:16400
	global_load_lds_dwordx4 v160, s[18:19]
	v_mfma_f32_32x32x16_bf16 v[66:81], v[138:141], v[228:231], v[66:81]
	s_add_u32 m0, s65, 0x3000
	s_nop 0
	global_load_lds_dwordx4 v161, s[18:19]
	v_mfma_f32_32x32x16_bf16 v[98:113], v[212:215], v[228:231], v[98:113]
	ds_read_b128 v[228:231], v236 offset:16400
	v_mfma_f32_32x32x16_bf16 v[66:81], v[142:145], v[232:235], v[66:81]
	v_mfma_f32_32x32x16_bf16 v[98:113], v[216:219], v[232:235], v[98:113]
	ds_read_b128 v[232:235], v237 offset:16400
	s_waitcnt lgkmcnt(3)
	v_mfma_f32_32x32x16_bf16 v[82:97], v[130:133], v[220:223], v[82:97]
	ds_read_b128 v[130:133], v154 offset:32784
	v_mfma_f32_32x32x16_bf16 v[114:129], v[146:149], v[220:223], v[114:129]
	ds_read_b128 v[220:223], v158 offset:24592
	ds_read_b128 v[146:149], v154 offset:40976
	s_waitcnt lgkmcnt(5)
	v_mfma_f32_32x32x16_bf16 v[82:97], v[134:137], v[224:227], v[82:97]
	ds_read_b128 v[134:137], v155 offset:32784
	v_mfma_f32_32x32x16_bf16 v[114:129], v[150:153], v[224:227], v[114:129]
	ds_read_b128 v[224:227], v159 offset:24592
	ds_read_b128 v[150:153], v155 offset:40976
	s_waitcnt lgkmcnt(7)
	v_mfma_f32_32x32x16_bf16 v[82:97], v[138:141], v[228:231], v[82:97]
	ds_read_b128 v[138:141], v156 offset:32784
	v_mfma_f32_32x32x16_bf16 v[114:129], v[212:215], v[228:231], v[114:129]
	ds_read_b128 v[228:231], v236 offset:24592
	ds_read_b128 v[212:215], v156 offset:40976
	s_waitcnt lgkmcnt(9)
	v_mfma_f32_32x32x16_bf16 v[82:97], v[142:145], v[232:235], v[82:97]
	ds_read_b128 v[142:145], v157 offset:32784
	v_mfma_f32_32x32x16_bf16 v[114:129], v[216:219], v[232:235], v[114:129]
	ds_read_b128 v[232:235], v237 offset:24592
	ds_read_b128 v[216:219], v157 offset:40976
	s_waitcnt vmcnt(0) lgkmcnt(0)
	s_barrier
	s_sub_u32 s59, s59, 1
	s_cmp_lg_u32 s59, 0
	s_cbranch_scc1 .Lhw_ffndown_loop
	v_mfma_f32_32x32x16_bf16 v[2:17], v[130:133], v[220:223], v[2:17]
	s_add_u32 m0, s65, 0x4000
	s_nop 0
	global_load_lds_dwordx4 v242, s[18:19]
	v_mfma_f32_32x32x16_bf16 v[34:49], v[146:149], v[220:223], v[34:49]
	s_add_u32 m0, s65, 0x5000
	ds_read_b128 v[220:223], v158 offset:16
	global_load_lds_dwordx4 v243, s[18:19]
	v_mfma_f32_32x32x16_bf16 v[2:17], v[134:137], v[224:227], v[2:17]
	v_mfma_f32_32x32x16_bf16 v[34:49], v[150:153], v[224:227], v[34:49]
	ds_read_b128 v[224:227], v159 offset:16
	v_mfma_f32_32x32x16_bf16 v[2:17], v[138:141], v[228:231], v[2:17]
	v_mfma_f32_32x32x16_bf16 v[34:49], v[212:215], v[228:231], v[34:49]
	ds_read_b128 v[228:231], v236 offset:16
	v_mfma_f32_32x32x16_bf16 v[2:17], v[142:145], v[232:235], v[2:17]
	v_mfma_f32_32x32x16_bf16 v[34:49], v[216:219], v[232:235], v[34:49]
	ds_read_b128 v[232:235], v237 offset:16
	s_waitcnt lgkmcnt(3)
	v_mfma_f32_32x32x16_bf16 v[18:33], v[130:133], v[220:223], v[18:33]
	v_mfma_f32_32x32x16_bf16 v[50:65], v[146:149], v[220:223], v[50:65]
	ds_read_b128 v[220:223], v158 offset:8208
	s_waitcnt lgkmcnt(3)
	v_mfma_f32_32x32x16_bf16 v[18:33], v[134:137], v[224:227], v[18:33]
	v_mfma_f32_32x32x16_bf16 v[50:65], v[150:153], v[224:227], v[50:65]
	ds_read_b128 v[224:227], v159 offset:8208
	s_waitcnt lgkmcnt(3)
	v_mfma_f32_32x32x16_bf16 v[18:33], v[138:141], v[228:231], v[18:33]
	v_mfma_f32_32x32x16_bf16 v[50:65], v[212:215], v[228:231], v[50:65]
	ds_read_b128 v[228:231], v236 offset:8208
	s_waitcnt lgkmcnt(3)
	v_mfma_f32_32x32x16_bf16 v[18:33], v[142:145], v[232:235], v[18:33]
	v_mfma_f32_32x32x16_bf16 v[50:65], v[216:219], v[232:235], v[50:65]
	ds_read_b128 v[232:235], v237 offset:8208
	s_waitcnt vmcnt(0) lgkmcnt(0)
	s_barrier
	v_mfma_f32_32x32x16_bf16 v[66:81], v[130:133], v[220:223], v[66:81]
	v_mfma_f32_32x32x16_bf16 v[98:113], v[146:149], v[220:223], v[98:113]
	ds_read_b128 v[220:223], v158 offset:16400
	v_mfma_f32_32x32x16_bf16 v[66:81], v[134:137], v[224:227], v[66:81]
	v_mfma_f32_32x32x16_bf16 v[98:113], v[150:153], v[224:227], v[98:113]
	ds_read_b128 v[224:227], v159 offset:16400
	v_mfma_f32_32x32x16_bf16 v[66:81], v[138:141], v[228:231], v[66:81]
	v_mfma_f32_32x32x16_bf16 v[98:113], v[212:215], v[228:231], v[98:113]
	ds_read_b128 v[228:231], v236 offset:16400
	v_mfma_f32_32x32x16_bf16 v[66:81], v[142:145], v[232:235], v[66:81]
	v_mfma_f32_32x32x16_bf16 v[98:113], v[216:219], v[232:235], v[98:113]
	ds_read_b128 v[232:235], v237 offset:16400
	s_waitcnt lgkmcnt(3)
	v_mfma_f32_32x32x16_bf16 v[82:97], v[130:133], v[220:223], v[82:97]
	v_mfma_f32_32x32x16_bf16 v[114:129], v[146:149], v[220:223], v[114:129]
	s_waitcnt lgkmcnt(2)
	v_mfma_f32_32x32x16_bf16 v[82:97], v[134:137], v[224:227], v[82:97]
	v_mfma_f32_32x32x16_bf16 v[114:129], v[150:153], v[224:227], v[114:129]
	s_waitcnt lgkmcnt(1)
	v_mfma_f32_32x32x16_bf16 v[82:97], v[138:141], v[228:231], v[82:97]
	v_mfma_f32_32x32x16_bf16 v[114:129], v[212:215], v[228:231], v[114:129]
	s_waitcnt lgkmcnt(0)
	v_mfma_f32_32x32x16_bf16 v[82:97], v[142:145], v[232:235], v[82:97]
	v_mfma_f32_32x32x16_bf16 v[114:129], v[216:219], v[232:235], v[114:129]
	s_nop 7
	s_nop 7
	s_sub_i32 s2, s6, 0x1000
	s_ashr_i32 s2, s2, 11
	s_add_i32 s2, s2, 1
	s_max_i32 s2, s2, 0
	v_readlane_b32 s17, v246, 28
	s_nop 0
	s_add_i32 s2, s2, s17
	s_mul_i32 s2, s2, 0x9000
	s_lshl_b32 s17, s15, 2
	s_add_u32 s2, s2, s17
	s_add_u32 s60, s12, s2
	s_addc_u32 s61, s13, 0
	s_lshr_b32 s2, s15, 7
	s_mul_i32 s2, s2, 0x18000
	s_lshl_b32 s20, s6, 2
	s_add_u32 s2, s2, s20
	s_add_u32 s10, s44, s2
	s_addc_u32 s11, s45, 0
	s_lshl_b32 s2, s6, 12
	s_add_u32 s2, s2, s17
	s_add_u32 s48, s40, s2
	s_addc_u32 s49, s41, 0
	global_load_dword v175, v166, s[60:61]
	global_load_dword v176, v166, s[60:61] offset:128
	global_load_dword v130, v162, s[48:49]
	global_load_dword v212, v162, s[48:49] offset:128
	global_load_dword v131, v163, s[48:49]
	global_load_dword v213, v163, s[48:49] offset:128
	global_load_dword v132, v164, s[48:49]
	global_load_dword v214, v164, s[48:49] offset:128
	global_load_dword v133, v165, s[48:49]
	global_load_dword v215, v165, s[48:49] offset:128
	s_add_u32 s48, s48, 0x8000
	s_addc_u32 s49, s49, 0
	global_load_dword v134, v162, s[48:49]
	global_load_dword v216, v162, s[48:49] offset:128
	global_load_dword v135, v163, s[48:49]
	global_load_dword v217, v163, s[48:49] offset:128
	global_load_dword v136, v164, s[48:49]
	global_load_dword v218, v164, s[48:49] offset:128
	global_load_dword v137, v165, s[48:49]
	global_load_dword v219, v165, s[48:49] offset:128
	s_add_u32 s48, s48, 0x8000
	s_addc_u32 s49, s49, 0
	global_load_dword v138, v162, s[48:49]
	global_load_dword v220, v162, s[48:49] offset:128
	global_load_dword v139, v163, s[48:49]
	global_load_dword v221, v163, s[48:49] offset:128
	global_load_dword v140, v164, s[48:49]
	global_load_dword v222, v164, s[48:49] offset:128
	global_load_dword v141, v165, s[48:49]
	global_load_dword v223, v165, s[48:49] offset:128
	s_add_u32 s48, s48, 0x8000
	s_addc_u32 s49, s49, 0
	global_load_dword v142, v162, s[48:49]
	global_load_dword v224, v162, s[48:49] offset:128
	global_load_dword v143, v163, s[48:49]
	global_load_dword v225, v163, s[48:49] offset:128
	global_load_dword v144, v164, s[48:49]
	global_load_dword v226, v164, s[48:49] offset:128
	global_load_dword v145, v165, s[48:49]
	global_load_dword v227, v165, s[48:49] offset:128
	s_sub_u32 s48, s48, 0x18000
	s_subb_u32 s49, s49, 0
	s_waitcnt vmcnt(32)
	v_mul_f32_e32 v175, 0.5, v175
	v_mul_f32_e32 v176, 0.5, v176
	s_waitcnt vmcnt(30)
	v_fmac_f32_e32 v130, v2, v175
	v_fmac_f32_e32 v212, v18, v176
	global_store_dword v162, v130, s[48:49]
	global_store_dword v162, v212, s[48:49] offset:128
	s_waitcnt vmcnt(30)
	v_fmac_f32_e32 v131, v3, v175
	v_fmac_f32_e32 v213, v19, v176
	global_store_dword v163, v131, s[48:49]
	global_store_dword v163, v213, s[48:49] offset:128
	s_waitcnt vmcnt(30)
	v_fmac_f32_e32 v132, v4, v175
	v_fmac_f32_e32 v214, v20, v176
	global_store_dword v164, v132, s[48:49]
	global_store_dword v164, v214, s[48:49] offset:128
	s_waitcnt vmcnt(30)
	v_fmac_f32_e32 v133, v5, v175
	v_fmac_f32_e32 v215, v21, v176
	global_store_dword v165, v133, s[48:49]
	global_store_dword v165, v215, s[48:49] offset:128
	s_add_u32 s48, s48, 0x8000
	s_addc_u32 s49, s49, 0
	s_waitcnt vmcnt(30)
	v_fmac_f32_e32 v134, v6, v175
	v_fmac_f32_e32 v216, v22, v176
	global_store_dword v162, v134, s[48:49]
	global_store_dword v162, v216, s[48:49] offset:128
	s_waitcnt vmcnt(30)
	v_fmac_f32_e32 v135, v7, v175
	v_fmac_f32_e32 v217, v23, v176
	global_store_dword v163, v135, s[48:49]
	global_store_dword v163, v217, s[48:49] offset:128
	s_waitcnt vmcnt(30)
	v_fmac_f32_e32 v136, v8, v175
	v_fmac_f32_e32 v218, v24, v176
	global_store_dword v164, v136, s[48:49]
	global_store_dword v164, v218, s[48:49] offset:128
	s_waitcnt vmcnt(30)
	v_fmac_f32_e32 v137, v9, v175
	v_fmac_f32_e32 v219, v25, v176
	global_store_dword v165, v137, s[48:49]
	global_store_dword v165, v219, s[48:49] offset:128
	s_add_u32 s48, s48, 0x8000
	s_addc_u32 s49, s49, 0
	s_waitcnt vmcnt(30)
	v_fmac_f32_e32 v138, v10, v175
	v_fmac_f32_e32 v220, v26, v176
	global_store_dword v162, v138, s[48:49]
	global_store_dword v162, v220, s[48:49] offset:128
	s_waitcnt vmcnt(30)
	v_fmac_f32_e32 v139, v11, v175
	v_fmac_f32_e32 v221, v27, v176
	global_store_dword v163, v139, s[48:49]
	global_store_dword v163, v221, s[48:49] offset:128
	s_waitcnt vmcnt(30)
	v_fmac_f32_e32 v140, v12, v175
	v_fmac_f32_e32 v222, v28, v176
	global_store_dword v164, v140, s[48:49]
	global_store_dword v164, v222, s[48:49] offset:128
	s_waitcnt vmcnt(30)
	v_fmac_f32_e32 v141, v13, v175
	v_fmac_f32_e32 v223, v29, v176
	global_store_dword v165, v141, s[48:49]
	global_store_dword v165, v223, s[48:49] offset:128
	s_add_u32 s48, s48, 0x8000
	s_addc_u32 s49, s49, 0
	s_waitcnt vmcnt(30)
	v_fmac_f32_e32 v142, v14, v175
	v_fmac_f32_e32 v224, v30, v176
	global_store_dword v162, v142, s[48:49]
	global_store_dword v162, v224, s[48:49] offset:128
	s_waitcnt vmcnt(30)
	v_fmac_f32_e32 v143, v15, v175
	v_fmac_f32_e32 v225, v31, v176
	global_store_dword v163, v143, s[48:49]
	global_store_dword v163, v225, s[48:49] offset:128
	s_waitcnt vmcnt(30)
	v_fmac_f32_e32 v144, v16, v175
	v_fmac_f32_e32 v226, v32, v176
	global_store_dword v164, v144, s[48:49]
	global_store_dword v164, v226, s[48:49] offset:128
	s_waitcnt vmcnt(30)
	v_fmac_f32_e32 v145, v17, v175
	v_fmac_f32_e32 v227, v33, v176
	global_store_dword v165, v145, s[48:49]
	global_store_dword v165, v227, s[48:49] offset:128
	s_sub_u32 s48, s48, 0x18000
	s_subb_u32 s49, s49, 0
	v_mul_f32_e32 v130, v130, v130
	v_fmac_f32_e32 v130, v212, v212
	v_mul_f32_e32 v131, v131, v131
	v_fmac_f32_e32 v131, v213, v213
	v_mul_f32_e32 v132, v132, v132
	v_fmac_f32_e32 v132, v214, v214
	v_mul_f32_e32 v133, v133, v133
	v_fmac_f32_e32 v133, v215, v215
	v_mul_f32_e32 v134, v134, v134
	v_fmac_f32_e32 v134, v216, v216
	v_mul_f32_e32 v135, v135, v135
	v_fmac_f32_e32 v135, v217, v217
	v_mul_f32_e32 v136, v136, v136
	v_fmac_f32_e32 v136, v218, v218
	v_mul_f32_e32 v137, v137, v137
	v_fmac_f32_e32 v137, v219, v219
	v_mul_f32_e32 v138, v138, v138
	v_fmac_f32_e32 v138, v220, v220
	v_mul_f32_e32 v139, v139, v139
	v_fmac_f32_e32 v139, v221, v221
	v_mul_f32_e32 v140, v140, v140
	v_fmac_f32_e32 v140, v222, v222
	v_mul_f32_e32 v141, v141, v141
	v_fmac_f32_e32 v141, v223, v223
	v_mul_f32_e32 v142, v142, v142
	v_fmac_f32_e32 v142, v224, v224
	v_mul_f32_e32 v143, v143, v143
	v_fmac_f32_e32 v143, v225, v225
	v_mul_f32_e32 v144, v144, v144
	v_fmac_f32_e32 v144, v226, v226
	v_mul_f32_e32 v145, v145, v145
	v_fmac_f32_e32 v145, v227, v227
	s_waitcnt lgkmcnt(0)
	ds_bpermute_b32 v212, v168, v130
	ds_bpermute_b32 v213, v168, v131
	ds_bpermute_b32 v214, v168, v132
	ds_bpermute_b32 v215, v168, v133
	ds_bpermute_b32 v216, v168, v134
	ds_bpermute_b32 v217, v168, v135
	ds_bpermute_b32 v218, v168, v136
	ds_bpermute_b32 v219, v168, v137
	s_waitcnt lgkmcnt(7)
	v_add_f32_e32 v130, v130, v212
	s_waitcnt lgkmcnt(6)
	v_add_f32_e32 v131, v131, v213
	s_waitcnt lgkmcnt(5)
	v_add_f32_e32 v132, v132, v214
	s_waitcnt lgkmcnt(4)
	v_add_f32_e32 v133, v133, v215
	s_waitcnt lgkmcnt(3)
	v_add_f32_e32 v134, v134, v216
	s_waitcnt lgkmcnt(2)
	v_add_f32_e32 v135, v135, v217
	s_waitcnt lgkmcnt(1)
	v_add_f32_e32 v136, v136, v218
	s_waitcnt lgkmcnt(0)
	v_add_f32_e32 v137, v137, v219
	ds_bpermute_b32 v212, v169, v130
	ds_bpermute_b32 v213, v169, v131
	ds_bpermute_b32 v214, v169, v132
	ds_bpermute_b32 v215, v169, v133
	ds_bpermute_b32 v216, v169, v134
	ds_bpermute_b32 v217, v169, v135
	ds_bpermute_b32 v218, v169, v136
	ds_bpermute_b32 v219, v169, v137
	s_waitcnt lgkmcnt(7)
	v_add_f32_e32 v130, v130, v212
	s_waitcnt lgkmcnt(6)
	v_add_f32_e32 v131, v131, v213
	s_waitcnt lgkmcnt(5)
	v_add_f32_e32 v132, v132, v214
	s_waitcnt lgkmcnt(4)
	v_add_f32_e32 v133, v133, v215
	s_waitcnt lgkmcnt(3)
	v_add_f32_e32 v134, v134, v216
	s_waitcnt lgkmcnt(2)
	v_add_f32_e32 v135, v135, v217
	s_waitcnt lgkmcnt(1)
	v_add_f32_e32 v136, v136, v218
	s_waitcnt lgkmcnt(0)
	v_add_f32_e32 v137, v137, v219
	ds_bpermute_b32 v212, v171, v130
	ds_bpermute_b32 v213, v171, v131
	ds_bpermute_b32 v214, v171, v132
	ds_bpermute_b32 v215, v171, v133
	ds_bpermute_b32 v216, v171, v134
	ds_bpermute_b32 v217, v171, v135
	ds_bpermute_b32 v218, v171, v136
	ds_bpermute_b32 v219, v171, v137
	s_waitcnt lgkmcnt(7)
	v_add_f32_e32 v130, v130, v212
	s_waitcnt lgkmcnt(6)
	v_add_f32_e32 v131, v131, v213
	s_waitcnt lgkmcnt(5)
	v_add_f32_e32 v132, v132, v214
	s_waitcnt lgkmcnt(4)
	v_add_f32_e32 v133, v133, v215
	s_waitcnt lgkmcnt(3)
	v_add_f32_e32 v134, v134, v216
	s_waitcnt lgkmcnt(2)
	v_add_f32_e32 v135, v135, v217
	s_waitcnt lgkmcnt(1)
	v_add_f32_e32 v136, v136, v218
	s_waitcnt lgkmcnt(0)
	v_add_f32_e32 v137, v137, v219
	ds_bpermute_b32 v212, v172, v130
	ds_bpermute_b32 v213, v172, v131
	ds_bpermute_b32 v214, v172, v132
	ds_bpermute_b32 v215, v172, v133
	ds_bpermute_b32 v216, v172, v134
	ds_bpermute_b32 v217, v172, v135
	ds_bpermute_b32 v218, v172, v136
	ds_bpermute_b32 v219, v172, v137
	s_waitcnt lgkmcnt(7)
	v_add_f32_e32 v130, v130, v212
	s_waitcnt lgkmcnt(6)
	v_add_f32_e32 v131, v131, v213
	s_waitcnt lgkmcnt(5)
	v_add_f32_e32 v132, v132, v214
	s_waitcnt lgkmcnt(4)
	v_add_f32_e32 v133, v133, v215
	s_waitcnt lgkmcnt(3)
	v_add_f32_e32 v134, v134, v216
	s_waitcnt lgkmcnt(2)
	v_add_f32_e32 v135, v135, v217
	s_waitcnt lgkmcnt(1)
	v_add_f32_e32 v136, v136, v218
	s_waitcnt lgkmcnt(0)
	v_add_f32_e32 v137, v137, v219
	ds_bpermute_b32 v212, v173, v130
	ds_bpermute_b32 v213, v173, v131
	ds_bpermute_b32 v214, v173, v132
	ds_bpermute_b32 v215, v173, v133
	ds_bpermute_b32 v216, v173, v134
	ds_bpermute_b32 v217, v173, v135
	ds_bpermute_b32 v218, v173, v136
	ds_bpermute_b32 v219, v173, v137
	s_waitcnt lgkmcnt(7)
	v_add_f32_e32 v130, v130, v212
	s_waitcnt lgkmcnt(6)
	v_add_f32_e32 v131, v131, v213
	s_waitcnt lgkmcnt(5)
	v_add_f32_e32 v132, v132, v214
	s_waitcnt lgkmcnt(4)
	v_add_f32_e32 v133, v133, v215
	s_waitcnt lgkmcnt(3)
	v_add_f32_e32 v134, v134, v216
	s_waitcnt lgkmcnt(2)
	v_add_f32_e32 v135, v135, v217
	s_waitcnt lgkmcnt(1)
	v_add_f32_e32 v136, v136, v218
	s_waitcnt lgkmcnt(0)
	v_add_f32_e32 v137, v137, v219
	ds_bpermute_b32 v220, v168, v138
	ds_bpermute_b32 v221, v168, v139
	ds_bpermute_b32 v222, v168, v140
	ds_bpermute_b32 v223, v168, v141
	ds_bpermute_b32 v224, v168, v142
	ds_bpermute_b32 v225, v168, v143
	ds_bpermute_b32 v226, v168, v144
	ds_bpermute_b32 v227, v168, v145
	s_waitcnt lgkmcnt(7)
	v_add_f32_e32 v138, v138, v220
	s_waitcnt lgkmcnt(6)
	v_add_f32_e32 v139, v139, v221
	s_waitcnt lgkmcnt(5)
	v_add_f32_e32 v140, v140, v222
	s_waitcnt lgkmcnt(4)
	v_add_f32_e32 v141, v141, v223
	s_waitcnt lgkmcnt(3)
	v_add_f32_e32 v142, v142, v224
	s_waitcnt lgkmcnt(2)
	v_add_f32_e32 v143, v143, v225
	s_waitcnt lgkmcnt(1)
	v_add_f32_e32 v144, v144, v226
	s_waitcnt lgkmcnt(0)
	v_add_f32_e32 v145, v145, v227
	ds_bpermute_b32 v220, v169, v138
	ds_bpermute_b32 v221, v169, v139
	ds_bpermute_b32 v222, v169, v140
	ds_bpermute_b32 v223, v169, v141
	ds_bpermute_b32 v224, v169, v142
	ds_bpermute_b32 v225, v169, v143
	ds_bpermute_b32 v226, v169, v144
	ds_bpermute_b32 v227, v169, v145
	s_waitcnt lgkmcnt(7)
	v_add_f32_e32 v138, v138, v220
	s_waitcnt lgkmcnt(6)
	v_add_f32_e32 v139, v139, v221
	s_waitcnt lgkmcnt(5)
	v_add_f32_e32 v140, v140, v222
	s_waitcnt lgkmcnt(4)
	v_add_f32_e32 v141, v141, v223
	s_waitcnt lgkmcnt(3)
	v_add_f32_e32 v142, v142, v224
	s_waitcnt lgkmcnt(2)
	v_add_f32_e32 v143, v143, v225
	s_waitcnt lgkmcnt(1)
	v_add_f32_e32 v144, v144, v226
	s_waitcnt lgkmcnt(0)
	v_add_f32_e32 v145, v145, v227
	ds_bpermute_b32 v220, v171, v138
	ds_bpermute_b32 v221, v171, v139
	ds_bpermute_b32 v222, v171, v140
	ds_bpermute_b32 v223, v171, v141
	ds_bpermute_b32 v224, v171, v142
	ds_bpermute_b32 v225, v171, v143
	ds_bpermute_b32 v226, v171, v144
	ds_bpermute_b32 v227, v171, v145
	s_waitcnt lgkmcnt(7)
	v_add_f32_e32 v138, v138, v220
	s_waitcnt lgkmcnt(6)
	v_add_f32_e32 v139, v139, v221
	s_waitcnt lgkmcnt(5)
	v_add_f32_e32 v140, v140, v222
	s_waitcnt lgkmcnt(4)
	v_add_f32_e32 v141, v141, v223
	s_waitcnt lgkmcnt(3)
	v_add_f32_e32 v142, v142, v224
	s_waitcnt lgkmcnt(2)
	v_add_f32_e32 v143, v143, v225
	s_waitcnt lgkmcnt(1)
	v_add_f32_e32 v144, v144, v226
	s_waitcnt lgkmcnt(0)
	v_add_f32_e32 v145, v145, v227
	ds_bpermute_b32 v220, v172, v138
	ds_bpermute_b32 v221, v172, v139
	ds_bpermute_b32 v222, v172, v140
	ds_bpermute_b32 v223, v172, v141
	ds_bpermute_b32 v224, v172, v142
	ds_bpermute_b32 v225, v172, v143
	ds_bpermute_b32 v226, v172, v144
	ds_bpermute_b32 v227, v172, v145
	s_waitcnt lgkmcnt(7)
	v_add_f32_e32 v138, v138, v220
	s_waitcnt lgkmcnt(6)
	v_add_f32_e32 v139, v139, v221
	s_waitcnt lgkmcnt(5)
	v_add_f32_e32 v140, v140, v222
	s_waitcnt lgkmcnt(4)
	v_add_f32_e32 v141, v141, v223
	s_waitcnt lgkmcnt(3)
	v_add_f32_e32 v142, v142, v224
	s_waitcnt lgkmcnt(2)
	v_add_f32_e32 v143, v143, v225
	s_waitcnt lgkmcnt(1)
	v_add_f32_e32 v144, v144, v226
	s_waitcnt lgkmcnt(0)
	v_add_f32_e32 v145, v145, v227
	ds_bpermute_b32 v220, v173, v138
	ds_bpermute_b32 v221, v173, v139
	ds_bpermute_b32 v222, v173, v140
	ds_bpermute_b32 v223, v173, v141
	ds_bpermute_b32 v224, v173, v142
	ds_bpermute_b32 v225, v173, v143
	ds_bpermute_b32 v226, v173, v144
	ds_bpermute_b32 v227, v173, v145
	s_waitcnt lgkmcnt(7)
	v_add_f32_e32 v138, v138, v220
	s_waitcnt lgkmcnt(6)
	v_add_f32_e32 v139, v139, v221
	s_waitcnt lgkmcnt(5)
	v_add_f32_e32 v140, v140, v222
	s_waitcnt lgkmcnt(4)
	v_add_f32_e32 v141, v141, v223
	s_waitcnt lgkmcnt(3)
	v_add_f32_e32 v142, v142, v224
	s_waitcnt lgkmcnt(2)
	v_add_f32_e32 v143, v143, v225
	s_waitcnt lgkmcnt(1)
	v_add_f32_e32 v144, v144, v226
	s_waitcnt lgkmcnt(0)
	v_add_f32_e32 v145, v145, v227
	v_cmp_eq_u32_e32 vcc, 0, v174
	s_and_saveexec_b64 s[58:59], vcc
	global_store_dword v167, v130, s[10:11]
	global_store_dword v167, v131, s[10:11] offset:4
	global_store_dword v167, v132, s[10:11] offset:8
	global_store_dword v167, v133, s[10:11] offset:12
	global_store_dword v167, v134, s[10:11] offset:32
	global_store_dword v167, v135, s[10:11] offset:36
	global_store_dword v167, v136, s[10:11] offset:40
	global_store_dword v167, v137, s[10:11] offset:44
	global_store_dword v167, v138, s[10:11] offset:64
	global_store_dword v167, v139, s[10:11] offset:68
	global_store_dword v167, v140, s[10:11] offset:72
	global_store_dword v167, v141, s[10:11] offset:76
	global_store_dword v167, v142, s[10:11] offset:96
	global_store_dword v167, v143, s[10:11] offset:100
	global_store_dword v167, v144, s[10:11] offset:104
	global_store_dword v167, v145, s[10:11] offset:108
	s_mov_b64 exec, -1
	s_add_u32 s48, s48, 0x20000
	s_addc_u32 s49, s49, 0
	global_load_dword v130, v162, s[48:49]
	global_load_dword v212, v162, s[48:49] offset:128
	global_load_dword v131, v163, s[48:49]
	global_load_dword v213, v163, s[48:49] offset:128
	global_load_dword v132, v164, s[48:49]
	global_load_dword v214, v164, s[48:49] offset:128
	global_load_dword v133, v165, s[48:49]
	global_load_dword v215, v165, s[48:49] offset:128
	s_add_u32 s48, s48, 0x8000
	s_addc_u32 s49, s49, 0
	global_load_dword v134, v162, s[48:49]
	global_load_dword v216, v162, s[48:49] offset:128
	global_load_dword v135, v163, s[48:49]
	global_load_dword v217, v163, s[48:49] offset:128
	global_load_dword v136, v164, s[48:49]
	global_load_dword v218, v164, s[48:49] offset:128
	global_load_dword v137, v165, s[48:49]
	global_load_dword v219, v165, s[48:49] offset:128
	s_add_u32 s48, s48, 0x8000
	s_addc_u32 s49, s49, 0
	global_load_dword v138, v162, s[48:49]
	global_load_dword v220, v162, s[48:49] offset:128
	global_load_dword v139, v163, s[48:49]
	global_load_dword v221, v163, s[48:49] offset:128
	global_load_dword v140, v164, s[48:49]
	global_load_dword v222, v164, s[48:49] offset:128
	global_load_dword v141, v165, s[48:49]
	global_load_dword v223, v165, s[48:49] offset:128
	s_add_u32 s48, s48, 0x8000
	s_addc_u32 s49, s49, 0
	global_load_dword v142, v162, s[48:49]
	global_load_dword v224, v162, s[48:49] offset:128
	global_load_dword v143, v163, s[48:49]
	global_load_dword v225, v163, s[48:49] offset:128
	global_load_dword v144, v164, s[48:49]
	global_load_dword v226, v164, s[48:49] offset:128
	global_load_dword v145, v165, s[48:49]
	global_load_dword v227, v165, s[48:49] offset:128
	s_sub_u32 s48, s48, 0x18000
	s_subb_u32 s49, s49, 0
	s_waitcnt vmcnt(30)
	v_fmac_f32_e32 v130, v34, v175
	v_fmac_f32_e32 v212, v50, v176
	global_store_dword v162, v130, s[48:49]
	global_store_dword v162, v212, s[48:49] offset:128
	s_waitcnt vmcnt(30)
	v_fmac_f32_e32 v131, v35, v175
	v_fmac_f32_e32 v213, v51, v176
	global_store_dword v163, v131, s[48:49]
	global_store_dword v163, v213, s[48:49] offset:128
	s_waitcnt vmcnt(30)
	v_fmac_f32_e32 v132, v36, v175
	v_fmac_f32_e32 v214, v52, v176
	global_store_dword v164, v132, s[48:49]
	global_store_dword v164, v214, s[48:49] offset:128
	s_waitcnt vmcnt(30)
	v_fmac_f32_e32 v133, v37, v175
	v_fmac_f32_e32 v215, v53, v176
	global_store_dword v165, v133, s[48:49]
	global_store_dword v165, v215, s[48:49] offset:128
	s_add_u32 s48, s48, 0x8000
	s_addc_u32 s49, s49, 0
	s_waitcnt vmcnt(30)
	v_fmac_f32_e32 v134, v38, v175
	v_fmac_f32_e32 v216, v54, v176
	global_store_dword v162, v134, s[48:49]
	global_store_dword v162, v216, s[48:49] offset:128
	s_waitcnt vmcnt(30)
	v_fmac_f32_e32 v135, v39, v175
	v_fmac_f32_e32 v217, v55, v176
	global_store_dword v163, v135, s[48:49]
	global_store_dword v163, v217, s[48:49] offset:128
	s_waitcnt vmcnt(30)
	v_fmac_f32_e32 v136, v40, v175
	v_fmac_f32_e32 v218, v56, v176
	global_store_dword v164, v136, s[48:49]
	global_store_dword v164, v218, s[48:49] offset:128
	s_waitcnt vmcnt(30)
	v_fmac_f32_e32 v137, v41, v175
	v_fmac_f32_e32 v219, v57, v176
	global_store_dword v165, v137, s[48:49]
	global_store_dword v165, v219, s[48:49] offset:128
	s_add_u32 s48, s48, 0x8000
	s_addc_u32 s49, s49, 0
	s_waitcnt vmcnt(30)
	v_fmac_f32_e32 v138, v42, v175
	v_fmac_f32_e32 v220, v58, v176
	global_store_dword v162, v138, s[48:49]
	global_store_dword v162, v220, s[48:49] offset:128
	s_waitcnt vmcnt(30)
	v_fmac_f32_e32 v139, v43, v175
	v_fmac_f32_e32 v221, v59, v176
	global_store_dword v163, v139, s[48:49]
	global_store_dword v163, v221, s[48:49] offset:128
	s_waitcnt vmcnt(30)
	v_fmac_f32_e32 v140, v44, v175
	v_fmac_f32_e32 v222, v60, v176
	global_store_dword v164, v140, s[48:49]
	global_store_dword v164, v222, s[48:49] offset:128
	s_waitcnt vmcnt(30)
	v_fmac_f32_e32 v141, v45, v175
	v_fmac_f32_e32 v223, v61, v176
	global_store_dword v165, v141, s[48:49]
	global_store_dword v165, v223, s[48:49] offset:128
	s_add_u32 s48, s48, 0x8000
	s_addc_u32 s49, s49, 0
	s_waitcnt vmcnt(30)
	v_fmac_f32_e32 v142, v46, v175
	v_fmac_f32_e32 v224, v62, v176
	global_store_dword v162, v142, s[48:49]
	global_store_dword v162, v224, s[48:49] offset:128
	s_waitcnt vmcnt(30)
	v_fmac_f32_e32 v143, v47, v175
	v_fmac_f32_e32 v225, v63, v176
	global_store_dword v163, v143, s[48:49]
	global_store_dword v163, v225, s[48:49] offset:128
	s_waitcnt vmcnt(30)
	v_fmac_f32_e32 v144, v48, v175
	v_fmac_f32_e32 v226, v64, v176
	global_store_dword v164, v144, s[48:49]
	global_store_dword v164, v226, s[48:49] offset:128
	s_waitcnt vmcnt(30)
	v_fmac_f32_e32 v145, v49, v175
	v_fmac_f32_e32 v227, v65, v176
	global_store_dword v165, v145, s[48:49]
	global_store_dword v165, v227, s[48:49] offset:128
	s_sub_u32 s48, s48, 0x18000
	s_subb_u32 s49, s49, 0
	v_mul_f32_e32 v130, v130, v130
	v_fmac_f32_e32 v130, v212, v212
	v_mul_f32_e32 v131, v131, v131
	v_fmac_f32_e32 v131, v213, v213
	v_mul_f32_e32 v132, v132, v132
	v_fmac_f32_e32 v132, v214, v214
	v_mul_f32_e32 v133, v133, v133
	v_fmac_f32_e32 v133, v215, v215
	v_mul_f32_e32 v134, v134, v134
	v_fmac_f32_e32 v134, v216, v216
	v_mul_f32_e32 v135, v135, v135
	v_fmac_f32_e32 v135, v217, v217
	v_mul_f32_e32 v136, v136, v136
	v_fmac_f32_e32 v136, v218, v218
	v_mul_f32_e32 v137, v137, v137
	v_fmac_f32_e32 v137, v219, v219
	v_mul_f32_e32 v138, v138, v138
	v_fmac_f32_e32 v138, v220, v220
	v_mul_f32_e32 v139, v139, v139
	v_fmac_f32_e32 v139, v221, v221
	v_mul_f32_e32 v140, v140, v140
	v_fmac_f32_e32 v140, v222, v222
	v_mul_f32_e32 v141, v141, v141
	v_fmac_f32_e32 v141, v223, v223
	v_mul_f32_e32 v142, v142, v142
	v_fmac_f32_e32 v142, v224, v224
	v_mul_f32_e32 v143, v143, v143
	v_fmac_f32_e32 v143, v225, v225
	v_mul_f32_e32 v144, v144, v144
	v_fmac_f32_e32 v144, v226, v226
	v_mul_f32_e32 v145, v145, v145
	v_fmac_f32_e32 v145, v227, v227
	s_waitcnt lgkmcnt(0)
	ds_bpermute_b32 v212, v168, v130
	ds_bpermute_b32 v213, v168, v131
	ds_bpermute_b32 v214, v168, v132
	ds_bpermute_b32 v215, v168, v133
	ds_bpermute_b32 v216, v168, v134
	ds_bpermute_b32 v217, v168, v135
	ds_bpermute_b32 v218, v168, v136
	ds_bpermute_b32 v219, v168, v137
	s_waitcnt lgkmcnt(7)
	v_add_f32_e32 v130, v130, v212
	s_waitcnt lgkmcnt(6)
	v_add_f32_e32 v131, v131, v213
	s_waitcnt lgkmcnt(5)
	v_add_f32_e32 v132, v132, v214
	s_waitcnt lgkmcnt(4)
	v_add_f32_e32 v133, v133, v215
	s_waitcnt lgkmcnt(3)
	v_add_f32_e32 v134, v134, v216
	s_waitcnt lgkmcnt(2)
	v_add_f32_e32 v135, v135, v217
	s_waitcnt lgkmcnt(1)
	v_add_f32_e32 v136, v136, v218
	s_waitcnt lgkmcnt(0)
	v_add_f32_e32 v137, v137, v219
	ds_bpermute_b32 v212, v169, v130
	ds_bpermute_b32 v213, v169, v131
	ds_bpermute_b32 v214, v169, v132
	ds_bpermute_b32 v215, v169, v133
	ds_bpermute_b32 v216, v169, v134
	ds_bpermute_b32 v217, v169, v135
	ds_bpermute_b32 v218, v169, v136
	ds_bpermute_b32 v219, v169, v137
	s_waitcnt lgkmcnt(7)
	v_add_f32_e32 v130, v130, v212
	s_waitcnt lgkmcnt(6)
	v_add_f32_e32 v131, v131, v213
	s_waitcnt lgkmcnt(5)
	v_add_f32_e32 v132, v132, v214
	s_waitcnt lgkmcnt(4)
	v_add_f32_e32 v133, v133, v215
	s_waitcnt lgkmcnt(3)
	v_add_f32_e32 v134, v134, v216
	s_waitcnt lgkmcnt(2)
	v_add_f32_e32 v135, v135, v217
	s_waitcnt lgkmcnt(1)
	v_add_f32_e32 v136, v136, v218
	s_waitcnt lgkmcnt(0)
	v_add_f32_e32 v137, v137, v219
	ds_bpermute_b32 v212, v171, v130
	ds_bpermute_b32 v213, v171, v131
	ds_bpermute_b32 v214, v171, v132
	ds_bpermute_b32 v215, v171, v133
	ds_bpermute_b32 v216, v171, v134
	ds_bpermute_b32 v217, v171, v135
	ds_bpermute_b32 v218, v171, v136
	ds_bpermute_b32 v219, v171, v137
	s_waitcnt lgkmcnt(7)
	v_add_f32_e32 v130, v130, v212
	s_waitcnt lgkmcnt(6)
	v_add_f32_e32 v131, v131, v213
	s_waitcnt lgkmcnt(5)
	v_add_f32_e32 v132, v132, v214
	s_waitcnt lgkmcnt(4)
	v_add_f32_e32 v133, v133, v215
	s_waitcnt lgkmcnt(3)
	v_add_f32_e32 v134, v134, v216
	s_waitcnt lgkmcnt(2)
	v_add_f32_e32 v135, v135, v217
	s_waitcnt lgkmcnt(1)
	v_add_f32_e32 v136, v136, v218
	s_waitcnt lgkmcnt(0)
	v_add_f32_e32 v137, v137, v219
	ds_bpermute_b32 v212, v172, v130
	ds_bpermute_b32 v213, v172, v131
	ds_bpermute_b32 v214, v172, v132
	ds_bpermute_b32 v215, v172, v133
	ds_bpermute_b32 v216, v172, v134
	ds_bpermute_b32 v217, v172, v135
	ds_bpermute_b32 v218, v172, v136
	ds_bpermute_b32 v219, v172, v137
	s_waitcnt lgkmcnt(7)
	v_add_f32_e32 v130, v130, v212
	s_waitcnt lgkmcnt(6)
	v_add_f32_e32 v131, v131, v213
	s_waitcnt lgkmcnt(5)
	v_add_f32_e32 v132, v132, v214
	s_waitcnt lgkmcnt(4)
	v_add_f32_e32 v133, v133, v215
	s_waitcnt lgkmcnt(3)
	v_add_f32_e32 v134, v134, v216
	s_waitcnt lgkmcnt(2)
	v_add_f32_e32 v135, v135, v217
	s_waitcnt lgkmcnt(1)
	v_add_f32_e32 v136, v136, v218
	s_waitcnt lgkmcnt(0)
	v_add_f32_e32 v137, v137, v219
	ds_bpermute_b32 v212, v173, v130
	ds_bpermute_b32 v213, v173, v131
	ds_bpermute_b32 v214, v173, v132
	ds_bpermute_b32 v215, v173, v133
	ds_bpermute_b32 v216, v173, v134
	ds_bpermute_b32 v217, v173, v135
	ds_bpermute_b32 v218, v173, v136
	ds_bpermute_b32 v219, v173, v137
	s_waitcnt lgkmcnt(7)
	v_add_f32_e32 v130, v130, v212
	s_waitcnt lgkmcnt(6)
	v_add_f32_e32 v131, v131, v213
	s_waitcnt lgkmcnt(5)
	v_add_f32_e32 v132, v132, v214
	s_waitcnt lgkmcnt(4)
	v_add_f32_e32 v133, v133, v215
	s_waitcnt lgkmcnt(3)
	v_add_f32_e32 v134, v134, v216
	s_waitcnt lgkmcnt(2)
	v_add_f32_e32 v135, v135, v217
	s_waitcnt lgkmcnt(1)
	v_add_f32_e32 v136, v136, v218
	s_waitcnt lgkmcnt(0)
	v_add_f32_e32 v137, v137, v219
	ds_bpermute_b32 v220, v168, v138
	ds_bpermute_b32 v221, v168, v139
	ds_bpermute_b32 v222, v168, v140
	ds_bpermute_b32 v223, v168, v141
	ds_bpermute_b32 v224, v168, v142
	ds_bpermute_b32 v225, v168, v143
	ds_bpermute_b32 v226, v168, v144
	ds_bpermute_b32 v227, v168, v145
	s_waitcnt lgkmcnt(7)
	v_add_f32_e32 v138, v138, v220
	s_waitcnt lgkmcnt(6)
	v_add_f32_e32 v139, v139, v221
	s_waitcnt lgkmcnt(5)
	v_add_f32_e32 v140, v140, v222
	s_waitcnt lgkmcnt(4)
	v_add_f32_e32 v141, v141, v223
	s_waitcnt lgkmcnt(3)
	v_add_f32_e32 v142, v142, v224
	s_waitcnt lgkmcnt(2)
	v_add_f32_e32 v143, v143, v225
	s_waitcnt lgkmcnt(1)
	v_add_f32_e32 v144, v144, v226
	s_waitcnt lgkmcnt(0)
	v_add_f32_e32 v145, v145, v227
	ds_bpermute_b32 v220, v169, v138
	ds_bpermute_b32 v221, v169, v139
	ds_bpermute_b32 v222, v169, v140
	ds_bpermute_b32 v223, v169, v141
	ds_bpermute_b32 v224, v169, v142
	ds_bpermute_b32 v225, v169, v143
	ds_bpermute_b32 v226, v169, v144
	ds_bpermute_b32 v227, v169, v145
	s_waitcnt lgkmcnt(7)
	v_add_f32_e32 v138, v138, v220
	s_waitcnt lgkmcnt(6)
	v_add_f32_e32 v139, v139, v221
	s_waitcnt lgkmcnt(5)
	v_add_f32_e32 v140, v140, v222
	s_waitcnt lgkmcnt(4)
	v_add_f32_e32 v141, v141, v223
	s_waitcnt lgkmcnt(3)
	v_add_f32_e32 v142, v142, v224
	s_waitcnt lgkmcnt(2)
	v_add_f32_e32 v143, v143, v225
	s_waitcnt lgkmcnt(1)
	v_add_f32_e32 v144, v144, v226
	s_waitcnt lgkmcnt(0)
	v_add_f32_e32 v145, v145, v227
	ds_bpermute_b32 v220, v171, v138
	ds_bpermute_b32 v221, v171, v139
	ds_bpermute_b32 v222, v171, v140
	ds_bpermute_b32 v223, v171, v141
	ds_bpermute_b32 v224, v171, v142
	ds_bpermute_b32 v225, v171, v143
	ds_bpermute_b32 v226, v171, v144
	ds_bpermute_b32 v227, v171, v145
	s_waitcnt lgkmcnt(7)
	v_add_f32_e32 v138, v138, v220
	s_waitcnt lgkmcnt(6)
	v_add_f32_e32 v139, v139, v221
	s_waitcnt lgkmcnt(5)
	v_add_f32_e32 v140, v140, v222
	s_waitcnt lgkmcnt(4)
	v_add_f32_e32 v141, v141, v223
	s_waitcnt lgkmcnt(3)
	v_add_f32_e32 v142, v142, v224
	s_waitcnt lgkmcnt(2)
	v_add_f32_e32 v143, v143, v225
	s_waitcnt lgkmcnt(1)
	v_add_f32_e32 v144, v144, v226
	s_waitcnt lgkmcnt(0)
	v_add_f32_e32 v145, v145, v227
	ds_bpermute_b32 v220, v172, v138
	ds_bpermute_b32 v221, v172, v139
	ds_bpermute_b32 v222, v172, v140
	ds_bpermute_b32 v223, v172, v141
	ds_bpermute_b32 v224, v172, v142
	ds_bpermute_b32 v225, v172, v143
	ds_bpermute_b32 v226, v172, v144
	ds_bpermute_b32 v227, v172, v145
	s_waitcnt lgkmcnt(7)
	v_add_f32_e32 v138, v138, v220
	s_waitcnt lgkmcnt(6)
	v_add_f32_e32 v139, v139, v221
	s_waitcnt lgkmcnt(5)
	v_add_f32_e32 v140, v140, v222
	s_waitcnt lgkmcnt(4)
	v_add_f32_e32 v141, v141, v223
	s_waitcnt lgkmcnt(3)
	v_add_f32_e32 v142, v142, v224
	s_waitcnt lgkmcnt(2)
	v_add_f32_e32 v143, v143, v225
	s_waitcnt lgkmcnt(1)
	v_add_f32_e32 v144, v144, v226
	s_waitcnt lgkmcnt(0)
	v_add_f32_e32 v145, v145, v227
	ds_bpermute_b32 v220, v173, v138
	ds_bpermute_b32 v221, v173, v139
	ds_bpermute_b32 v222, v173, v140
	ds_bpermute_b32 v223, v173, v141
	ds_bpermute_b32 v224, v173, v142
	ds_bpermute_b32 v225, v173, v143
	ds_bpermute_b32 v226, v173, v144
	ds_bpermute_b32 v227, v173, v145
	s_waitcnt lgkmcnt(7)
	v_add_f32_e32 v138, v138, v220
	s_waitcnt lgkmcnt(6)
	v_add_f32_e32 v139, v139, v221
	s_waitcnt lgkmcnt(5)
	v_add_f32_e32 v140, v140, v222
	s_waitcnt lgkmcnt(4)
	v_add_f32_e32 v141, v141, v223
	s_waitcnt lgkmcnt(3)
	v_add_f32_e32 v142, v142, v224
	s_waitcnt lgkmcnt(2)
	v_add_f32_e32 v143, v143, v225
	s_waitcnt lgkmcnt(1)
	v_add_f32_e32 v144, v144, v226
	s_waitcnt lgkmcnt(0)
	v_add_f32_e32 v145, v145, v227
	v_cmp_eq_u32_e32 vcc, 0, v174
	s_and_saveexec_b64 s[58:59], vcc
	global_store_dword v167, v130, s[10:11] offset:128
	global_store_dword v167, v131, s[10:11] offset:132
	global_store_dword v167, v132, s[10:11] offset:136
	global_store_dword v167, v133, s[10:11] offset:140
	global_store_dword v167, v134, s[10:11] offset:160
	global_store_dword v167, v135, s[10:11] offset:164
	global_store_dword v167, v136, s[10:11] offset:168
	global_store_dword v167, v137, s[10:11] offset:172
	global_store_dword v167, v138, s[10:11] offset:192
	global_store_dword v167, v139, s[10:11] offset:196
	global_store_dword v167, v140, s[10:11] offset:200
	global_store_dword v167, v141, s[10:11] offset:204
	global_store_dword v167, v142, s[10:11] offset:224
	global_store_dword v167, v143, s[10:11] offset:228
	global_store_dword v167, v144, s[10:11] offset:232
	global_store_dword v167, v145, s[10:11] offset:236
	s_mov_b64 exec, -1
	s_sub_u32 s48, s48, 0x20000
	s_subb_u32 s49, s49, 0
	s_add_u32 s60, s60, 0x200
	s_addc_u32 s61, s61, 0
	s_add_u32 s10, s10, 0x18000
	s_addc_u32 s11, s11, 0
	s_add_u32 s48, s48, 0x200
	s_addc_u32 s49, s49, 0
	global_load_dword v175, v166, s[60:61]
	global_load_dword v176, v166, s[60:61] offset:128
	global_load_dword v130, v162, s[48:49]
	global_load_dword v212, v162, s[48:49] offset:128
	global_load_dword v131, v163, s[48:49]
	global_load_dword v213, v163, s[48:49] offset:128
	global_load_dword v132, v164, s[48:49]
	global_load_dword v214, v164, s[48:49] offset:128
	global_load_dword v133, v165, s[48:49]
	global_load_dword v215, v165, s[48:49] offset:128
	s_add_u32 s48, s48, 0x8000
	s_addc_u32 s49, s49, 0
	global_load_dword v134, v162, s[48:49]
	global_load_dword v216, v162, s[48:49] offset:128
	global_load_dword v135, v163, s[48:49]
	global_load_dword v217, v163, s[48:49] offset:128
	global_load_dword v136, v164, s[48:49]
	global_load_dword v218, v164, s[48:49] offset:128
	global_load_dword v137, v165, s[48:49]
	global_load_dword v219, v165, s[48:49] offset:128
	s_add_u32 s48, s48, 0x8000
	s_addc_u32 s49, s49, 0
	global_load_dword v138, v162, s[48:49]
	global_load_dword v220, v162, s[48:49] offset:128
	global_load_dword v139, v163, s[48:49]
	global_load_dword v221, v163, s[48:49] offset:128
	global_load_dword v140, v164, s[48:49]
	global_load_dword v222, v164, s[48:49] offset:128
	global_load_dword v141, v165, s[48:49]
	global_load_dword v223, v165, s[48:49] offset:128
	s_add_u32 s48, s48, 0x8000
	s_addc_u32 s49, s49, 0
	global_load_dword v142, v162, s[48:49]
	global_load_dword v224, v162, s[48:49] offset:128
	global_load_dword v143, v163, s[48:49]
	global_load_dword v225, v163, s[48:49] offset:128
	global_load_dword v144, v164, s[48:49]
	global_load_dword v226, v164, s[48:49] offset:128
	global_load_dword v145, v165, s[48:49]
	global_load_dword v227, v165, s[48:49] offset:128
	s_sub_u32 s48, s48, 0x18000
	s_subb_u32 s49, s49, 0
	s_waitcnt vmcnt(32)
	v_mul_f32_e32 v175, 0.5, v175
	v_mul_f32_e32 v176, 0.5, v176
	s_waitcnt vmcnt(30)
	v_fmac_f32_e32 v130, v66, v175
	v_fmac_f32_e32 v212, v82, v176
	global_store_dword v162, v130, s[48:49]
	global_store_dword v162, v212, s[48:49] offset:128
	s_waitcnt vmcnt(30)
	v_fmac_f32_e32 v131, v67, v175
	v_fmac_f32_e32 v213, v83, v176
	global_store_dword v163, v131, s[48:49]
	global_store_dword v163, v213, s[48:49] offset:128
	s_waitcnt vmcnt(30)
	v_fmac_f32_e32 v132, v68, v175
	v_fmac_f32_e32 v214, v84, v176
	global_store_dword v164, v132, s[48:49]
	global_store_dword v164, v214, s[48:49] offset:128
	s_waitcnt vmcnt(30)
	v_fmac_f32_e32 v133, v69, v175
	v_fmac_f32_e32 v215, v85, v176
	global_store_dword v165, v133, s[48:49]
	global_store_dword v165, v215, s[48:49] offset:128
	s_add_u32 s48, s48, 0x8000
	s_addc_u32 s49, s49, 0
	s_waitcnt vmcnt(30)
	v_fmac_f32_e32 v134, v70, v175
	v_fmac_f32_e32 v216, v86, v176
	global_store_dword v162, v134, s[48:49]
	global_store_dword v162, v216, s[48:49] offset:128
	s_waitcnt vmcnt(30)
	v_fmac_f32_e32 v135, v71, v175
	v_fmac_f32_e32 v217, v87, v176
	global_store_dword v163, v135, s[48:49]
	global_store_dword v163, v217, s[48:49] offset:128
	s_waitcnt vmcnt(30)
	v_fmac_f32_e32 v136, v72, v175
	v_fmac_f32_e32 v218, v88, v176
	global_store_dword v164, v136, s[48:49]
	global_store_dword v164, v218, s[48:49] offset:128
	s_waitcnt vmcnt(30)
	v_fmac_f32_e32 v137, v73, v175
	v_fmac_f32_e32 v219, v89, v176
	global_store_dword v165, v137, s[48:49]
	global_store_dword v165, v219, s[48:49] offset:128
	s_add_u32 s48, s48, 0x8000
	s_addc_u32 s49, s49, 0
	s_waitcnt vmcnt(30)
	v_fmac_f32_e32 v138, v74, v175
	v_fmac_f32_e32 v220, v90, v176
	global_store_dword v162, v138, s[48:49]
	global_store_dword v162, v220, s[48:49] offset:128
	s_waitcnt vmcnt(30)
	v_fmac_f32_e32 v139, v75, v175
	v_fmac_f32_e32 v221, v91, v176
	global_store_dword v163, v139, s[48:49]
	global_store_dword v163, v221, s[48:49] offset:128
	s_waitcnt vmcnt(30)
	v_fmac_f32_e32 v140, v76, v175
	v_fmac_f32_e32 v222, v92, v176
	global_store_dword v164, v140, s[48:49]
	global_store_dword v164, v222, s[48:49] offset:128
	s_waitcnt vmcnt(30)
	v_fmac_f32_e32 v141, v77, v175
	v_fmac_f32_e32 v223, v93, v176
	global_store_dword v165, v141, s[48:49]
	global_store_dword v165, v223, s[48:49] offset:128
	s_add_u32 s48, s48, 0x8000
	s_addc_u32 s49, s49, 0
	s_waitcnt vmcnt(30)
	v_fmac_f32_e32 v142, v78, v175
	v_fmac_f32_e32 v224, v94, v176
	global_store_dword v162, v142, s[48:49]
	global_store_dword v162, v224, s[48:49] offset:128
	s_waitcnt vmcnt(30)
	v_fmac_f32_e32 v143, v79, v175
	v_fmac_f32_e32 v225, v95, v176
	global_store_dword v163, v143, s[48:49]
	global_store_dword v163, v225, s[48:49] offset:128
	s_waitcnt vmcnt(30)
	v_fmac_f32_e32 v144, v80, v175
	v_fmac_f32_e32 v226, v96, v176
	global_store_dword v164, v144, s[48:49]
	global_store_dword v164, v226, s[48:49] offset:128
	s_waitcnt vmcnt(30)
	v_fmac_f32_e32 v145, v81, v175
	v_fmac_f32_e32 v227, v97, v176
	global_store_dword v165, v145, s[48:49]
	global_store_dword v165, v227, s[48:49] offset:128
	s_sub_u32 s48, s48, 0x18000
	s_subb_u32 s49, s49, 0
	v_mul_f32_e32 v130, v130, v130
	v_fmac_f32_e32 v130, v212, v212
	v_mul_f32_e32 v131, v131, v131
	v_fmac_f32_e32 v131, v213, v213
	v_mul_f32_e32 v132, v132, v132
	v_fmac_f32_e32 v132, v214, v214
	v_mul_f32_e32 v133, v133, v133
	v_fmac_f32_e32 v133, v215, v215
	v_mul_f32_e32 v134, v134, v134
	v_fmac_f32_e32 v134, v216, v216
	v_mul_f32_e32 v135, v135, v135
	v_fmac_f32_e32 v135, v217, v217
	v_mul_f32_e32 v136, v136, v136
	v_fmac_f32_e32 v136, v218, v218
	v_mul_f32_e32 v137, v137, v137
	v_fmac_f32_e32 v137, v219, v219
	v_mul_f32_e32 v138, v138, v138
	v_fmac_f32_e32 v138, v220, v220
	v_mul_f32_e32 v139, v139, v139
	v_fmac_f32_e32 v139, v221, v221
	v_mul_f32_e32 v140, v140, v140
	v_fmac_f32_e32 v140, v222, v222
	v_mul_f32_e32 v141, v141, v141
	v_fmac_f32_e32 v141, v223, v223
	v_mul_f32_e32 v142, v142, v142
	v_fmac_f32_e32 v142, v224, v224
	v_mul_f32_e32 v143, v143, v143
	v_fmac_f32_e32 v143, v225, v225
	v_mul_f32_e32 v144, v144, v144
	v_fmac_f32_e32 v144, v226, v226
	v_mul_f32_e32 v145, v145, v145
	v_fmac_f32_e32 v145, v227, v227
	s_waitcnt lgkmcnt(0)
	ds_bpermute_b32 v212, v168, v130
	ds_bpermute_b32 v213, v168, v131
	ds_bpermute_b32 v214, v168, v132
	ds_bpermute_b32 v215, v168, v133
	ds_bpermute_b32 v216, v168, v134
	ds_bpermute_b32 v217, v168, v135
	ds_bpermute_b32 v218, v168, v136
	ds_bpermute_b32 v219, v168, v137
	s_waitcnt lgkmcnt(7)
	v_add_f32_e32 v130, v130, v212
	s_waitcnt lgkmcnt(6)
	v_add_f32_e32 v131, v131, v213
	s_waitcnt lgkmcnt(5)
	v_add_f32_e32 v132, v132, v214
	s_waitcnt lgkmcnt(4)
	v_add_f32_e32 v133, v133, v215
	s_waitcnt lgkmcnt(3)
	v_add_f32_e32 v134, v134, v216
	s_waitcnt lgkmcnt(2)
	v_add_f32_e32 v135, v135, v217
	s_waitcnt lgkmcnt(1)
	v_add_f32_e32 v136, v136, v218
	s_waitcnt lgkmcnt(0)
	v_add_f32_e32 v137, v137, v219
	ds_bpermute_b32 v212, v169, v130
	ds_bpermute_b32 v213, v169, v131
	ds_bpermute_b32 v214, v169, v132
	ds_bpermute_b32 v215, v169, v133
	ds_bpermute_b32 v216, v169, v134
	ds_bpermute_b32 v217, v169, v135
	ds_bpermute_b32 v218, v169, v136
	ds_bpermute_b32 v219, v169, v137
	s_waitcnt lgkmcnt(7)
	v_add_f32_e32 v130, v130, v212
	s_waitcnt lgkmcnt(6)
	v_add_f32_e32 v131, v131, v213
	s_waitcnt lgkmcnt(5)
	v_add_f32_e32 v132, v132, v214
	s_waitcnt lgkmcnt(4)
	v_add_f32_e32 v133, v133, v215
	s_waitcnt lgkmcnt(3)
	v_add_f32_e32 v134, v134, v216
	s_waitcnt lgkmcnt(2)
	v_add_f32_e32 v135, v135, v217
	s_waitcnt lgkmcnt(1)
	v_add_f32_e32 v136, v136, v218
	s_waitcnt lgkmcnt(0)
	v_add_f32_e32 v137, v137, v219
	ds_bpermute_b32 v212, v171, v130
	ds_bpermute_b32 v213, v171, v131
	ds_bpermute_b32 v214, v171, v132
	ds_bpermute_b32 v215, v171, v133
	ds_bpermute_b32 v216, v171, v134
	ds_bpermute_b32 v217, v171, v135
	ds_bpermute_b32 v218, v171, v136
	ds_bpermute_b32 v219, v171, v137
	s_waitcnt lgkmcnt(7)
	v_add_f32_e32 v130, v130, v212
	s_waitcnt lgkmcnt(6)
	v_add_f32_e32 v131, v131, v213
	s_waitcnt lgkmcnt(5)
	v_add_f32_e32 v132, v132, v214
	s_waitcnt lgkmcnt(4)
	v_add_f32_e32 v133, v133, v215
	s_waitcnt lgkmcnt(3)
	v_add_f32_e32 v134, v134, v216
	s_waitcnt lgkmcnt(2)
	v_add_f32_e32 v135, v135, v217
	s_waitcnt lgkmcnt(1)
	v_add_f32_e32 v136, v136, v218
	s_waitcnt lgkmcnt(0)
	v_add_f32_e32 v137, v137, v219
	ds_bpermute_b32 v212, v172, v130
	ds_bpermute_b32 v213, v172, v131
	ds_bpermute_b32 v214, v172, v132
	ds_bpermute_b32 v215, v172, v133
	ds_bpermute_b32 v216, v172, v134
	ds_bpermute_b32 v217, v172, v135
	ds_bpermute_b32 v218, v172, v136
	ds_bpermute_b32 v219, v172, v137
	s_waitcnt lgkmcnt(7)
	v_add_f32_e32 v130, v130, v212
	s_waitcnt lgkmcnt(6)
	v_add_f32_e32 v131, v131, v213
	s_waitcnt lgkmcnt(5)
	v_add_f32_e32 v132, v132, v214
	s_waitcnt lgkmcnt(4)
	v_add_f32_e32 v133, v133, v215
	s_waitcnt lgkmcnt(3)
	v_add_f32_e32 v134, v134, v216
	s_waitcnt lgkmcnt(2)
	v_add_f32_e32 v135, v135, v217
	s_waitcnt lgkmcnt(1)
	v_add_f32_e32 v136, v136, v218
	s_waitcnt lgkmcnt(0)
	v_add_f32_e32 v137, v137, v219
	ds_bpermute_b32 v212, v173, v130
	ds_bpermute_b32 v213, v173, v131
	ds_bpermute_b32 v214, v173, v132
	ds_bpermute_b32 v215, v173, v133
	ds_bpermute_b32 v216, v173, v134
	ds_bpermute_b32 v217, v173, v135
	ds_bpermute_b32 v218, v173, v136
	ds_bpermute_b32 v219, v173, v137
	s_waitcnt lgkmcnt(7)
	v_add_f32_e32 v130, v130, v212
	s_waitcnt lgkmcnt(6)
	v_add_f32_e32 v131, v131, v213
	s_waitcnt lgkmcnt(5)
	v_add_f32_e32 v132, v132, v214
	s_waitcnt lgkmcnt(4)
	v_add_f32_e32 v133, v133, v215
	s_waitcnt lgkmcnt(3)
	v_add_f32_e32 v134, v134, v216
	s_waitcnt lgkmcnt(2)
	v_add_f32_e32 v135, v135, v217
	s_waitcnt lgkmcnt(1)
	v_add_f32_e32 v136, v136, v218
	s_waitcnt lgkmcnt(0)
	v_add_f32_e32 v137, v137, v219
	ds_bpermute_b32 v220, v168, v138
	ds_bpermute_b32 v221, v168, v139
	ds_bpermute_b32 v222, v168, v140
	ds_bpermute_b32 v223, v168, v141
	ds_bpermute_b32 v224, v168, v142
	ds_bpermute_b32 v225, v168, v143
	ds_bpermute_b32 v226, v168, v144
	ds_bpermute_b32 v227, v168, v145
	s_waitcnt lgkmcnt(7)
	v_add_f32_e32 v138, v138, v220
	s_waitcnt lgkmcnt(6)
	v_add_f32_e32 v139, v139, v221
	s_waitcnt lgkmcnt(5)
	v_add_f32_e32 v140, v140, v222
	s_waitcnt lgkmcnt(4)
	v_add_f32_e32 v141, v141, v223
	s_waitcnt lgkmcnt(3)
	v_add_f32_e32 v142, v142, v224
	s_waitcnt lgkmcnt(2)
	v_add_f32_e32 v143, v143, v225
	s_waitcnt lgkmcnt(1)
	v_add_f32_e32 v144, v144, v226
	s_waitcnt lgkmcnt(0)
	v_add_f32_e32 v145, v145, v227
	ds_bpermute_b32 v220, v169, v138
	ds_bpermute_b32 v221, v169, v139
	ds_bpermute_b32 v222, v169, v140
	ds_bpermute_b32 v223, v169, v141
	ds_bpermute_b32 v224, v169, v142
	ds_bpermute_b32 v225, v169, v143
	ds_bpermute_b32 v226, v169, v144
	ds_bpermute_b32 v227, v169, v145
	s_waitcnt lgkmcnt(7)
	v_add_f32_e32 v138, v138, v220
	s_waitcnt lgkmcnt(6)
	v_add_f32_e32 v139, v139, v221
	s_waitcnt lgkmcnt(5)
	v_add_f32_e32 v140, v140, v222
	s_waitcnt lgkmcnt(4)
	v_add_f32_e32 v141, v141, v223
	s_waitcnt lgkmcnt(3)
	v_add_f32_e32 v142, v142, v224
	s_waitcnt lgkmcnt(2)
	v_add_f32_e32 v143, v143, v225
	s_waitcnt lgkmcnt(1)
	v_add_f32_e32 v144, v144, v226
	s_waitcnt lgkmcnt(0)
	v_add_f32_e32 v145, v145, v227
	ds_bpermute_b32 v220, v171, v138
	ds_bpermute_b32 v221, v171, v139
	ds_bpermute_b32 v222, v171, v140
	ds_bpermute_b32 v223, v171, v141
	ds_bpermute_b32 v224, v171, v142
	ds_bpermute_b32 v225, v171, v143
	ds_bpermute_b32 v226, v171, v144
	ds_bpermute_b32 v227, v171, v145
	s_waitcnt lgkmcnt(7)
	v_add_f32_e32 v138, v138, v220
	s_waitcnt lgkmcnt(6)
	v_add_f32_e32 v139, v139, v221
	s_waitcnt lgkmcnt(5)
	v_add_f32_e32 v140, v140, v222
	s_waitcnt lgkmcnt(4)
	v_add_f32_e32 v141, v141, v223
	s_waitcnt lgkmcnt(3)
	v_add_f32_e32 v142, v142, v224
	s_waitcnt lgkmcnt(2)
	v_add_f32_e32 v143, v143, v225
	s_waitcnt lgkmcnt(1)
	v_add_f32_e32 v144, v144, v226
	s_waitcnt lgkmcnt(0)
	v_add_f32_e32 v145, v145, v227
	ds_bpermute_b32 v220, v172, v138
	ds_bpermute_b32 v221, v172, v139
	ds_bpermute_b32 v222, v172, v140
	ds_bpermute_b32 v223, v172, v141
	ds_bpermute_b32 v224, v172, v142
	ds_bpermute_b32 v225, v172, v143
	ds_bpermute_b32 v226, v172, v144
	ds_bpermute_b32 v227, v172, v145
	s_waitcnt lgkmcnt(7)
	v_add_f32_e32 v138, v138, v220
	s_waitcnt lgkmcnt(6)
	v_add_f32_e32 v139, v139, v221
	s_waitcnt lgkmcnt(5)
	v_add_f32_e32 v140, v140, v222
	s_waitcnt lgkmcnt(4)
	v_add_f32_e32 v141, v141, v223
	s_waitcnt lgkmcnt(3)
	v_add_f32_e32 v142, v142, v224
	s_waitcnt lgkmcnt(2)
	v_add_f32_e32 v143, v143, v225
	s_waitcnt lgkmcnt(1)
	v_add_f32_e32 v144, v144, v226
	s_waitcnt lgkmcnt(0)
	v_add_f32_e32 v145, v145, v227
	ds_bpermute_b32 v220, v173, v138
	ds_bpermute_b32 v221, v173, v139
	ds_bpermute_b32 v222, v173, v140
	ds_bpermute_b32 v223, v173, v141
	ds_bpermute_b32 v224, v173, v142
	ds_bpermute_b32 v225, v173, v143
	ds_bpermute_b32 v226, v173, v144
	ds_bpermute_b32 v227, v173, v145
	s_waitcnt lgkmcnt(7)
	v_add_f32_e32 v138, v138, v220
	s_waitcnt lgkmcnt(6)
	v_add_f32_e32 v139, v139, v221
	s_waitcnt lgkmcnt(5)
	v_add_f32_e32 v140, v140, v222
	s_waitcnt lgkmcnt(4)
	v_add_f32_e32 v141, v141, v223
	s_waitcnt lgkmcnt(3)
	v_add_f32_e32 v142, v142, v224
	s_waitcnt lgkmcnt(2)
	v_add_f32_e32 v143, v143, v225
	s_waitcnt lgkmcnt(1)
	v_add_f32_e32 v144, v144, v226
	s_waitcnt lgkmcnt(0)
	v_add_f32_e32 v145, v145, v227
	v_cmp_eq_u32_e32 vcc, 0, v174
	s_and_saveexec_b64 s[58:59], vcc
	global_store_dword v167, v130, s[10:11]
	global_store_dword v167, v131, s[10:11] offset:4
	global_store_dword v167, v132, s[10:11] offset:8
	global_store_dword v167, v133, s[10:11] offset:12
	global_store_dword v167, v134, s[10:11] offset:32
	global_store_dword v167, v135, s[10:11] offset:36
	global_store_dword v167, v136, s[10:11] offset:40
	global_store_dword v167, v137, s[10:11] offset:44
	global_store_dword v167, v138, s[10:11] offset:64
	global_store_dword v167, v139, s[10:11] offset:68
	global_store_dword v167, v140, s[10:11] offset:72
	global_store_dword v167, v141, s[10:11] offset:76
	global_store_dword v167, v142, s[10:11] offset:96
	global_store_dword v167, v143, s[10:11] offset:100
	global_store_dword v167, v144, s[10:11] offset:104
	global_store_dword v167, v145, s[10:11] offset:108
	s_mov_b64 exec, -1
	s_add_u32 s48, s48, 0x20000
	s_addc_u32 s49, s49, 0
	global_load_dword v130, v162, s[48:49]
	global_load_dword v212, v162, s[48:49] offset:128
	global_load_dword v131, v163, s[48:49]
	global_load_dword v213, v163, s[48:49] offset:128
	global_load_dword v132, v164, s[48:49]
	global_load_dword v214, v164, s[48:49] offset:128
	global_load_dword v133, v165, s[48:49]
	global_load_dword v215, v165, s[48:49] offset:128
	s_add_u32 s48, s48, 0x8000
	s_addc_u32 s49, s49, 0
	global_load_dword v134, v162, s[48:49]
	global_load_dword v216, v162, s[48:49] offset:128
	global_load_dword v135, v163, s[48:49]
	global_load_dword v217, v163, s[48:49] offset:128
	global_load_dword v136, v164, s[48:49]
	global_load_dword v218, v164, s[48:49] offset:128
	global_load_dword v137, v165, s[48:49]
	global_load_dword v219, v165, s[48:49] offset:128
	s_add_u32 s48, s48, 0x8000
	s_addc_u32 s49, s49, 0
	global_load_dword v138, v162, s[48:49]
	global_load_dword v220, v162, s[48:49] offset:128
	global_load_dword v139, v163, s[48:49]
	global_load_dword v221, v163, s[48:49] offset:128
	global_load_dword v140, v164, s[48:49]
	global_load_dword v222, v164, s[48:49] offset:128
	global_load_dword v141, v165, s[48:49]
	global_load_dword v223, v165, s[48:49] offset:128
	s_add_u32 s48, s48, 0x8000
	s_addc_u32 s49, s49, 0
	global_load_dword v142, v162, s[48:49]
	global_load_dword v224, v162, s[48:49] offset:128
	global_load_dword v143, v163, s[48:49]
	global_load_dword v225, v163, s[48:49] offset:128
	global_load_dword v144, v164, s[48:49]
	global_load_dword v226, v164, s[48:49] offset:128
	global_load_dword v145, v165, s[48:49]
	global_load_dword v227, v165, s[48:49] offset:128
	s_sub_u32 s48, s48, 0x18000
	s_subb_u32 s49, s49, 0
	s_waitcnt vmcnt(30)
	v_fmac_f32_e32 v130, v98, v175
	v_fmac_f32_e32 v212, v114, v176
	global_store_dword v162, v130, s[48:49]
	global_store_dword v162, v212, s[48:49] offset:128
	s_waitcnt vmcnt(30)
	v_fmac_f32_e32 v131, v99, v175
	v_fmac_f32_e32 v213, v115, v176
	global_store_dword v163, v131, s[48:49]
	global_store_dword v163, v213, s[48:49] offset:128
	s_waitcnt vmcnt(30)
	v_fmac_f32_e32 v132, v100, v175
	v_fmac_f32_e32 v214, v116, v176
	global_store_dword v164, v132, s[48:49]
	global_store_dword v164, v214, s[48:49] offset:128
	s_waitcnt vmcnt(30)
	v_fmac_f32_e32 v133, v101, v175
	v_fmac_f32_e32 v215, v117, v176
	global_store_dword v165, v133, s[48:49]
	global_store_dword v165, v215, s[48:49] offset:128
	s_add_u32 s48, s48, 0x8000
	s_addc_u32 s49, s49, 0
	s_waitcnt vmcnt(30)
	v_fmac_f32_e32 v134, v102, v175
	v_fmac_f32_e32 v216, v118, v176
	global_store_dword v162, v134, s[48:49]
	global_store_dword v162, v216, s[48:49] offset:128
	s_waitcnt vmcnt(30)
	v_fmac_f32_e32 v135, v103, v175
	v_fmac_f32_e32 v217, v119, v176
	global_store_dword v163, v135, s[48:49]
	global_store_dword v163, v217, s[48:49] offset:128
	s_waitcnt vmcnt(30)
	v_fmac_f32_e32 v136, v104, v175
	v_fmac_f32_e32 v218, v120, v176
	global_store_dword v164, v136, s[48:49]
	global_store_dword v164, v218, s[48:49] offset:128
	s_waitcnt vmcnt(30)
	v_fmac_f32_e32 v137, v105, v175
	v_fmac_f32_e32 v219, v121, v176
	global_store_dword v165, v137, s[48:49]
	global_store_dword v165, v219, s[48:49] offset:128
	s_add_u32 s48, s48, 0x8000
	s_addc_u32 s49, s49, 0
	s_waitcnt vmcnt(30)
	v_fmac_f32_e32 v138, v106, v175
	v_fmac_f32_e32 v220, v122, v176
	global_store_dword v162, v138, s[48:49]
	global_store_dword v162, v220, s[48:49] offset:128
	s_waitcnt vmcnt(30)
	v_fmac_f32_e32 v139, v107, v175
	v_fmac_f32_e32 v221, v123, v176
	global_store_dword v163, v139, s[48:49]
	global_store_dword v163, v221, s[48:49] offset:128
	s_waitcnt vmcnt(30)
	v_fmac_f32_e32 v140, v108, v175
	v_fmac_f32_e32 v222, v124, v176
	global_store_dword v164, v140, s[48:49]
	global_store_dword v164, v222, s[48:49] offset:128
	s_waitcnt vmcnt(30)
	v_fmac_f32_e32 v141, v109, v175
	v_fmac_f32_e32 v223, v125, v176
	global_store_dword v165, v141, s[48:49]
	global_store_dword v165, v223, s[48:49] offset:128
	s_add_u32 s48, s48, 0x8000
	s_addc_u32 s49, s49, 0
	s_waitcnt vmcnt(30)
	v_fmac_f32_e32 v142, v110, v175
	v_fmac_f32_e32 v224, v126, v176
	global_store_dword v162, v142, s[48:49]
	global_store_dword v162, v224, s[48:49] offset:128
	s_waitcnt vmcnt(30)
	v_fmac_f32_e32 v143, v111, v175
	v_fmac_f32_e32 v225, v127, v176
	global_store_dword v163, v143, s[48:49]
	global_store_dword v163, v225, s[48:49] offset:128
	s_waitcnt vmcnt(30)
	v_fmac_f32_e32 v144, v112, v175
	v_fmac_f32_e32 v226, v128, v176
	global_store_dword v164, v144, s[48:49]
	global_store_dword v164, v226, s[48:49] offset:128
	s_waitcnt vmcnt(30)
	v_fmac_f32_e32 v145, v113, v175
	v_fmac_f32_e32 v227, v129, v176
	global_store_dword v165, v145, s[48:49]
	global_store_dword v165, v227, s[48:49] offset:128
	s_sub_u32 s48, s48, 0x18000
	s_subb_u32 s49, s49, 0
	v_mul_f32_e32 v130, v130, v130
	v_fmac_f32_e32 v130, v212, v212
	v_mul_f32_e32 v131, v131, v131
	v_fmac_f32_e32 v131, v213, v213
	v_mul_f32_e32 v132, v132, v132
	v_fmac_f32_e32 v132, v214, v214
	v_mul_f32_e32 v133, v133, v133
	v_fmac_f32_e32 v133, v215, v215
	v_mul_f32_e32 v134, v134, v134
	v_fmac_f32_e32 v134, v216, v216
	v_mul_f32_e32 v135, v135, v135
	v_fmac_f32_e32 v135, v217, v217
	v_mul_f32_e32 v136, v136, v136
	v_fmac_f32_e32 v136, v218, v218
	v_mul_f32_e32 v137, v137, v137
	v_fmac_f32_e32 v137, v219, v219
	v_mul_f32_e32 v138, v138, v138
	v_fmac_f32_e32 v138, v220, v220
	v_mul_f32_e32 v139, v139, v139
	v_fmac_f32_e32 v139, v221, v221
	v_mul_f32_e32 v140, v140, v140
	v_fmac_f32_e32 v140, v222, v222
	v_mul_f32_e32 v141, v141, v141
	v_fmac_f32_e32 v141, v223, v223
	v_mul_f32_e32 v142, v142, v142
	v_fmac_f32_e32 v142, v224, v224
	v_mul_f32_e32 v143, v143, v143
	v_fmac_f32_e32 v143, v225, v225
	v_mul_f32_e32 v144, v144, v144
	v_fmac_f32_e32 v144, v226, v226
	v_mul_f32_e32 v145, v145, v145
	v_fmac_f32_e32 v145, v227, v227
	s_waitcnt lgkmcnt(0)
	ds_bpermute_b32 v212, v168, v130
	ds_bpermute_b32 v213, v168, v131
	ds_bpermute_b32 v214, v168, v132
	ds_bpermute_b32 v215, v168, v133
	ds_bpermute_b32 v216, v168, v134
	ds_bpermute_b32 v217, v168, v135
	ds_bpermute_b32 v218, v168, v136
	ds_bpermute_b32 v219, v168, v137
	s_waitcnt lgkmcnt(7)
	v_add_f32_e32 v130, v130, v212
	s_waitcnt lgkmcnt(6)
	v_add_f32_e32 v131, v131, v213
	s_waitcnt lgkmcnt(5)
	v_add_f32_e32 v132, v132, v214
	s_waitcnt lgkmcnt(4)
	v_add_f32_e32 v133, v133, v215
	s_waitcnt lgkmcnt(3)
	v_add_f32_e32 v134, v134, v216
	s_waitcnt lgkmcnt(2)
	v_add_f32_e32 v135, v135, v217
	s_waitcnt lgkmcnt(1)
	v_add_f32_e32 v136, v136, v218
	s_waitcnt lgkmcnt(0)
	v_add_f32_e32 v137, v137, v219
	ds_bpermute_b32 v212, v169, v130
	ds_bpermute_b32 v213, v169, v131
	ds_bpermute_b32 v214, v169, v132
	ds_bpermute_b32 v215, v169, v133
	ds_bpermute_b32 v216, v169, v134
	ds_bpermute_b32 v217, v169, v135
	ds_bpermute_b32 v218, v169, v136
	ds_bpermute_b32 v219, v169, v137
	s_waitcnt lgkmcnt(7)
	v_add_f32_e32 v130, v130, v212
	s_waitcnt lgkmcnt(6)
	v_add_f32_e32 v131, v131, v213
	s_waitcnt lgkmcnt(5)
	v_add_f32_e32 v132, v132, v214
	s_waitcnt lgkmcnt(4)
	v_add_f32_e32 v133, v133, v215
	s_waitcnt lgkmcnt(3)
	v_add_f32_e32 v134, v134, v216
	s_waitcnt lgkmcnt(2)
	v_add_f32_e32 v135, v135, v217
	s_waitcnt lgkmcnt(1)
	v_add_f32_e32 v136, v136, v218
	s_waitcnt lgkmcnt(0)
	v_add_f32_e32 v137, v137, v219
	ds_bpermute_b32 v212, v171, v130
	ds_bpermute_b32 v213, v171, v131
	ds_bpermute_b32 v214, v171, v132
	ds_bpermute_b32 v215, v171, v133
	ds_bpermute_b32 v216, v171, v134
	ds_bpermute_b32 v217, v171, v135
	ds_bpermute_b32 v218, v171, v136
	ds_bpermute_b32 v219, v171, v137
	s_waitcnt lgkmcnt(7)
	v_add_f32_e32 v130, v130, v212
	s_waitcnt lgkmcnt(6)
	v_add_f32_e32 v131, v131, v213
	s_waitcnt lgkmcnt(5)
	v_add_f32_e32 v132, v132, v214
	s_waitcnt lgkmcnt(4)
	v_add_f32_e32 v133, v133, v215
	s_waitcnt lgkmcnt(3)
	v_add_f32_e32 v134, v134, v216
	s_waitcnt lgkmcnt(2)
	v_add_f32_e32 v135, v135, v217
	s_waitcnt lgkmcnt(1)
	v_add_f32_e32 v136, v136, v218
	s_waitcnt lgkmcnt(0)
	v_add_f32_e32 v137, v137, v219
	ds_bpermute_b32 v212, v172, v130
	ds_bpermute_b32 v213, v172, v131
	ds_bpermute_b32 v214, v172, v132
	ds_bpermute_b32 v215, v172, v133
	ds_bpermute_b32 v216, v172, v134
	ds_bpermute_b32 v217, v172, v135
	ds_bpermute_b32 v218, v172, v136
	ds_bpermute_b32 v219, v172, v137
	s_waitcnt lgkmcnt(7)
	v_add_f32_e32 v130, v130, v212
	s_waitcnt lgkmcnt(6)
	v_add_f32_e32 v131, v131, v213
	s_waitcnt lgkmcnt(5)
	v_add_f32_e32 v132, v132, v214
	s_waitcnt lgkmcnt(4)
	v_add_f32_e32 v133, v133, v215
	s_waitcnt lgkmcnt(3)
	v_add_f32_e32 v134, v134, v216
	s_waitcnt lgkmcnt(2)
	v_add_f32_e32 v135, v135, v217
	s_waitcnt lgkmcnt(1)
	v_add_f32_e32 v136, v136, v218
	s_waitcnt lgkmcnt(0)
	v_add_f32_e32 v137, v137, v219
	ds_bpermute_b32 v212, v173, v130
	ds_bpermute_b32 v213, v173, v131
	ds_bpermute_b32 v214, v173, v132
	ds_bpermute_b32 v215, v173, v133
	ds_bpermute_b32 v216, v173, v134
	ds_bpermute_b32 v217, v173, v135
	ds_bpermute_b32 v218, v173, v136
	ds_bpermute_b32 v219, v173, v137
	s_waitcnt lgkmcnt(7)
	v_add_f32_e32 v130, v130, v212
	s_waitcnt lgkmcnt(6)
	v_add_f32_e32 v131, v131, v213
	s_waitcnt lgkmcnt(5)
	v_add_f32_e32 v132, v132, v214
	s_waitcnt lgkmcnt(4)
	v_add_f32_e32 v133, v133, v215
	s_waitcnt lgkmcnt(3)
	v_add_f32_e32 v134, v134, v216
	s_waitcnt lgkmcnt(2)
	v_add_f32_e32 v135, v135, v217
	s_waitcnt lgkmcnt(1)
	v_add_f32_e32 v136, v136, v218
	s_waitcnt lgkmcnt(0)
	v_add_f32_e32 v137, v137, v219
	ds_bpermute_b32 v220, v168, v138
	ds_bpermute_b32 v221, v168, v139
	ds_bpermute_b32 v222, v168, v140
	ds_bpermute_b32 v223, v168, v141
	ds_bpermute_b32 v224, v168, v142
	ds_bpermute_b32 v225, v168, v143
	ds_bpermute_b32 v226, v168, v144
	ds_bpermute_b32 v227, v168, v145
	s_waitcnt lgkmcnt(7)
	v_add_f32_e32 v138, v138, v220
	s_waitcnt lgkmcnt(6)
	v_add_f32_e32 v139, v139, v221
	s_waitcnt lgkmcnt(5)
	v_add_f32_e32 v140, v140, v222
	s_waitcnt lgkmcnt(4)
	v_add_f32_e32 v141, v141, v223
	s_waitcnt lgkmcnt(3)
	v_add_f32_e32 v142, v142, v224
	s_waitcnt lgkmcnt(2)
	v_add_f32_e32 v143, v143, v225
	s_waitcnt lgkmcnt(1)
	v_add_f32_e32 v144, v144, v226
	s_waitcnt lgkmcnt(0)
	v_add_f32_e32 v145, v145, v227
	ds_bpermute_b32 v220, v169, v138
	ds_bpermute_b32 v221, v169, v139
	ds_bpermute_b32 v222, v169, v140
	ds_bpermute_b32 v223, v169, v141
	ds_bpermute_b32 v224, v169, v142
	ds_bpermute_b32 v225, v169, v143
	ds_bpermute_b32 v226, v169, v144
	ds_bpermute_b32 v227, v169, v145
	s_waitcnt lgkmcnt(7)
	v_add_f32_e32 v138, v138, v220
	s_waitcnt lgkmcnt(6)
	v_add_f32_e32 v139, v139, v221
	s_waitcnt lgkmcnt(5)
	v_add_f32_e32 v140, v140, v222
	s_waitcnt lgkmcnt(4)
	v_add_f32_e32 v141, v141, v223
	s_waitcnt lgkmcnt(3)
	v_add_f32_e32 v142, v142, v224
	s_waitcnt lgkmcnt(2)
	v_add_f32_e32 v143, v143, v225
	s_waitcnt lgkmcnt(1)
	v_add_f32_e32 v144, v144, v226
	s_waitcnt lgkmcnt(0)
	v_add_f32_e32 v145, v145, v227
	ds_bpermute_b32 v220, v171, v138
	ds_bpermute_b32 v221, v171, v139
	ds_bpermute_b32 v222, v171, v140
	ds_bpermute_b32 v223, v171, v141
	ds_bpermute_b32 v224, v171, v142
	ds_bpermute_b32 v225, v171, v143
	ds_bpermute_b32 v226, v171, v144
	ds_bpermute_b32 v227, v171, v145
	s_waitcnt lgkmcnt(7)
	v_add_f32_e32 v138, v138, v220
	s_waitcnt lgkmcnt(6)
	v_add_f32_e32 v139, v139, v221
	s_waitcnt lgkmcnt(5)
	v_add_f32_e32 v140, v140, v222
	s_waitcnt lgkmcnt(4)
	v_add_f32_e32 v141, v141, v223
	s_waitcnt lgkmcnt(3)
	v_add_f32_e32 v142, v142, v224
	s_waitcnt lgkmcnt(2)
	v_add_f32_e32 v143, v143, v225
	s_waitcnt lgkmcnt(1)
	v_add_f32_e32 v144, v144, v226
	s_waitcnt lgkmcnt(0)
	v_add_f32_e32 v145, v145, v227
	ds_bpermute_b32 v220, v172, v138
	ds_bpermute_b32 v221, v172, v139
	ds_bpermute_b32 v222, v172, v140
	ds_bpermute_b32 v223, v172, v141
	ds_bpermute_b32 v224, v172, v142
	ds_bpermute_b32 v225, v172, v143
	ds_bpermute_b32 v226, v172, v144
	ds_bpermute_b32 v227, v172, v145
	s_waitcnt lgkmcnt(7)
	v_add_f32_e32 v138, v138, v220
	s_waitcnt lgkmcnt(6)
	v_add_f32_e32 v139, v139, v221
	s_waitcnt lgkmcnt(5)
	v_add_f32_e32 v140, v140, v222
	s_waitcnt lgkmcnt(4)
	v_add_f32_e32 v141, v141, v223
	s_waitcnt lgkmcnt(3)
	v_add_f32_e32 v142, v142, v224
	s_waitcnt lgkmcnt(2)
	v_add_f32_e32 v143, v143, v225
	s_waitcnt lgkmcnt(1)
	v_add_f32_e32 v144, v144, v226
	s_waitcnt lgkmcnt(0)
	v_add_f32_e32 v145, v145, v227
	ds_bpermute_b32 v220, v173, v138
	ds_bpermute_b32 v221, v173, v139
	ds_bpermute_b32 v222, v173, v140
	ds_bpermute_b32 v223, v173, v141
	ds_bpermute_b32 v224, v173, v142
	ds_bpermute_b32 v225, v173, v143
	ds_bpermute_b32 v226, v173, v144
	ds_bpermute_b32 v227, v173, v145
	s_waitcnt lgkmcnt(7)
	v_add_f32_e32 v138, v138, v220
	s_waitcnt lgkmcnt(6)
	v_add_f32_e32 v139, v139, v221
	s_waitcnt lgkmcnt(5)
	v_add_f32_e32 v140, v140, v222
	s_waitcnt lgkmcnt(4)
	v_add_f32_e32 v141, v141, v223
	s_waitcnt lgkmcnt(3)
	v_add_f32_e32 v142, v142, v224
	s_waitcnt lgkmcnt(2)
	v_add_f32_e32 v143, v143, v225
	s_waitcnt lgkmcnt(1)
	v_add_f32_e32 v144, v144, v226
	s_waitcnt lgkmcnt(0)
	v_add_f32_e32 v145, v145, v227
	v_cmp_eq_u32_e32 vcc, 0, v174
	s_and_saveexec_b64 s[58:59], vcc
	global_store_dword v167, v130, s[10:11] offset:128
	global_store_dword v167, v131, s[10:11] offset:132
	global_store_dword v167, v132, s[10:11] offset:136
	global_store_dword v167, v133, s[10:11] offset:140
	global_store_dword v167, v134, s[10:11] offset:160
	global_store_dword v167, v135, s[10:11] offset:164
	global_store_dword v167, v136, s[10:11] offset:168
	global_store_dword v167, v137, s[10:11] offset:172
	global_store_dword v167, v138, s[10:11] offset:192
	global_store_dword v167, v139, s[10:11] offset:196
	global_store_dword v167, v140, s[10:11] offset:200
	global_store_dword v167, v141, s[10:11] offset:204
	global_store_dword v167, v142, s[10:11] offset:224
	global_store_dword v167, v143, s[10:11] offset:228
	global_store_dword v167, v144, s[10:11] offset:232
	global_store_dword v167, v145, s[10:11] offset:236
	s_mov_b64 exec, -1
	s_sub_u32 s48, s48, 0x20000
	s_subb_u32 s49, s49, 0
	v_readlane_b32 s2, v246, 14
	s_nop 0
	s_add_i32 s16, s16, s2
	s_branch .Lhw_ffndown_tloop
